# GEMM K loops: the s_nop between the M0 write and each LDS-DMA load replaced by moving the address add behind the M0 write (80 sites); on v085
# speedup vs baseline: 1.0025x; 1.0025x over previous
.LBB0_178:
	ds_read_b128 v[148:151], v159
	ds_read_b128 v[152:155], v159 offset:1024
	ds_read_b128 v[164:167], v159 offset:2048
	ds_read_b128 v[168:171], v159 offset:3072
	s_add_u32 s52, s50, 0xfffc0080
	s_addc_u32 s53, s51, -1
	s_cmp_eq_u32 s92, 12
	s_cselect_b32 s55, s11, s53
	s_cselect_b32 s54, s13, s52
	s_cselect_b32 s53, s17, s91
	s_cselect_b32 s52, s43, s45
	v_lshl_add_u64 v[156:157], s[50:51], 0, v[140:141]
	s_add_i32 m0, s58, 0xc000
	ds_read_b128 v[172:175], v160
	ds_read_b128 v[176:179], v160 offset:1024
	ds_read_b128 v[180:183], v160 offset:2048
	ds_read_b128 v[184:187], v160 offset:3072
	ds_read_b128 v[188:191], v160 offset:4096
	ds_read_b128 v[196:199], v160 offset:5120
	ds_read_b128 v[200:203], v160 offset:6144
	ds_read_b128 v[204:207], v160 offset:7168
	global_load_lds_dwordx4 v[156:157], off
	s_add_i32 m0, s58, 0xe000
	v_lshl_add_u64 v[156:157], s[50:51], 0, v[142:143]
	global_load_lds_dwordx4 v[156:157], off
	s_waitcnt lgkmcnt(8)
	s_barrier
	s_waitcnt lgkmcnt(0)
	s_waitcnt lgkmcnt(0)
	s_cmp_eq_u32 s92, -2
	s_cbranch_scc1 .Lz1_0_first
	v_mfma_f32_16x16x32_bf16 v[124:127], v[148:151], v[172:175], v[124:127]
	v_mfma_f32_16x16x32_bf16 v[120:123], v[164:167], v[172:175], v[120:123]
	v_mfma_f32_16x16x32_bf16 v[108:111], v[148:151], v[180:183], v[108:111]
	v_mfma_f32_16x16x32_bf16 v[104:107], v[164:167], v[180:183], v[104:107]
	v_mfma_f32_16x16x32_bf16 v[92:95], v[148:151], v[188:191], v[92:95]
	v_mfma_f32_16x16x32_bf16 v[88:91], v[164:167], v[188:191], v[88:91]
	v_mfma_f32_16x16x32_bf16 v[76:79], v[148:151], v[200:203], v[76:79]
	v_mfma_f32_16x16x32_bf16 v[72:75], v[164:167], v[200:203], v[72:75]
	v_mfma_f32_16x16x32_bf16 v[124:127], v[152:155], v[176:179], v[124:127]
	v_mfma_f32_16x16x32_bf16 v[120:123], v[168:171], v[176:179], v[120:123]
	v_mfma_f32_16x16x32_bf16 v[108:111], v[152:155], v[184:187], v[108:111]
	v_mfma_f32_16x16x32_bf16 v[104:107], v[168:171], v[184:187], v[104:107]
	v_mfma_f32_16x16x32_bf16 v[92:95], v[152:155], v[196:199], v[92:95]
	v_mfma_f32_16x16x32_bf16 v[88:91], v[168:171], v[196:199], v[88:91]
	v_mfma_f32_16x16x32_bf16 v[76:79], v[152:155], v[204:207], v[76:79]
	v_mfma_f32_16x16x32_bf16 v[72:75], v[168:171], v[204:207], v[72:75]
.Lz1_0_join:
	s_barrier
	s_add_i32 s93, s89, s57
	v_lshl_add_u64 v[156:157], s[52:53], 0, v[130:131]
	s_mov_b32 m0, s93
	ds_read_b128 v[208:211], v161
	ds_read_b128 v[212:215], v161 offset:1024
	ds_read_b128 v[216:219], v161 offset:2048
	ds_read_b128 v[220:223], v161 offset:3072
	global_load_lds_dwordx4 v[156:157], off
	s_add_i32 m0, s93, 0x2000
	v_lshl_add_u64 v[224:225], s[52:53], 0, v[134:135]
	global_load_lds_dwordx4 v[224:225], off
	s_barrier
	s_waitcnt lgkmcnt(0)
	s_waitcnt lgkmcnt(0)
	s_cmp_eq_u32 s92, -2
	s_cbranch_scc1 .Lz1_1_first
	v_mfma_f32_16x16x32_bf16 v[116:119], v[208:211], v[172:175], v[116:119]
	v_mfma_f32_16x16x32_bf16 v[112:115], v[216:219], v[172:175], v[112:115]
	v_mfma_f32_16x16x32_bf16 v[100:103], v[208:211], v[180:183], v[100:103]
	v_mfma_f32_16x16x32_bf16 v[96:99], v[216:219], v[180:183], v[96:99]
	v_mfma_f32_16x16x32_bf16 v[84:87], v[208:211], v[188:191], v[84:87]
	v_mfma_f32_16x16x32_bf16 v[80:83], v[216:219], v[188:191], v[80:83]
	v_mfma_f32_16x16x32_bf16 v[68:71], v[208:211], v[200:203], v[68:71]
	v_mfma_f32_16x16x32_bf16 v[64:67], v[216:219], v[200:203], v[64:67]
	v_mfma_f32_16x16x32_bf16 v[116:119], v[212:215], v[176:179], v[116:119]
	v_mfma_f32_16x16x32_bf16 v[112:115], v[220:223], v[176:179], v[112:115]
	v_mfma_f32_16x16x32_bf16 v[100:103], v[212:215], v[184:187], v[100:103]
	v_mfma_f32_16x16x32_bf16 v[96:99], v[220:223], v[184:187], v[96:99]
	v_mfma_f32_16x16x32_bf16 v[84:87], v[212:215], v[196:199], v[84:87]
	v_mfma_f32_16x16x32_bf16 v[80:83], v[220:223], v[196:199], v[80:83]
	v_mfma_f32_16x16x32_bf16 v[68:71], v[212:215], v[204:207], v[68:71]
	v_mfma_f32_16x16x32_bf16 v[64:67], v[220:223], v[204:207], v[64:67]
.Lz1_1_join:
	s_mov_b32 m0, s58
	v_lshl_add_u64 v[226:227], s[54:55], 0, v[128:129]
	s_barrier
	ds_read_b128 v[172:175], v160 offset:16384
	ds_read_b128 v[176:179], v160 offset:17408
	ds_read_b128 v[180:183], v160 offset:18432
	ds_read_b128 v[184:187], v160 offset:19456
	ds_read_b128 v[188:191], v160 offset:20480
	ds_read_b128 v[196:199], v160 offset:21504
	ds_read_b128 v[200:203], v160 offset:22528
	ds_read_b128 v[204:207], v160 offset:23552
	global_load_lds_dwordx4 v[226:227], off
	s_mov_b32 m0, s59
	v_lshl_add_u64 v[228:229], s[54:55], 0, v[132:133]
	global_load_lds_dwordx4 v[228:229], off
	s_barrier
	s_waitcnt lgkmcnt(0)
	s_waitcnt lgkmcnt(0)
	s_cmp_eq_u32 s92, -2
	s_cbranch_scc1 .Lz1_2_first
	v_mfma_f32_16x16x32_bf16 v[60:63], v[148:151], v[172:175], v[60:63]
	v_mfma_f32_16x16x32_bf16 v[56:59], v[164:167], v[172:175], v[56:59]
	v_mfma_f32_16x16x32_bf16 v[44:47], v[148:151], v[180:183], v[44:47]
	v_mfma_f32_16x16x32_bf16 v[40:43], v[164:167], v[180:183], v[40:43]
	v_mfma_f32_16x16x32_bf16 v[28:31], v[148:151], v[188:191], v[28:31]
	v_mfma_f32_16x16x32_bf16 v[24:27], v[164:167], v[188:191], v[24:27]
	v_mfma_f32_16x16x32_bf16 v[12:15], v[148:151], v[200:203], v[12:15]
	v_mfma_f32_16x16x32_bf16 v[8:11], v[164:167], v[200:203], v[8:11]
	v_mfma_f32_16x16x32_bf16 v[60:63], v[152:155], v[176:179], v[60:63]
	v_mfma_f32_16x16x32_bf16 v[56:59], v[168:171], v[176:179], v[56:59]
	v_mfma_f32_16x16x32_bf16 v[44:47], v[152:155], v[184:187], v[44:47]
	v_mfma_f32_16x16x32_bf16 v[40:43], v[168:171], v[184:187], v[40:43]
	v_mfma_f32_16x16x32_bf16 v[28:31], v[152:155], v[196:199], v[28:31]
	v_mfma_f32_16x16x32_bf16 v[24:27], v[168:171], v[196:199], v[24:27]
	v_mfma_f32_16x16x32_bf16 v[12:15], v[152:155], v[204:207], v[12:15]
	v_mfma_f32_16x16x32_bf16 v[8:11], v[168:171], v[204:207], v[8:11]
.Lz1_2_join:
	s_barrier
	s_add_u32 s94, s52, 0x10000
	s_addc_u32 s95, s53, 0
	s_add_i32 s93, s90, s57
	s_mov_b32 m0, s93
	v_lshl_add_u64 v[148:149], s[94:95], 0, v[130:131]
	global_load_lds_dwordx4 v[148:149], off
	s_add_i32 m0, s93, 0x2000
	v_lshl_add_u64 v[148:149], s[94:95], 0, v[134:135]
	global_load_lds_dwordx4 v[148:149], off
	s_cmp_eq_u32 s98, 0
	s_cbranch_scc1 .Lk1_w4n
	s_mov_b32 s98, 0
	s_waitcnt vmcnt(24)
	s_branch .Lk1_w4j

.Lz1_3_join:
	s_add_i32 s93, 0, 0x18000
	v_add_u32_e32 v136, s93, v158
	s_barrier
	ds_read_b128 v[148:151], v136
	ds_read_b128 v[152:155], v136 offset:1024
	ds_read_b128 v[164:167], v136 offset:2048
	ds_read_b128 v[168:171], v136 offset:3072
	s_add_u32 s54, s54, 0x40000
	s_addc_u32 s55, s55, 0
	s_mov_b32 m0, s60
	v_lshl_add_u64 v[208:209], s[54:55], 0, v[128:129]
	ds_read_b128 v[172:175], v160 offset:32768
	ds_read_b128 v[176:179], v160 offset:33792
	ds_read_b128 v[180:183], v160 offset:34816
	ds_read_b128 v[184:187], v160 offset:35840
	ds_read_b128 v[188:191], v160 offset:36864
	ds_read_b128 v[196:199], v160 offset:37888
	ds_read_b128 v[200:203], v160 offset:38912
	ds_read_b128 v[204:207], v160 offset:39936
	global_load_lds_dwordx4 v[208:209], off
	s_mov_b32 m0, s61
	v_lshl_add_u64 v[208:209], s[54:55], 0, v[132:133]
	global_load_lds_dwordx4 v[208:209], off
	s_waitcnt lgkmcnt(8)
	s_barrier
	s_waitcnt lgkmcnt(0)
	s_waitcnt lgkmcnt(0)
	v_mfma_f32_16x16x32_bf16 v[124:127], v[148:151], v[172:175], v[124:127]
	v_mfma_f32_16x16x32_bf16 v[120:123], v[164:167], v[172:175], v[120:123]
	v_mfma_f32_16x16x32_bf16 v[108:111], v[148:151], v[180:183], v[108:111]
	v_mfma_f32_16x16x32_bf16 v[104:107], v[164:167], v[180:183], v[104:107]
	v_mfma_f32_16x16x32_bf16 v[92:95], v[148:151], v[188:191], v[92:95]
	v_mfma_f32_16x16x32_bf16 v[88:91], v[164:167], v[188:191], v[88:91]
	v_mfma_f32_16x16x32_bf16 v[76:79], v[148:151], v[200:203], v[76:79]
	v_mfma_f32_16x16x32_bf16 v[72:75], v[164:167], v[200:203], v[72:75]
	v_mfma_f32_16x16x32_bf16 v[124:127], v[152:155], v[176:179], v[124:127]
	v_mfma_f32_16x16x32_bf16 v[120:123], v[168:171], v[176:179], v[120:123]
	v_mfma_f32_16x16x32_bf16 v[108:111], v[152:155], v[184:187], v[108:111]
	v_mfma_f32_16x16x32_bf16 v[104:107], v[168:171], v[184:187], v[104:107]
	v_mfma_f32_16x16x32_bf16 v[92:95], v[152:155], v[196:199], v[92:95]
	v_mfma_f32_16x16x32_bf16 v[88:91], v[168:171], v[196:199], v[88:91]
	v_mfma_f32_16x16x32_bf16 v[76:79], v[152:155], v[204:207], v[76:79]
	v_mfma_f32_16x16x32_bf16 v[72:75], v[168:171], v[204:207], v[72:75]
	s_barrier
	s_add_i32 s54, 0, 0x1c000
	s_add_i32 s55, s93, s57
	v_add_u32_e32 v136, s54, v158
	v_lshl_add_u64 v[156:157], v[156:157], 0, s[0:1]
	s_mov_b32 m0, s55
	ds_read_b128 v[208:211], v136
	ds_read_b128 v[212:215], v136 offset:1024
	ds_read_b128 v[216:219], v136 offset:2048
	ds_read_b128 v[220:223], v136 offset:3072
	global_load_lds_dwordx4 v[156:157], off
	s_add_i32 m0, s55, 0x2000
	v_lshl_add_u64 v[156:157], v[224:225], 0, s[0:1]
	global_load_lds_dwordx4 v[156:157], off
	s_barrier
	s_waitcnt lgkmcnt(0)
	s_waitcnt lgkmcnt(0)
	v_mfma_f32_16x16x32_bf16 v[116:119], v[208:211], v[172:175], v[116:119]
	v_mfma_f32_16x16x32_bf16 v[112:115], v[216:219], v[172:175], v[112:115]
	v_mfma_f32_16x16x32_bf16 v[100:103], v[208:211], v[180:183], v[100:103]
	v_mfma_f32_16x16x32_bf16 v[96:99], v[216:219], v[180:183], v[96:99]
	v_mfma_f32_16x16x32_bf16 v[84:87], v[208:211], v[188:191], v[84:87]
	v_mfma_f32_16x16x32_bf16 v[80:83], v[216:219], v[188:191], v[80:83]
	v_mfma_f32_16x16x32_bf16 v[68:71], v[208:211], v[200:203], v[68:71]
	v_mfma_f32_16x16x32_bf16 v[64:67], v[216:219], v[200:203], v[64:67]
	v_mfma_f32_16x16x32_bf16 v[116:119], v[212:215], v[176:179], v[116:119]
	v_mfma_f32_16x16x32_bf16 v[112:115], v[220:223], v[176:179], v[112:115]
	v_mfma_f32_16x16x32_bf16 v[100:103], v[212:215], v[184:187], v[100:103]
	v_mfma_f32_16x16x32_bf16 v[96:99], v[220:223], v[184:187], v[96:99]
	v_mfma_f32_16x16x32_bf16 v[84:87], v[212:215], v[196:199], v[84:87]
	v_mfma_f32_16x16x32_bf16 v[80:83], v[220:223], v[196:199], v[80:83]
	v_mfma_f32_16x16x32_bf16 v[68:71], v[212:215], v[204:207], v[68:71]
	v_mfma_f32_16x16x32_bf16 v[64:67], v[220:223], v[204:207], v[64:67]
	s_mov_b32 m0, s65
	v_lshl_add_u64 v[156:157], v[226:227], 0, s[0:1]
	s_waitcnt vmcnt(10)
	s_barrier
	ds_read_b128 v[172:175], v160 offset:49152
	ds_read_b128 v[176:179], v160 offset:50176
	ds_read_b128 v[180:183], v160 offset:51200
	ds_read_b128 v[184:187], v160 offset:52224
	ds_read_b128 v[188:191], v160 offset:53248
	ds_read_b128 v[196:199], v160 offset:54272
	ds_read_b128 v[200:203], v160 offset:55296
	ds_read_b128 v[204:207], v160 offset:56320
	global_load_lds_dwordx4 v[156:157], off
	s_mov_b32 m0, s66
	v_lshl_add_u64 v[156:157], v[228:229], 0, s[0:1]
	global_load_lds_dwordx4 v[156:157], off
	s_barrier
	s_waitcnt lgkmcnt(0)
	s_waitcnt lgkmcnt(0)
	v_mfma_f32_16x16x32_bf16 v[60:63], v[148:151], v[172:175], v[60:63]
	v_mfma_f32_16x16x32_bf16 v[56:59], v[164:167], v[172:175], v[56:59]
	v_mfma_f32_16x16x32_bf16 v[44:47], v[148:151], v[180:183], v[44:47]
	v_mfma_f32_16x16x32_bf16 v[40:43], v[164:167], v[180:183], v[40:43]
	v_mfma_f32_16x16x32_bf16 v[28:31], v[148:151], v[188:191], v[28:31]
	v_mfma_f32_16x16x32_bf16 v[24:27], v[164:167], v[188:191], v[24:27]
	v_mfma_f32_16x16x32_bf16 v[12:15], v[148:151], v[200:203], v[12:15]
	v_mfma_f32_16x16x32_bf16 v[8:11], v[164:167], v[200:203], v[8:11]
	v_mfma_f32_16x16x32_bf16 v[60:63], v[152:155], v[176:179], v[60:63]
	v_mfma_f32_16x16x32_bf16 v[56:59], v[168:171], v[176:179], v[56:59]
	v_mfma_f32_16x16x32_bf16 v[44:47], v[152:155], v[184:187], v[44:47]
	v_mfma_f32_16x16x32_bf16 v[40:43], v[168:171], v[184:187], v[40:43]
	v_mfma_f32_16x16x32_bf16 v[28:31], v[152:155], v[196:199], v[28:31]
	v_mfma_f32_16x16x32_bf16 v[24:27], v[168:171], v[196:199], v[24:27]
	v_mfma_f32_16x16x32_bf16 v[12:15], v[152:155], v[204:207], v[12:15]
	v_mfma_f32_16x16x32_bf16 v[8:11], v[168:171], v[204:207], v[8:11]
	s_barrier
	s_add_u32 s52, s52, 0x10080
	s_addc_u32 s53, s53, 0
	s_add_i32 s54, s54, s57
	s_mov_b32 m0, s54
	v_lshl_add_u64 v[148:149], s[52:53], 0, v[130:131]
	global_load_lds_dwordx4 v[148:149], off
	s_add_i32 m0, s54, 0x2000
	v_lshl_add_u64 v[148:149], s[52:53], 0, v[134:135]
	global_load_lds_dwordx4 v[148:149], off
	s_waitcnt vmcnt(6)
	s_barrier
	v_mfma_f32_16x16x32_bf16 v[52:55], v[208:211], v[172:175], v[52:55]
	v_mfma_f32_16x16x32_bf16 v[48:51], v[216:219], v[172:175], v[48:51]
	v_mfma_f32_16x16x32_bf16 v[36:39], v[208:211], v[180:183], v[36:39]
	v_mfma_f32_16x16x32_bf16 v[32:35], v[216:219], v[180:183], v[32:35]
	v_mfma_f32_16x16x32_bf16 v[20:23], v[208:211], v[188:191], v[20:23]
	v_mfma_f32_16x16x32_bf16 v[16:19], v[216:219], v[188:191], v[16:19]
	v_mfma_f32_16x16x32_bf16 v[4:7], v[208:211], v[200:203], v[4:7]
	v_mfma_f32_16x16x32_bf16 v[0:3], v[216:219], v[200:203], v[0:3]
	v_mfma_f32_16x16x32_bf16 v[52:55], v[212:215], v[176:179], v[52:55]
	v_mfma_f32_16x16x32_bf16 v[48:51], v[220:223], v[176:179], v[48:51]
	v_mfma_f32_16x16x32_bf16 v[36:39], v[212:215], v[184:187], v[36:39]
	v_mfma_f32_16x16x32_bf16 v[32:35], v[220:223], v[184:187], v[32:35]
	v_mfma_f32_16x16x32_bf16 v[20:23], v[212:215], v[196:199], v[20:23]
	v_mfma_f32_16x16x32_bf16 v[16:19], v[220:223], v[196:199], v[16:19]
	v_mfma_f32_16x16x32_bf16 v[4:7], v[212:215], v[204:207], v[4:7]
	v_mfma_f32_16x16x32_bf16 v[0:3], v[220:223], v[204:207], v[0:3]
	s_add_i32 s92, s92, 2
	s_add_u32 s50, s50, 0x100
	s_addc_u32 s51, s51, 0
	s_add_u32 s45, s45, 0x100
	s_addc_u32 s91, s91, 0
	s_cmp_gt_u32 s92, 13
	s_barrier
	s_cbranch_scc0 .LBB0_178
	s_branch .Lz1_skip

.LBB0_342:
	ds_read_b128 v[146:149], v143
	ds_read_b128 v[150:153], v143 offset:1024
	ds_read_b128 v[154:157], v143 offset:2048
	ds_read_b128 v[158:161], v143 offset:3072
	s_add_u32 s46, s44, 0xfffc0080
	s_addc_u32 s47, s45, -1
	s_cmp_eq_u32 s67, 12
	s_cselect_b32 s49, s9, s47
	s_cselect_b32 s48, s63, s46
	s_cselect_b32 s47, s7, s66
	s_cselect_b32 s46, s64, s65
	v_lshl_add_u64 v[190:191], s[44:45], 0, v[136:137]
	s_add_i32 m0, s43, 0xc000
	ds_read_b128 v[162:165], v144
	ds_read_b128 v[166:169], v144 offset:1024
	ds_read_b128 v[170:173], v144 offset:2048
	ds_read_b128 v[174:177], v144 offset:3072
	ds_read_b128 v[178:181], v144 offset:4096
	ds_read_b128 v[182:185], v144 offset:5120
	ds_read_b128 v[186:189], v144 offset:6144
	ds_read_b128 v[196:199], v144 offset:7168
	global_load_lds_dwordx4 v[190:191], off
	s_add_i32 m0, s43, 0xe000
	v_lshl_add_u64 v[190:191], s[44:45], 0, v[138:139]
	global_load_lds_dwordx4 v[190:191], off
	s_waitcnt lgkmcnt(8)
	s_barrier
	s_waitcnt lgkmcnt(0)
	s_waitcnt lgkmcnt(0)
	v_mfma_f32_16x16x32_bf16 v[124:127], v[146:149], v[162:165], v[124:127]
	v_mfma_f32_16x16x32_bf16 v[120:123], v[154:157], v[162:165], v[120:123]
	v_mfma_f32_16x16x32_bf16 v[108:111], v[146:149], v[170:173], v[108:111]
	v_mfma_f32_16x16x32_bf16 v[104:107], v[154:157], v[170:173], v[104:107]
	v_mfma_f32_16x16x32_bf16 v[92:95], v[146:149], v[178:181], v[92:95]
	v_mfma_f32_16x16x32_bf16 v[88:91], v[154:157], v[178:181], v[88:91]
	v_mfma_f32_16x16x32_bf16 v[76:79], v[146:149], v[186:189], v[76:79]
	v_mfma_f32_16x16x32_bf16 v[72:75], v[154:157], v[186:189], v[72:75]
	v_mfma_f32_16x16x32_bf16 v[124:127], v[150:153], v[166:169], v[124:127]
	v_mfma_f32_16x16x32_bf16 v[120:123], v[158:161], v[166:169], v[120:123]
	v_mfma_f32_16x16x32_bf16 v[108:111], v[150:153], v[174:177], v[108:111]
	v_mfma_f32_16x16x32_bf16 v[104:107], v[158:161], v[174:177], v[104:107]
	v_mfma_f32_16x16x32_bf16 v[92:95], v[150:153], v[182:185], v[92:95]
	v_mfma_f32_16x16x32_bf16 v[88:91], v[158:161], v[182:185], v[88:91]
	v_mfma_f32_16x16x32_bf16 v[76:79], v[150:153], v[196:199], v[76:79]
	v_mfma_f32_16x16x32_bf16 v[72:75], v[158:161], v[196:199], v[72:75]
	s_barrier
	s_add_i32 s84, s60, s50
	v_lshl_add_u64 v[190:191], s[46:47], 0, v[132:133]
	s_mov_b32 m0, s84
	ds_read_b128 v[200:203], v145
	ds_read_b128 v[204:207], v145 offset:1024
	ds_read_b128 v[208:211], v145 offset:2048
	ds_read_b128 v[212:215], v145 offset:3072
	global_load_lds_dwordx4 v[190:191], off
	s_add_i32 m0, s84, 0x2000
	v_lshl_add_u64 v[216:217], s[46:47], 0, v[128:129]
	global_load_lds_dwordx4 v[216:217], off
	s_barrier
	s_waitcnt lgkmcnt(0)
	s_waitcnt lgkmcnt(0)
	v_mfma_f32_16x16x32_bf16 v[116:119], v[200:203], v[162:165], v[116:119]
	v_mfma_f32_16x16x32_bf16 v[112:115], v[208:211], v[162:165], v[112:115]
	v_mfma_f32_16x16x32_bf16 v[100:103], v[200:203], v[170:173], v[100:103]
	v_mfma_f32_16x16x32_bf16 v[96:99], v[208:211], v[170:173], v[96:99]
	v_mfma_f32_16x16x32_bf16 v[84:87], v[200:203], v[178:181], v[84:87]
	v_mfma_f32_16x16x32_bf16 v[80:83], v[208:211], v[178:181], v[80:83]
	v_mfma_f32_16x16x32_bf16 v[68:71], v[200:203], v[186:189], v[68:71]
	v_mfma_f32_16x16x32_bf16 v[64:67], v[208:211], v[186:189], v[64:67]
	v_mfma_f32_16x16x32_bf16 v[116:119], v[204:207], v[166:169], v[116:119]
	v_mfma_f32_16x16x32_bf16 v[112:115], v[212:215], v[166:169], v[112:115]
	v_mfma_f32_16x16x32_bf16 v[100:103], v[204:207], v[174:177], v[100:103]
	v_mfma_f32_16x16x32_bf16 v[96:99], v[212:215], v[174:177], v[96:99]
	v_mfma_f32_16x16x32_bf16 v[84:87], v[204:207], v[182:185], v[84:87]
	v_mfma_f32_16x16x32_bf16 v[80:83], v[212:215], v[182:185], v[80:83]
	v_mfma_f32_16x16x32_bf16 v[68:71], v[204:207], v[196:199], v[68:71]
	v_mfma_f32_16x16x32_bf16 v[64:67], v[212:215], v[196:199], v[64:67]
	s_mov_b32 m0, s43
	v_lshl_add_u64 v[218:219], s[48:49], 0, v[134:135]
	s_barrier
	ds_read_b128 v[162:165], v144 offset:16384
	ds_read_b128 v[166:169], v144 offset:17408
	ds_read_b128 v[170:173], v144 offset:18432
	ds_read_b128 v[174:177], v144 offset:19456
	ds_read_b128 v[178:181], v144 offset:20480
	ds_read_b128 v[182:185], v144 offset:21504
	ds_read_b128 v[186:189], v144 offset:22528
	ds_read_b128 v[196:199], v144 offset:23552
	global_load_lds_dwordx4 v[218:219], off
	s_mov_b32 m0, s52
	v_lshl_add_u64 v[220:221], s[48:49], 0, v[130:131]
	global_load_lds_dwordx4 v[220:221], off
	s_barrier
	s_waitcnt lgkmcnt(0)
	s_waitcnt lgkmcnt(0)
	v_mfma_f32_16x16x32_bf16 v[60:63], v[146:149], v[162:165], v[60:63]
	v_mfma_f32_16x16x32_bf16 v[56:59], v[154:157], v[162:165], v[56:59]
	v_mfma_f32_16x16x32_bf16 v[44:47], v[146:149], v[170:173], v[44:47]
	v_mfma_f32_16x16x32_bf16 v[40:43], v[154:157], v[170:173], v[40:43]
	v_mfma_f32_16x16x32_bf16 v[28:31], v[146:149], v[178:181], v[28:31]
	v_mfma_f32_16x16x32_bf16 v[24:27], v[154:157], v[178:181], v[24:27]
	v_mfma_f32_16x16x32_bf16 v[12:15], v[146:149], v[186:189], v[12:15]
	v_mfma_f32_16x16x32_bf16 v[8:11], v[154:157], v[186:189], v[8:11]
	v_mfma_f32_16x16x32_bf16 v[60:63], v[150:153], v[166:169], v[60:63]
	v_mfma_f32_16x16x32_bf16 v[56:59], v[158:161], v[166:169], v[56:59]
	v_mfma_f32_16x16x32_bf16 v[44:47], v[150:153], v[174:177], v[44:47]
	v_mfma_f32_16x16x32_bf16 v[40:43], v[158:161], v[174:177], v[40:43]
	v_mfma_f32_16x16x32_bf16 v[28:31], v[150:153], v[182:185], v[28:31]
	v_mfma_f32_16x16x32_bf16 v[24:27], v[158:161], v[182:185], v[24:27]
	v_mfma_f32_16x16x32_bf16 v[12:15], v[150:153], v[196:199], v[12:15]
	v_mfma_f32_16x16x32_bf16 v[8:11], v[158:161], v[196:199], v[8:11]
	s_barrier
	s_add_u32 s84, s46, 0x10000
	s_addc_u32 s85, s47, 0
	s_add_i32 s89, s61, s50
	s_mov_b32 m0, s89
	v_lshl_add_u64 v[146:147], s[84:85], 0, v[132:133]
	global_load_lds_dwordx4 v[146:147], off
	s_add_i32 m0, s89, 0x2000
	v_lshl_add_u64 v[146:147], s[84:85], 0, v[128:129]
	global_load_lds_dwordx4 v[146:147], off
	s_waitcnt vmcnt(6)
	s_barrier
	v_mfma_f32_16x16x32_bf16 v[52:55], v[200:203], v[162:165], v[52:55]
	v_mfma_f32_16x16x32_bf16 v[48:51], v[208:211], v[162:165], v[48:51]
	v_mfma_f32_16x16x32_bf16 v[36:39], v[200:203], v[170:173], v[36:39]
	v_mfma_f32_16x16x32_bf16 v[32:35], v[208:211], v[170:173], v[32:35]
	v_mfma_f32_16x16x32_bf16 v[20:23], v[200:203], v[178:181], v[20:23]
	v_mfma_f32_16x16x32_bf16 v[16:19], v[208:211], v[178:181], v[16:19]
	v_mfma_f32_16x16x32_bf16 v[4:7], v[200:203], v[186:189], v[4:7]
	v_mfma_f32_16x16x32_bf16 v[0:3], v[208:211], v[186:189], v[0:3]
	v_mfma_f32_16x16x32_bf16 v[52:55], v[204:207], v[166:169], v[52:55]
	v_mfma_f32_16x16x32_bf16 v[48:51], v[212:215], v[166:169], v[48:51]
	v_mfma_f32_16x16x32_bf16 v[36:39], v[204:207], v[174:177], v[36:39]
	v_mfma_f32_16x16x32_bf16 v[32:35], v[212:215], v[174:177], v[32:35]
	v_mfma_f32_16x16x32_bf16 v[20:23], v[204:207], v[182:185], v[20:23]
	v_mfma_f32_16x16x32_bf16 v[16:19], v[212:215], v[182:185], v[16:19]
	v_mfma_f32_16x16x32_bf16 v[4:7], v[204:207], v[196:199], v[4:7]
	v_mfma_f32_16x16x32_bf16 v[0:3], v[212:215], v[196:199], v[0:3]
	s_add_i32 s84, 0, 0x18000
	v_add_u32_e32 v158, s84, v141
	s_barrier
	ds_read_b128 v[146:149], v158
	ds_read_b128 v[150:153], v158 offset:1024
	ds_read_b128 v[154:157], v158 offset:2048
	ds_read_b128 v[158:161], v158 offset:3072
	s_add_u32 s48, s48, 0x40000
	s_addc_u32 s49, s49, 0
	s_mov_b32 m0, s53
	v_lshl_add_u64 v[200:201], s[48:49], 0, v[134:135]
	ds_read_b128 v[162:165], v144 offset:32768
	ds_read_b128 v[166:169], v144 offset:33792
	ds_read_b128 v[170:173], v144 offset:34816
	ds_read_b128 v[174:177], v144 offset:35840
	ds_read_b128 v[178:181], v144 offset:36864
	ds_read_b128 v[182:185], v144 offset:37888
	ds_read_b128 v[186:189], v144 offset:38912
	ds_read_b128 v[196:199], v144 offset:39936
	global_load_lds_dwordx4 v[200:201], off
	s_mov_b32 m0, s54
	v_lshl_add_u64 v[200:201], s[48:49], 0, v[130:131]
	global_load_lds_dwordx4 v[200:201], off
	s_waitcnt lgkmcnt(8)
	s_barrier
	s_waitcnt lgkmcnt(0)
	s_waitcnt lgkmcnt(0)
	v_mfma_f32_16x16x32_bf16 v[124:127], v[146:149], v[162:165], v[124:127]
	v_mfma_f32_16x16x32_bf16 v[120:123], v[154:157], v[162:165], v[120:123]
	v_mfma_f32_16x16x32_bf16 v[108:111], v[146:149], v[170:173], v[108:111]
	v_mfma_f32_16x16x32_bf16 v[104:107], v[154:157], v[170:173], v[104:107]
	v_mfma_f32_16x16x32_bf16 v[92:95], v[146:149], v[178:181], v[92:95]
	v_mfma_f32_16x16x32_bf16 v[88:91], v[154:157], v[178:181], v[88:91]
	v_mfma_f32_16x16x32_bf16 v[76:79], v[146:149], v[186:189], v[76:79]
	v_mfma_f32_16x16x32_bf16 v[72:75], v[154:157], v[186:189], v[72:75]
	v_mfma_f32_16x16x32_bf16 v[124:127], v[150:153], v[166:169], v[124:127]
	v_mfma_f32_16x16x32_bf16 v[120:123], v[158:161], v[166:169], v[120:123]
	v_mfma_f32_16x16x32_bf16 v[108:111], v[150:153], v[174:177], v[108:111]
	v_mfma_f32_16x16x32_bf16 v[104:107], v[158:161], v[174:177], v[104:107]
	v_mfma_f32_16x16x32_bf16 v[92:95], v[150:153], v[182:185], v[92:95]
	v_mfma_f32_16x16x32_bf16 v[88:91], v[158:161], v[182:185], v[88:91]
	v_mfma_f32_16x16x32_bf16 v[76:79], v[150:153], v[196:199], v[76:79]
	v_mfma_f32_16x16x32_bf16 v[72:75], v[158:161], v[196:199], v[72:75]
	s_barrier
	s_add_i32 s48, 0, 0x1c000
	s_add_i32 s49, s84, s50
	v_add_u32_e32 v195, s48, v141
	v_lshl_add_u64 v[190:191], v[190:191], 0, s[0:1]
	s_mov_b32 m0, s49
	ds_read_b128 v[200:203], v195
	ds_read_b128 v[204:207], v195 offset:1024
	ds_read_b128 v[208:211], v195 offset:2048
	ds_read_b128 v[212:215], v195 offset:3072
	global_load_lds_dwordx4 v[190:191], off
	s_add_i32 m0, s49, 0x2000
	v_lshl_add_u64 v[190:191], v[216:217], 0, s[0:1]
	global_load_lds_dwordx4 v[190:191], off
	s_barrier
	s_waitcnt lgkmcnt(0)
	s_waitcnt lgkmcnt(0)
	v_mfma_f32_16x16x32_bf16 v[116:119], v[200:203], v[162:165], v[116:119]
	v_mfma_f32_16x16x32_bf16 v[112:115], v[208:211], v[162:165], v[112:115]
	v_mfma_f32_16x16x32_bf16 v[100:103], v[200:203], v[170:173], v[100:103]
	v_mfma_f32_16x16x32_bf16 v[96:99], v[208:211], v[170:173], v[96:99]
	v_mfma_f32_16x16x32_bf16 v[84:87], v[200:203], v[178:181], v[84:87]
	v_mfma_f32_16x16x32_bf16 v[80:83], v[208:211], v[178:181], v[80:83]
	v_mfma_f32_16x16x32_bf16 v[68:71], v[200:203], v[186:189], v[68:71]
	v_mfma_f32_16x16x32_bf16 v[64:67], v[208:211], v[186:189], v[64:67]
	v_mfma_f32_16x16x32_bf16 v[116:119], v[204:207], v[166:169], v[116:119]
	v_mfma_f32_16x16x32_bf16 v[112:115], v[212:215], v[166:169], v[112:115]
	v_mfma_f32_16x16x32_bf16 v[100:103], v[204:207], v[174:177], v[100:103]
	v_mfma_f32_16x16x32_bf16 v[96:99], v[212:215], v[174:177], v[96:99]
	v_mfma_f32_16x16x32_bf16 v[84:87], v[204:207], v[182:185], v[84:87]
	v_mfma_f32_16x16x32_bf16 v[80:83], v[212:215], v[182:185], v[80:83]
	v_mfma_f32_16x16x32_bf16 v[68:71], v[204:207], v[196:199], v[68:71]
	v_mfma_f32_16x16x32_bf16 v[64:67], v[212:215], v[196:199], v[64:67]
	s_mov_b32 m0, s57
	v_lshl_add_u64 v[190:191], v[218:219], 0, s[0:1]
	s_barrier
	ds_read_b128 v[162:165], v144 offset:49152
	ds_read_b128 v[166:169], v144 offset:50176
	ds_read_b128 v[170:173], v144 offset:51200
	ds_read_b128 v[174:177], v144 offset:52224
	ds_read_b128 v[178:181], v144 offset:53248
	ds_read_b128 v[182:185], v144 offset:54272
	ds_read_b128 v[186:189], v144 offset:55296
	ds_read_b128 v[196:199], v144 offset:56320
	global_load_lds_dwordx4 v[190:191], off
	s_mov_b32 m0, s58
	v_lshl_add_u64 v[190:191], v[220:221], 0, s[0:1]
	global_load_lds_dwordx4 v[190:191], off
	s_barrier
	s_waitcnt lgkmcnt(0)
	s_waitcnt lgkmcnt(0)
	v_mfma_f32_16x16x32_bf16 v[60:63], v[146:149], v[162:165], v[60:63]
	v_mfma_f32_16x16x32_bf16 v[56:59], v[154:157], v[162:165], v[56:59]
	v_mfma_f32_16x16x32_bf16 v[44:47], v[146:149], v[170:173], v[44:47]
	v_mfma_f32_16x16x32_bf16 v[40:43], v[154:157], v[170:173], v[40:43]
	v_mfma_f32_16x16x32_bf16 v[28:31], v[146:149], v[178:181], v[28:31]
	v_mfma_f32_16x16x32_bf16 v[24:27], v[154:157], v[178:181], v[24:27]
	v_mfma_f32_16x16x32_bf16 v[12:15], v[146:149], v[186:189], v[12:15]
	v_mfma_f32_16x16x32_bf16 v[8:11], v[154:157], v[186:189], v[8:11]
	v_mfma_f32_16x16x32_bf16 v[60:63], v[150:153], v[166:169], v[60:63]
	v_mfma_f32_16x16x32_bf16 v[56:59], v[158:161], v[166:169], v[56:59]
	v_mfma_f32_16x16x32_bf16 v[44:47], v[150:153], v[174:177], v[44:47]
	v_mfma_f32_16x16x32_bf16 v[40:43], v[158:161], v[174:177], v[40:43]
	v_mfma_f32_16x16x32_bf16 v[28:31], v[150:153], v[182:185], v[28:31]
	v_mfma_f32_16x16x32_bf16 v[24:27], v[158:161], v[182:185], v[24:27]
	v_mfma_f32_16x16x32_bf16 v[12:15], v[150:153], v[196:199], v[12:15]
	v_mfma_f32_16x16x32_bf16 v[8:11], v[158:161], v[196:199], v[8:11]
	s_barrier
	s_add_u32 s46, s46, 0x10080
	s_addc_u32 s47, s47, 0
	s_add_i32 s48, s48, s50
	s_mov_b32 m0, s48
	v_lshl_add_u64 v[146:147], s[46:47], 0, v[132:133]
	global_load_lds_dwordx4 v[146:147], off
	s_add_i32 m0, s48, 0x2000
	v_lshl_add_u64 v[146:147], s[46:47], 0, v[128:129]
	global_load_lds_dwordx4 v[146:147], off
	s_waitcnt vmcnt(6)
	s_barrier
	v_mfma_f32_16x16x32_bf16 v[52:55], v[200:203], v[162:165], v[52:55]
	v_mfma_f32_16x16x32_bf16 v[48:51], v[208:211], v[162:165], v[48:51]
	v_mfma_f32_16x16x32_bf16 v[36:39], v[200:203], v[170:173], v[36:39]
	v_mfma_f32_16x16x32_bf16 v[32:35], v[208:211], v[170:173], v[32:35]
	v_mfma_f32_16x16x32_bf16 v[20:23], v[200:203], v[178:181], v[20:23]
	v_mfma_f32_16x16x32_bf16 v[16:19], v[208:211], v[178:181], v[16:19]
	v_mfma_f32_16x16x32_bf16 v[4:7], v[200:203], v[186:189], v[4:7]
	v_mfma_f32_16x16x32_bf16 v[0:3], v[208:211], v[186:189], v[0:3]
	v_mfma_f32_16x16x32_bf16 v[52:55], v[204:207], v[166:169], v[52:55]
	v_mfma_f32_16x16x32_bf16 v[48:51], v[212:215], v[166:169], v[48:51]
	v_mfma_f32_16x16x32_bf16 v[36:39], v[204:207], v[174:177], v[36:39]
	v_mfma_f32_16x16x32_bf16 v[32:35], v[212:215], v[174:177], v[32:35]
	v_mfma_f32_16x16x32_bf16 v[20:23], v[204:207], v[182:185], v[20:23]
	v_mfma_f32_16x16x32_bf16 v[16:19], v[212:215], v[182:185], v[16:19]
	v_mfma_f32_16x16x32_bf16 v[4:7], v[204:207], v[196:199], v[4:7]
	v_mfma_f32_16x16x32_bf16 v[0:3], v[212:215], v[196:199], v[0:3]
	s_add_i32 s67, s67, 2
	s_add_u32 s44, s44, 0x100
	s_addc_u32 s45, s45, 0
	s_add_u32 s65, s65, 0x100
	s_addc_u32 s66, s66, 0
	s_cmp_gt_u32 s67, 13
	s_barrier
	s_cbranch_scc0 .LBB0_342
	v_cvt_pk_bf16_f32 v124, v124, v125
	v_cvt_pk_bf16_f32 v120, v120, v121
	v_cvt_pk_bf16_f32 v121, v122, v123
	v_cvt_pk_bf16_f32 v122, v116, v117
	v_cvt_pk_bf16_f32 v112, v112, v113
	v_cvt_pk_bf16_f32 v125, v126, v127
	v_cvt_pk_bf16_f32 v118, v118, v119
	v_cvt_pk_bf16_f32 v113, v114, v115
	v_cndmask_b32_e64 v114, v124, v122, s[2:3]
	v_mov_b32_e32 v123, 0
	v_cndmask_b32_e64 v115, v120, v112, s[2:3]
	v_mov_b32_e32 v126, 0
	v_lshl_add_u32 v148, s42, 8, v140
	v_mov_b32_dpp v123, v114 row_ror:8 row_mask:0xf bank_mask:0xf
	v_cndmask_b32_e64 v114, v125, v118, s[2:3]
	v_mov_b32_e32 v119, 0
	v_mov_b32_dpp v126, v115 row_ror:8 row_mask:0xf bank_mask:0xf
	v_mov_b32_e32 v127, 0
	v_mov_b32_dpp v119, v114 row_ror:8 row_mask:0xf bank_mask:0xf
	v_cndmask_b32_e64 v114, v121, v113, s[2:3]
	v_cndmask_b32_e64 v116, v126, v120, s[2:3]
	v_cndmask_b32_e64 v120, v112, v126, s[2:3]
	v_add_u32_e32 v112, -8, v148
	v_mov_b32_dpp v127, v114 row_ror:8 row_mask:0xf bank_mask:0xf
	v_cndmask_b32_e64 v112, v112, v148, s[2:3]
	v_lshl_or_b32 v146, s62, 8, v142
	v_cndmask_b32_e64 v117, v127, v121, s[2:3]
	v_cndmask_b32_e64 v121, v113, v127, s[2:3]
	v_ashrrev_i32_e32 v113, 31, v112
	v_ashrrev_i32_e32 v147, 31, v146
	v_lshlrev_b64 v[112:113], 11, v[112:113]
	v_cndmask_b32_e64 v115, v119, v125, s[2:3]
	v_cndmask_b32_e64 v114, v123, v124, s[2:3]
	v_cndmask_b32_e64 v119, v118, v119, s[2:3]
	v_cndmask_b32_e64 v118, v122, v123, s[2:3]
	v_lshl_add_u64 v[122:123], s[40:41], 0, v[112:113]
	v_lshlrev_b64 v[112:113], 1, v[146:147]
	v_lshl_add_u64 v[122:123], v[122:123], 0, v[112:113]
	global_store_dwordx4 v[122:123], v[114:117], off
	v_cvt_pk_bf16_f32 v108, v108, v109
	v_cvt_pk_bf16_f32 v100, v100, v101
	v_add_u32_e32 v116, 8, v148
	v_cndmask_b32_e64 v114, v148, v116, s[2:3]
	v_ashrrev_i32_e32 v115, 31, v114
	v_lshlrev_b64 v[114:115], 11, v[114:115]
	v_lshl_add_u64 v[114:115], s[40:41], 0, v[114:115]
	v_cvt_pk_bf16_f32 v109, v110, v111
	v_cvt_pk_bf16_f32 v104, v104, v105
	v_cvt_pk_bf16_f32 v105, v106, v107
	v_cvt_pk_bf16_f32 v101, v102, v103
	v_cvt_pk_bf16_f32 v102, v96, v97
	v_cndmask_b32_e64 v96, v108, v100, s[2:3]
	v_mov_b32_e32 v106, 0
	v_lshl_add_u64 v[114:115], v[114:115], 0, v[112:113]
	v_cvt_pk_bf16_f32 v103, v98, v99
	v_mov_b32_dpp v106, v96 row_ror:8 row_mask:0xf bank_mask:0xf
	v_cndmask_b32_e64 v96, v109, v101, s[2:3]
	v_mov_b32_e32 v107, 0
	v_cndmask_b32_e64 v97, v104, v102, s[2:3]
	v_mov_b32_e32 v110, 0
	global_store_dwordx4 v[114:115], v[118:121], off
	v_or_b32_e32 v114, 16, v148
	v_mov_b32_dpp v107, v96 row_ror:8 row_mask:0xf bank_mask:0xf
	v_cndmask_b32_e64 v96, v105, v103, s[2:3]
	v_mov_b32_dpp v110, v97 row_ror:8 row_mask:0xf bank_mask:0xf
	v_mov_b32_e32 v111, 0
	v_cndmask_b32_e64 v98, v110, v104, s[2:3]
	v_cndmask_b32_e64 v104, v116, v114, s[2:3]
	v_mov_b32_dpp v111, v96 row_ror:8 row_mask:0xf bank_mask:0xf
	v_cndmask_b32_e64 v99, v111, v105, s[2:3]
	v_ashrrev_i32_e32 v105, 31, v104
	v_lshlrev_b64 v[104:105], 11, v[104:105]
	v_lshl_add_u64 v[104:105], s[40:41], 0, v[104:105]
	v_cndmask_b32_e64 v97, v107, v109, s[2:3]
	v_cndmask_b32_e64 v96, v106, v108, s[2:3]
	v_lshl_add_u64 v[104:105], v[104:105], 0, v[112:113]
	global_store_dwordx4 v[104:105], v[96:99], off
	v_cvt_pk_bf16_f32 v92, v92, v93
	v_cvt_pk_bf16_f32 v84, v84, v85
	v_add_u32_e32 v98, 24, v148
	v_cndmask_b32_e64 v96, v114, v98, s[2:3]
	v_ashrrev_i32_e32 v97, 31, v96
	v_lshlrev_b64 v[96:97], 11, v[96:97]
	v_lshl_add_u64 v[96:97], s[40:41], 0, v[96:97]
	v_cvt_pk_bf16_f32 v93, v94, v95
	v_cvt_pk_bf16_f32 v88, v88, v89
	v_cvt_pk_bf16_f32 v89, v90, v91
	v_cvt_pk_bf16_f32 v85, v86, v87
	v_cvt_pk_bf16_f32 v86, v80, v81
	v_cndmask_b32_e64 v80, v92, v84, s[2:3]
	v_mov_b32_e32 v90, 0
	v_cndmask_b32_e64 v103, v103, v111, s[2:3]
	v_cndmask_b32_e64 v102, v102, v110, s[2:3]
	v_cndmask_b32_e64 v101, v101, v107, s[2:3]
	v_cndmask_b32_e64 v100, v100, v106, s[2:3]
	v_lshl_add_u64 v[96:97], v[96:97], 0, v[112:113]
	v_cvt_pk_bf16_f32 v87, v82, v83
	v_mov_b32_dpp v90, v80 row_ror:8 row_mask:0xf bank_mask:0xf
	v_cndmask_b32_e64 v80, v93, v85, s[2:3]
	v_mov_b32_e32 v91, 0
	v_cndmask_b32_e64 v81, v88, v86, s[2:3]
	v_mov_b32_e32 v94, 0
	global_store_dwordx4 v[96:97], v[100:103], off
	v_or_b32_e32 v96, 32, v148
	v_mov_b32_dpp v91, v80 row_ror:8 row_mask:0xf bank_mask:0xf
	v_cndmask_b32_e64 v80, v89, v87, s[2:3]
	v_mov_b32_dpp v94, v81 row_ror:8 row_mask:0xf bank_mask:0xf
	v_mov_b32_e32 v95, 0
	v_cndmask_b32_e64 v82, v94, v88, s[2:3]
	v_cndmask_b32_e64 v88, v98, v96, s[2:3]
	v_mov_b32_dpp v95, v80 row_ror:8 row_mask:0xf bank_mask:0xf
	v_cndmask_b32_e64 v83, v95, v89, s[2:3]
	v_ashrrev_i32_e32 v89, 31, v88
	v_lshlrev_b64 v[88:89], 11, v[88:89]
	v_lshl_add_u64 v[88:89], s[40:41], 0, v[88:89]
	v_cndmask_b32_e64 v81, v91, v93, s[2:3]
	v_cndmask_b32_e64 v80, v90, v92, s[2:3]
	v_lshl_add_u64 v[88:89], v[88:89], 0, v[112:113]
	global_store_dwordx4 v[88:89], v[80:83], off
	v_cvt_pk_bf16_f32 v76, v76, v77
	v_cvt_pk_bf16_f32 v68, v68, v69
	v_add_u32_e32 v82, 40, v148
	v_cndmask_b32_e64 v80, v96, v82, s[2:3]
	v_ashrrev_i32_e32 v81, 31, v80
	v_lshlrev_b64 v[80:81], 11, v[80:81]
	v_lshl_add_u64 v[80:81], s[40:41], 0, v[80:81]
	v_cvt_pk_bf16_f32 v77, v78, v79
	v_cvt_pk_bf16_f32 v72, v72, v73
	v_cvt_pk_bf16_f32 v73, v74, v75
	v_cvt_pk_bf16_f32 v69, v70, v71
	v_cvt_pk_bf16_f32 v70, v64, v65
	v_cndmask_b32_e64 v64, v76, v68, s[2:3]
	v_mov_b32_e32 v74, 0
	v_cndmask_b32_e64 v87, v87, v95, s[2:3]
	v_cndmask_b32_e64 v86, v86, v94, s[2:3]
	v_cndmask_b32_e64 v85, v85, v91, s[2:3]
	v_cndmask_b32_e64 v84, v84, v90, s[2:3]
	v_lshl_add_u64 v[80:81], v[80:81], 0, v[112:113]
	v_cvt_pk_bf16_f32 v71, v66, v67
	v_mov_b32_dpp v74, v64 row_ror:8 row_mask:0xf bank_mask:0xf
	v_cndmask_b32_e64 v64, v77, v69, s[2:3]
	v_mov_b32_e32 v75, 0
	v_cndmask_b32_e64 v65, v72, v70, s[2:3]
	v_mov_b32_e32 v78, 0
	global_store_dwordx4 v[80:81], v[84:87], off
	v_or_b32_e32 v80, 48, v148
	v_mov_b32_dpp v75, v64 row_ror:8 row_mask:0xf bank_mask:0xf
	v_cndmask_b32_e64 v64, v73, v71, s[2:3]
	v_mov_b32_dpp v78, v65 row_ror:8 row_mask:0xf bank_mask:0xf
	v_mov_b32_e32 v79, 0
	v_cndmask_b32_e64 v66, v78, v72, s[2:3]
	v_cndmask_b32_e64 v72, v82, v80, s[2:3]
	v_mov_b32_dpp v79, v64 row_ror:8 row_mask:0xf bank_mask:0xf
	v_cndmask_b32_e64 v67, v79, v73, s[2:3]
	v_ashrrev_i32_e32 v73, 31, v72
	v_lshlrev_b64 v[72:73], 11, v[72:73]
	v_lshl_add_u64 v[72:73], s[40:41], 0, v[72:73]
	v_cndmask_b32_e64 v65, v75, v77, s[2:3]
	v_cndmask_b32_e64 v64, v74, v76, s[2:3]
	v_lshl_add_u64 v[72:73], v[72:73], 0, v[112:113]
	global_store_dwordx4 v[72:73], v[64:67], off
	v_cvt_pk_bf16_f32 v60, v60, v61
	v_cvt_pk_bf16_f32 v56, v56, v57
	v_add_u32_e32 v64, 56, v148
	v_cndmask_b32_e64 v64, v80, v64, s[2:3]
	v_ashrrev_i32_e32 v65, 31, v64
	v_lshlrev_b64 v[64:65], 11, v[64:65]
	v_cvt_pk_bf16_f32 v52, v52, v53
	v_cvt_pk_bf16_f32 v53, v54, v55
	v_cvt_pk_bf16_f32 v54, v48, v49
	v_lshl_add_u64 v[64:65], s[40:41], 0, v[64:65]
	v_cvt_pk_bf16_f32 v61, v62, v63
	v_cvt_pk_bf16_f32 v57, v58, v59
	v_cndmask_b32_e64 v48, v60, v52, s[2:3]
	v_mov_b32_e32 v58, 0
	v_cndmask_b32_e64 v49, v56, v54, s[2:3]
	v_mov_b32_e32 v62, 0
	v_cndmask_b32_e64 v71, v71, v79, s[2:3]
	v_cndmask_b32_e64 v70, v70, v78, s[2:3]
	v_cndmask_b32_e64 v69, v69, v75, s[2:3]
	v_cndmask_b32_e64 v68, v68, v74, s[2:3]
	v_lshl_add_u64 v[64:65], v[64:65], 0, v[112:113]
	v_cvt_pk_bf16_f32 v55, v50, v51
	v_mov_b32_dpp v58, v48 row_ror:8 row_mask:0xf bank_mask:0xf
	v_cndmask_b32_e64 v48, v61, v53, s[2:3]
	v_mov_b32_e32 v59, 0
	v_mov_b32_dpp v62, v49 row_ror:8 row_mask:0xf bank_mask:0xf
	global_store_dwordx4 v[64:65], v[68:71], off
	v_add_u32_e32 v64, 0x80, v148
	v_mov_b32_dpp v59, v48 row_ror:8 row_mask:0xf bank_mask:0xf
	v_cndmask_b32_e64 v48, v57, v55, s[2:3]
	v_mov_b32_e32 v63, 0
	v_cndmask_b32_e64 v50, v62, v56, s[2:3]
	v_add_u32_e32 v56, 0x78, v148
	v_mov_b32_dpp v63, v48 row_ror:8 row_mask:0xf bank_mask:0xf
	v_cndmask_b32_e64 v56, v56, v64, s[2:3]
	v_cndmask_b32_e64 v51, v63, v57, s[2:3]
	v_ashrrev_i32_e32 v57, 31, v56
	v_lshlrev_b64 v[56:57], 11, v[56:57]
	v_lshl_add_u64 v[56:57], s[40:41], 0, v[56:57]
	v_cndmask_b32_e64 v49, v59, v61, s[2:3]
	v_cndmask_b32_e64 v48, v58, v60, s[2:3]
	v_lshl_add_u64 v[56:57], v[56:57], 0, v[112:113]
	global_store_dwordx4 v[56:57], v[48:51], off
	v_cvt_pk_bf16_f32 v44, v44, v45
	v_cvt_pk_bf16_f32 v36, v36, v37
	v_add_u32_e32 v50, 0x88, v148
	v_cndmask_b32_e64 v48, v64, v50, s[2:3]
	v_ashrrev_i32_e32 v49, 31, v48
	v_lshlrev_b64 v[48:49], 11, v[48:49]
	v_lshl_add_u64 v[48:49], s[40:41], 0, v[48:49]
	v_cvt_pk_bf16_f32 v45, v46, v47
	v_cvt_pk_bf16_f32 v40, v40, v41
	v_cvt_pk_bf16_f32 v41, v42, v43
	v_cvt_pk_bf16_f32 v37, v38, v39
	v_cvt_pk_bf16_f32 v38, v32, v33
	v_cndmask_b32_e64 v32, v44, v36, s[2:3]
	v_mov_b32_e32 v42, 0
	v_cndmask_b32_e64 v55, v55, v63, s[2:3]
	v_cndmask_b32_e64 v54, v54, v62, s[2:3]
	v_cndmask_b32_e64 v53, v53, v59, s[2:3]
	v_cndmask_b32_e64 v52, v52, v58, s[2:3]
	v_lshl_add_u64 v[48:49], v[48:49], 0, v[112:113]
	v_cvt_pk_bf16_f32 v39, v34, v35
	v_mov_b32_dpp v42, v32 row_ror:8 row_mask:0xf bank_mask:0xf
	v_cndmask_b32_e64 v32, v45, v37, s[2:3]
	v_mov_b32_e32 v43, 0
	v_cndmask_b32_e64 v33, v40, v38, s[2:3]
	v_mov_b32_e32 v46, 0
	global_store_dwordx4 v[48:49], v[52:55], off
	v_add_u32_e32 v48, 0x90, v148
	v_mov_b32_dpp v43, v32 row_ror:8 row_mask:0xf bank_mask:0xf
	v_cndmask_b32_e64 v32, v41, v39, s[2:3]
	v_mov_b32_dpp v46, v33 row_ror:8 row_mask:0xf bank_mask:0xf
	v_mov_b32_e32 v47, 0
	v_cndmask_b32_e64 v34, v46, v40, s[2:3]
	v_cndmask_b32_e64 v40, v50, v48, s[2:3]
	v_mov_b32_dpp v47, v32 row_ror:8 row_mask:0xf bank_mask:0xf
	v_cndmask_b32_e64 v35, v47, v41, s[2:3]
	v_ashrrev_i32_e32 v41, 31, v40
	v_lshlrev_b64 v[40:41], 11, v[40:41]
	v_lshl_add_u64 v[40:41], s[40:41], 0, v[40:41]
	v_cndmask_b32_e64 v33, v43, v45, s[2:3]
	v_cndmask_b32_e64 v32, v42, v44, s[2:3]
	v_lshl_add_u64 v[40:41], v[40:41], 0, v[112:113]
	global_store_dwordx4 v[40:41], v[32:35], off
	v_cvt_pk_bf16_f32 v28, v28, v29
	v_cvt_pk_bf16_f32 v20, v20, v21
	v_add_u32_e32 v34, 0x98, v148
	v_cndmask_b32_e64 v32, v48, v34, s[2:3]
	v_ashrrev_i32_e32 v33, 31, v32
	v_lshlrev_b64 v[32:33], 11, v[32:33]
	v_lshl_add_u64 v[32:33], s[40:41], 0, v[32:33]
	v_cvt_pk_bf16_f32 v29, v30, v31
	v_cvt_pk_bf16_f32 v24, v24, v25
	v_cvt_pk_bf16_f32 v25, v26, v27
	v_cvt_pk_bf16_f32 v21, v22, v23
	v_cvt_pk_bf16_f32 v22, v16, v17
	v_cndmask_b32_e64 v16, v28, v20, s[2:3]
	v_mov_b32_e32 v26, 0
	v_cndmask_b32_e64 v39, v39, v47, s[2:3]
	v_cndmask_b32_e64 v38, v38, v46, s[2:3]
	v_cndmask_b32_e64 v37, v37, v43, s[2:3]
	v_cndmask_b32_e64 v36, v36, v42, s[2:3]
	v_lshl_add_u64 v[32:33], v[32:33], 0, v[112:113]
	v_cvt_pk_bf16_f32 v23, v18, v19
	v_mov_b32_dpp v26, v16 row_ror:8 row_mask:0xf bank_mask:0xf
	v_cndmask_b32_e64 v16, v29, v21, s[2:3]
	v_mov_b32_e32 v27, 0
	v_cndmask_b32_e64 v17, v24, v22, s[2:3]
	v_mov_b32_e32 v30, 0
	global_store_dwordx4 v[32:33], v[36:39], off
	v_add_u32_e32 v32, 0xa0, v148
	v_mov_b32_dpp v27, v16 row_ror:8 row_mask:0xf bank_mask:0xf
	v_cndmask_b32_e64 v16, v25, v23, s[2:3]
	v_mov_b32_dpp v30, v17 row_ror:8 row_mask:0xf bank_mask:0xf
	v_mov_b32_e32 v31, 0
	v_cndmask_b32_e64 v18, v30, v24, s[2:3]
	v_cndmask_b32_e64 v24, v34, v32, s[2:3]
	v_mov_b32_dpp v31, v16 row_ror:8 row_mask:0xf bank_mask:0xf
	v_cndmask_b32_e64 v19, v31, v25, s[2:3]
	v_ashrrev_i32_e32 v25, 31, v24
	v_lshlrev_b64 v[24:25], 11, v[24:25]
	v_lshl_add_u64 v[24:25], s[40:41], 0, v[24:25]
	v_cndmask_b32_e64 v17, v27, v29, s[2:3]
	v_cndmask_b32_e64 v16, v26, v28, s[2:3]
	v_lshl_add_u64 v[24:25], v[24:25], 0, v[112:113]
	global_store_dwordx4 v[24:25], v[16:19], off
	v_cndmask_b32_e64 v23, v23, v31, s[2:3]
	v_cndmask_b32_e64 v22, v22, v30, s[2:3]
	v_add_u32_e32 v18, 0xa8, v148
	v_cndmask_b32_e64 v16, v32, v18, s[2:3]
	v_ashrrev_i32_e32 v17, 31, v16
	v_lshlrev_b64 v[16:17], 11, v[16:17]
	v_lshl_add_u64 v[16:17], s[40:41], 0, v[16:17]
	v_cndmask_b32_e64 v21, v21, v27, s[2:3]
	v_cndmask_b32_e64 v20, v20, v26, s[2:3]
	v_lshl_add_u64 v[16:17], v[16:17], 0, v[112:113]
	global_store_dwordx4 v[16:17], v[20:23], off
	v_add_u32_e32 v16, 0xb0, v148
	v_cvt_pk_bf16_f32 v12, v12, v13
	v_cvt_pk_bf16_f32 v8, v8, v9
	v_cvt_pk_bf16_f32 v9, v10, v11
	v_cvt_pk_bf16_f32 v10, v4, v5
	v_cvt_pk_bf16_f32 v13, v14, v15
	v_cvt_pk_bf16_f32 v6, v6, v7
	v_cvt_pk_bf16_f32 v7, v0, v1
	v_cndmask_b32_e64 v0, v12, v10, s[2:3]
	v_mov_b32_e32 v14, 0
	v_cndmask_b32_e64 v4, v18, v16, s[2:3]
	v_cvt_pk_bf16_f32 v11, v2, v3
	v_mov_b32_dpp v14, v0 row_ror:8 row_mask:0xf bank_mask:0xf
	v_cndmask_b32_e64 v0, v13, v6, s[2:3]
	v_mov_b32_e32 v15, 0
	v_ashrrev_i32_e32 v5, 31, v4
	v_cndmask_b32_e64 v1, v8, v7, s[2:3]
	v_mov_b32_dpp v15, v0 row_ror:8 row_mask:0xf bank_mask:0xf
	v_cndmask_b32_e64 v0, v9, v11, s[2:3]
	v_mov_b32_e32 v17, 0
	v_mov_b32_e32 v19, 0
	v_lshlrev_b64 v[4:5], 11, v[4:5]
	v_mov_b32_dpp v17, v1 row_ror:8 row_mask:0xf bank_mask:0xf
	v_mov_b32_dpp v19, v0 row_ror:8 row_mask:0xf bank_mask:0xf
	v_lshl_add_u64 v[4:5], s[40:41], 0, v[4:5]
	v_cndmask_b32_e64 v3, v19, v9, s[2:3]
	v_cndmask_b32_e64 v2, v17, v8, s[2:3]
	v_cndmask_b32_e64 v1, v15, v13, s[2:3]
	v_cndmask_b32_e64 v0, v14, v12, s[2:3]
	v_lshl_add_u64 v[4:5], v[4:5], 0, v[112:113]
	global_store_dwordx4 v[4:5], v[0:3], off
	s_and_b64 vcc, exec, s[4:5]
	s_mov_b32 s62, s6
	v_add_u32_e32 v0, 0xb8, v148
	v_cndmask_b32_e64 v0, v16, v0, s[2:3]
	v_ashrrev_i32_e32 v1, 31, v0
	v_lshlrev_b64 v[0:1], 11, v[0:1]
	v_lshl_add_u64 v[0:1], s[40:41], 0, v[0:1]
	v_lshl_add_u64 v[4:5], v[0:1], 0, v[112:113]
	v_cndmask_b32_e64 v3, v11, v19, s[2:3]
	v_cndmask_b32_e64 v2, v7, v17, s[2:3]
	v_cndmask_b32_e64 v1, v6, v15, s[2:3]
	v_cndmask_b32_e64 v0, v10, v14, s[2:3]
	s_mov_b32 s42, s8
	s_mov_b64 s[46:47], s[12:13]
	s_mov_b64 s[44:45], s[10:11]
	global_store_dwordx4 v[4:5], v[0:3], off
	s_cbranch_vccz .LBB0_335
	s_waitcnt vmcnt(0)
	s_cmpk_gt_u32 s17, 0xff
	s_cbranch_scc1 .LBB0_346
	s_barrier

.LBB0_667:
	s_add_u32 s56, s52, s54
	s_addc_u32 s57, s53, s55
	s_add_u32 s56, s56, 0x100
	s_addc_u32 s57, s57, 0
	s_add_u32 vcc_lo, s96, s54
	s_addc_u32 vcc_hi, s97, s55
	s_cmpk_eq_i32 s54, 0x700
	s_cselect_b32 s59, s47, s57
	s_cselect_b32 s58, s94, s56
	s_cselect_b32 s57, s45, vcc_hi
	s_cselect_b32 s56, s95, vcc_lo
	s_add_i32 vcc_lo, 0, 0x10000
	v_add_u32_e32 v1, vcc_lo, v196
	ds_read_b128 v[132:135], v1
	ds_read_b128 v[136:139], v1 offset:1024
	ds_read_b128 v[140:143], v1 offset:2048
	ds_read_b128 v[144:147], v1 offset:3072
	v_lshl_add_u64 v[2:3], v[188:189], 0, s[54:55]
	s_add_i32 m0, s63, 0xc000
	ds_read_b128 v[148:151], v199
	ds_read_b128 v[152:155], v199 offset:1024
	ds_read_b128 v[156:159], v199 offset:2048
	ds_read_b128 v[160:163], v199 offset:3072
	ds_read_b128 v[164:167], v199 offset:4096
	ds_read_b128 v[200:203], v199 offset:5120
	ds_read_b128 v[204:207], v199 offset:6144
	ds_read_b128 v[208:211], v199 offset:7168
	global_load_lds_dwordx4 v[2:3], off
	s_add_i32 m0, s63, 0xe000
	v_lshl_add_u64 v[2:3], v[190:191], 0, s[54:55]
	global_load_lds_dwordx4 v[2:3], off
	s_waitcnt lgkmcnt(8)
	s_barrier
	s_waitcnt lgkmcnt(0)
	s_waitcnt lgkmcnt(0)
	v_mfma_f32_16x16x32_bf16 v[128:131], v[132:135], v[148:151], v[128:131]
	v_mfma_f32_16x16x32_bf16 v[124:127], v[140:143], v[148:151], v[124:127]
	v_mfma_f32_16x16x32_bf16 v[112:115], v[132:135], v[156:159], v[112:115]
	v_mfma_f32_16x16x32_bf16 v[108:111], v[140:143], v[156:159], v[108:111]
	v_mfma_f32_16x16x32_bf16 v[96:99], v[132:135], v[164:167], v[96:99]
	v_mfma_f32_16x16x32_bf16 v[92:95], v[140:143], v[164:167], v[92:95]
	v_mfma_f32_16x16x32_bf16 v[80:83], v[132:135], v[204:207], v[80:83]
	v_mfma_f32_16x16x32_bf16 v[76:79], v[140:143], v[204:207], v[76:79]
	v_mfma_f32_16x16x32_bf16 v[128:131], v[136:139], v[152:155], v[128:131]
	v_mfma_f32_16x16x32_bf16 v[124:127], v[144:147], v[152:155], v[124:127]
	v_mfma_f32_16x16x32_bf16 v[112:115], v[136:139], v[160:163], v[112:115]
	v_mfma_f32_16x16x32_bf16 v[108:111], v[144:147], v[160:163], v[108:111]
	v_mfma_f32_16x16x32_bf16 v[96:99], v[136:139], v[200:203], v[96:99]
	v_mfma_f32_16x16x32_bf16 v[92:95], v[144:147], v[200:203], v[92:95]
	v_mfma_f32_16x16x32_bf16 v[80:83], v[136:139], v[208:211], v[80:83]
	v_mfma_f32_16x16x32_bf16 v[76:79], v[144:147], v[208:211], v[76:79]
	s_barrier
	s_add_i32 vcc_lo, vcc_lo, s61
	v_add_u32_e32 v1, s93, v196
	v_lshl_add_u64 v[228:229], s[56:57], 0, v[172:173]
	s_mov_b32 m0, vcc_lo
	ds_read_b128 v[212:215], v1
	ds_read_b128 v[216:219], v1 offset:1024
	ds_read_b128 v[220:223], v1 offset:2048
	ds_read_b128 v[224:227], v1 offset:3072
	global_load_lds_dwordx4 v[228:229], off
	s_add_i32 m0, vcc_lo, 0x2000
	v_lshl_add_u64 v[230:231], s[56:57], 0, v[168:169]
	global_load_lds_dwordx4 v[230:231], off
	s_barrier
	s_waitcnt lgkmcnt(0)
	s_waitcnt lgkmcnt(0)
	v_mfma_f32_16x16x32_bf16 v[120:123], v[212:215], v[148:151], v[120:123]
	v_mfma_f32_16x16x32_bf16 v[116:119], v[220:223], v[148:151], v[116:119]
	v_mfma_f32_16x16x32_bf16 v[104:107], v[212:215], v[156:159], v[104:107]
	v_mfma_f32_16x16x32_bf16 v[100:103], v[220:223], v[156:159], v[100:103]
	v_mfma_f32_16x16x32_bf16 v[88:91], v[212:215], v[164:167], v[88:91]
	v_mfma_f32_16x16x32_bf16 v[84:87], v[220:223], v[164:167], v[84:87]
	v_mfma_f32_16x16x32_bf16 v[72:75], v[212:215], v[204:207], v[72:75]
	v_mfma_f32_16x16x32_bf16 v[68:71], v[220:223], v[204:207], v[68:71]
	v_mfma_f32_16x16x32_bf16 v[120:123], v[216:219], v[152:155], v[120:123]
	v_mfma_f32_16x16x32_bf16 v[116:119], v[224:227], v[152:155], v[116:119]
	v_mfma_f32_16x16x32_bf16 v[104:107], v[216:219], v[160:163], v[104:107]
	v_mfma_f32_16x16x32_bf16 v[100:103], v[224:227], v[160:163], v[100:103]
	v_mfma_f32_16x16x32_bf16 v[88:91], v[216:219], v[200:203], v[88:91]
	v_mfma_f32_16x16x32_bf16 v[84:87], v[224:227], v[200:203], v[84:87]
	v_mfma_f32_16x16x32_bf16 v[72:75], v[216:219], v[208:211], v[72:75]
	v_mfma_f32_16x16x32_bf16 v[68:71], v[224:227], v[208:211], v[68:71]
	s_mov_b32 m0, s63
	v_lshl_add_u64 v[232:233], s[58:59], 0, v[174:175]
	s_barrier
	ds_read_b128 v[148:151], v199 offset:16384
	ds_read_b128 v[152:155], v199 offset:17408
	ds_read_b128 v[156:159], v199 offset:18432
	ds_read_b128 v[160:163], v199 offset:19456
	ds_read_b128 v[164:167], v199 offset:20480
	ds_read_b128 v[200:203], v199 offset:21504
	ds_read_b128 v[204:207], v199 offset:22528
	ds_read_b128 v[208:211], v199 offset:23552
	global_load_lds_dwordx4 v[232:233], off
	s_mov_b32 m0, s64
	v_lshl_add_u64 v[234:235], s[58:59], 0, v[170:171]
	global_load_lds_dwordx4 v[234:235], off
	s_barrier
	s_waitcnt lgkmcnt(0)
	s_waitcnt lgkmcnt(0)
	v_mfma_f32_16x16x32_bf16 v[64:67], v[132:135], v[148:151], v[64:67]
	v_mfma_f32_16x16x32_bf16 v[60:63], v[140:143], v[148:151], v[60:63]
	v_mfma_f32_16x16x32_bf16 v[48:51], v[132:135], v[156:159], v[48:51]
	v_mfma_f32_16x16x32_bf16 v[44:47], v[140:143], v[156:159], v[44:47]
	v_mfma_f32_16x16x32_bf16 v[32:35], v[132:135], v[164:167], v[32:35]
	v_mfma_f32_16x16x32_bf16 v[28:31], v[140:143], v[164:167], v[28:31]
	v_mfma_f32_16x16x32_bf16 v[16:19], v[132:135], v[204:207], v[16:19]
	v_mfma_f32_16x16x32_bf16 v[12:15], v[140:143], v[204:207], v[12:15]
	v_mfma_f32_16x16x32_bf16 v[64:67], v[136:139], v[152:155], v[64:67]
	v_mfma_f32_16x16x32_bf16 v[60:63], v[144:147], v[152:155], v[60:63]
	v_mfma_f32_16x16x32_bf16 v[48:51], v[136:139], v[160:163], v[48:51]
	v_mfma_f32_16x16x32_bf16 v[44:47], v[144:147], v[160:163], v[44:47]
	v_mfma_f32_16x16x32_bf16 v[32:35], v[136:139], v[200:203], v[32:35]
	v_mfma_f32_16x16x32_bf16 v[28:31], v[144:147], v[200:203], v[28:31]
	v_mfma_f32_16x16x32_bf16 v[16:19], v[136:139], v[208:211], v[16:19]
	v_mfma_f32_16x16x32_bf16 v[12:15], v[144:147], v[208:211], v[12:15]
	s_barrier
	s_add_u32 vcc_lo, s56, 0x10000
	s_addc_u32 vcc_hi, s57, 0
	s_add_i32 s28, s93, s61
	s_mov_b32 m0, s28
	v_lshl_add_u64 v[2:3], vcc, 0, v[172:173]
	global_load_lds_dwordx4 v[2:3], off
	s_add_i32 m0, s28, 0x2000
	v_lshl_add_u64 v[2:3], vcc, 0, v[168:169]
	global_load_lds_dwordx4 v[2:3], off
	s_waitcnt vmcnt(6)
	s_barrier
	v_mfma_f32_16x16x32_bf16 v[56:59], v[212:215], v[148:151], v[56:59]
	v_mfma_f32_16x16x32_bf16 v[52:55], v[220:223], v[148:151], v[52:55]
	v_mfma_f32_16x16x32_bf16 v[40:43], v[212:215], v[156:159], v[40:43]
	v_mfma_f32_16x16x32_bf16 v[36:39], v[220:223], v[156:159], v[36:39]
	v_mfma_f32_16x16x32_bf16 v[24:27], v[212:215], v[164:167], v[24:27]
	v_mfma_f32_16x16x32_bf16 v[20:23], v[220:223], v[164:167], v[20:23]
	v_mfma_f32_16x16x32_bf16 v[8:11], v[212:215], v[204:207], v[8:11]
	v_mfma_f32_16x16x32_bf16 v[2:5], v[220:223], v[204:207], v[4:7]
	v_mfma_f32_16x16x32_bf16 v[56:59], v[216:219], v[152:155], v[56:59]
	v_mfma_f32_16x16x32_bf16 v[52:55], v[224:227], v[152:155], v[52:55]
	v_mfma_f32_16x16x32_bf16 v[40:43], v[216:219], v[160:163], v[40:43]
	v_mfma_f32_16x16x32_bf16 v[36:39], v[224:227], v[160:163], v[36:39]
	v_mfma_f32_16x16x32_bf16 v[24:27], v[216:219], v[200:203], v[24:27]
	v_mfma_f32_16x16x32_bf16 v[20:23], v[224:227], v[200:203], v[20:23]
	v_mfma_f32_16x16x32_bf16 v[8:11], v[216:219], v[208:211], v[8:11]
	v_mfma_f32_16x16x32_bf16 v[2:5], v[224:227], v[208:211], v[2:5]
	s_add_i32 s28, 0, 0x18000
	v_add_u32_e32 v1, s28, v196
	s_barrier
	ds_read_b128 v[132:135], v1
	ds_read_b128 v[136:139], v1 offset:1024
	ds_read_b128 v[140:143], v1 offset:2048
	ds_read_b128 v[144:147], v1 offset:3072
	s_add_u32 s58, s58, 0x40000
	s_addc_u32 s59, s59, 0
	s_mov_b32 m0, s65
	v_lshl_add_u64 v[6:7], s[58:59], 0, v[174:175]
	ds_read_b128 v[148:151], v199 offset:32768
	ds_read_b128 v[152:155], v199 offset:33792
	ds_read_b128 v[156:159], v199 offset:34816
	ds_read_b128 v[160:163], v199 offset:35840
	ds_read_b128 v[164:167], v199 offset:36864
	ds_read_b128 v[200:203], v199 offset:37888
	ds_read_b128 v[204:207], v199 offset:38912
	ds_read_b128 v[208:211], v199 offset:39936
	global_load_lds_dwordx4 v[6:7], off
	s_mov_b32 m0, s66
	v_lshl_add_u64 v[6:7], s[58:59], 0, v[170:171]
	global_load_lds_dwordx4 v[6:7], off
	s_waitcnt lgkmcnt(8)
	s_barrier
	s_waitcnt lgkmcnt(0)
	s_waitcnt lgkmcnt(0)
	v_mfma_f32_16x16x32_bf16 v[128:131], v[132:135], v[148:151], v[128:131]
	v_mfma_f32_16x16x32_bf16 v[124:127], v[140:143], v[148:151], v[124:127]
	v_mfma_f32_16x16x32_bf16 v[112:115], v[132:135], v[156:159], v[112:115]
	v_mfma_f32_16x16x32_bf16 v[108:111], v[140:143], v[156:159], v[108:111]
	v_mfma_f32_16x16x32_bf16 v[96:99], v[132:135], v[164:167], v[96:99]
	v_mfma_f32_16x16x32_bf16 v[92:95], v[140:143], v[164:167], v[92:95]
	v_mfma_f32_16x16x32_bf16 v[80:83], v[132:135], v[204:207], v[80:83]
	v_mfma_f32_16x16x32_bf16 v[76:79], v[140:143], v[204:207], v[76:79]
	v_mfma_f32_16x16x32_bf16 v[128:131], v[136:139], v[152:155], v[128:131]
	v_mfma_f32_16x16x32_bf16 v[124:127], v[144:147], v[152:155], v[124:127]
	v_mfma_f32_16x16x32_bf16 v[112:115], v[136:139], v[160:163], v[112:115]
	v_mfma_f32_16x16x32_bf16 v[108:111], v[144:147], v[160:163], v[108:111]
	v_mfma_f32_16x16x32_bf16 v[96:99], v[136:139], v[200:203], v[96:99]
	v_mfma_f32_16x16x32_bf16 v[92:95], v[144:147], v[200:203], v[92:95]
	v_mfma_f32_16x16x32_bf16 v[80:83], v[136:139], v[208:211], v[80:83]
	v_mfma_f32_16x16x32_bf16 v[76:79], v[144:147], v[208:211], v[76:79]
	s_barrier
	s_add_i32 s29, 0, 0x1c000
	s_add_i32 s28, s28, s61
	v_add_u32_e32 v1, s29, v196
	v_lshl_add_u64 v[6:7], v[228:229], 0, s[0:1]
	s_mov_b32 m0, s28
	ds_read_b128 v[212:215], v1
	ds_read_b128 v[216:219], v1 offset:1024
	ds_read_b128 v[220:223], v1 offset:2048
	ds_read_b128 v[224:227], v1 offset:3072
	global_load_lds_dwordx4 v[6:7], off
	s_add_i32 m0, s28, 0x2000
	v_lshl_add_u64 v[6:7], v[230:231], 0, s[0:1]
	global_load_lds_dwordx4 v[6:7], off
	s_barrier
	s_waitcnt lgkmcnt(0)
	s_waitcnt lgkmcnt(0)
	v_mfma_f32_16x16x32_bf16 v[120:123], v[212:215], v[148:151], v[120:123]
	v_mfma_f32_16x16x32_bf16 v[116:119], v[220:223], v[148:151], v[116:119]
	v_mfma_f32_16x16x32_bf16 v[104:107], v[212:215], v[156:159], v[104:107]
	v_mfma_f32_16x16x32_bf16 v[100:103], v[220:223], v[156:159], v[100:103]
	v_mfma_f32_16x16x32_bf16 v[88:91], v[212:215], v[164:167], v[88:91]
	v_mfma_f32_16x16x32_bf16 v[84:87], v[220:223], v[164:167], v[84:87]
	v_mfma_f32_16x16x32_bf16 v[72:75], v[212:215], v[204:207], v[72:75]
	v_mfma_f32_16x16x32_bf16 v[68:71], v[220:223], v[204:207], v[68:71]
	v_mfma_f32_16x16x32_bf16 v[120:123], v[216:219], v[152:155], v[120:123]
	v_mfma_f32_16x16x32_bf16 v[116:119], v[224:227], v[152:155], v[116:119]
	v_mfma_f32_16x16x32_bf16 v[104:107], v[216:219], v[160:163], v[104:107]
	v_mfma_f32_16x16x32_bf16 v[100:103], v[224:227], v[160:163], v[100:103]
	v_mfma_f32_16x16x32_bf16 v[88:91], v[216:219], v[200:203], v[88:91]
	v_mfma_f32_16x16x32_bf16 v[84:87], v[224:227], v[200:203], v[84:87]
	v_mfma_f32_16x16x32_bf16 v[72:75], v[216:219], v[208:211], v[72:75]
	v_mfma_f32_16x16x32_bf16 v[68:71], v[224:227], v[208:211], v[68:71]
	s_mov_b32 m0, s81
	v_lshl_add_u64 v[6:7], v[232:233], 0, s[0:1]
	s_barrier
	ds_read_b128 v[148:151], v199 offset:49152
	ds_read_b128 v[152:155], v199 offset:50176
	ds_read_b128 v[156:159], v199 offset:51200
	ds_read_b128 v[160:163], v199 offset:52224
	ds_read_b128 v[164:167], v199 offset:53248
	ds_read_b128 v[200:203], v199 offset:54272
	ds_read_b128 v[204:207], v199 offset:55296
	ds_read_b128 v[208:211], v199 offset:56320
	global_load_lds_dwordx4 v[6:7], off
	s_mov_b32 m0, s82
	v_lshl_add_u64 v[6:7], v[234:235], 0, s[0:1]
	global_load_lds_dwordx4 v[6:7], off
	s_barrier
	s_waitcnt lgkmcnt(0)
	s_waitcnt lgkmcnt(0)
	v_mfma_f32_16x16x32_bf16 v[64:67], v[132:135], v[148:151], v[64:67]
	v_mfma_f32_16x16x32_bf16 v[60:63], v[140:143], v[148:151], v[60:63]
	v_mfma_f32_16x16x32_bf16 v[48:51], v[132:135], v[156:159], v[48:51]
	v_mfma_f32_16x16x32_bf16 v[44:47], v[140:143], v[156:159], v[44:47]
	v_mfma_f32_16x16x32_bf16 v[32:35], v[132:135], v[164:167], v[32:35]
	v_mfma_f32_16x16x32_bf16 v[28:31], v[140:143], v[164:167], v[28:31]
	v_mfma_f32_16x16x32_bf16 v[16:19], v[132:135], v[204:207], v[16:19]
	v_mfma_f32_16x16x32_bf16 v[12:15], v[140:143], v[204:207], v[12:15]
	v_mfma_f32_16x16x32_bf16 v[64:67], v[136:139], v[152:155], v[64:67]
	v_mfma_f32_16x16x32_bf16 v[60:63], v[144:147], v[152:155], v[60:63]
	v_mfma_f32_16x16x32_bf16 v[48:51], v[136:139], v[160:163], v[48:51]
	v_mfma_f32_16x16x32_bf16 v[44:47], v[144:147], v[160:163], v[44:47]
	v_mfma_f32_16x16x32_bf16 v[32:35], v[136:139], v[200:203], v[32:35]
	v_mfma_f32_16x16x32_bf16 v[28:31], v[144:147], v[200:203], v[28:31]
	v_mfma_f32_16x16x32_bf16 v[16:19], v[136:139], v[208:211], v[16:19]
	v_mfma_f32_16x16x32_bf16 v[12:15], v[144:147], v[208:211], v[12:15]
	s_barrier
	s_add_u32 s56, s56, 0x10080
	s_addc_u32 s57, s57, 0
	s_add_i32 s28, s29, s61
	s_mov_b32 m0, s28
	v_lshl_add_u64 v[6:7], s[56:57], 0, v[172:173]
	global_load_lds_dwordx4 v[6:7], off
	s_add_i32 m0, s28, 0x2000
	v_lshl_add_u64 v[6:7], s[56:57], 0, v[168:169]
	global_load_lds_dwordx4 v[6:7], off
	s_waitcnt vmcnt(6)
	s_barrier
	v_mfma_f32_16x16x32_bf16 v[56:59], v[212:215], v[148:151], v[56:59]
	v_mfma_f32_16x16x32_bf16 v[52:55], v[220:223], v[148:151], v[52:55]
	v_mfma_f32_16x16x32_bf16 v[40:43], v[212:215], v[156:159], v[40:43]
	v_mfma_f32_16x16x32_bf16 v[36:39], v[220:223], v[156:159], v[36:39]
	v_mfma_f32_16x16x32_bf16 v[24:27], v[212:215], v[164:167], v[24:27]
	v_mfma_f32_16x16x32_bf16 v[20:23], v[220:223], v[164:167], v[20:23]
	v_mfma_f32_16x16x32_bf16 v[6:9], v[212:215], v[204:207], v[8:11]
	v_mfma_f32_16x16x32_bf16 v[2:5], v[220:223], v[204:207], v[2:5]
	v_mfma_f32_16x16x32_bf16 v[56:59], v[216:219], v[152:155], v[56:59]
	v_mfma_f32_16x16x32_bf16 v[52:55], v[224:227], v[152:155], v[52:55]
	v_mfma_f32_16x16x32_bf16 v[40:43], v[216:219], v[160:163], v[40:43]
	v_mfma_f32_16x16x32_bf16 v[36:39], v[224:227], v[160:163], v[36:39]
	v_mfma_f32_16x16x32_bf16 v[24:27], v[216:219], v[200:203], v[24:27]
	v_mfma_f32_16x16x32_bf16 v[20:23], v[224:227], v[200:203], v[20:23]
	v_mfma_f32_16x16x32_bf16 v[8:11], v[216:219], v[208:211], v[6:9]
	v_mfma_f32_16x16x32_bf16 v[4:7], v[224:227], v[208:211], v[2:5]
	s_add_i32 s17, s17, 2
	s_add_u32 s54, s54, 0x100
	s_addc_u32 s55, s55, 0
	s_cmp_gt_u32 s17, 13
	s_barrier
	s_cbranch_scc1 .LBB0_659

.LBB0_740:
	ds_read_b128 v[64:67], v221
	ds_read_b128 v[68:71], v221 offset:1024
	ds_read_b128 v[84:87], v221 offset:2048
	ds_read_b128 v[92:95], v221 offset:3072
	s_add_u32 s28, s10, 0xfffc0080
	s_addc_u32 s29, s11, -1
	s_cmp_eq_u32 s92, 12
	s_cselect_b32 s65, s9, s29
	s_cselect_b32 s64, s13, s28
	s_cselect_b32 s63, s17, s57
	s_cselect_b32 s62, s44, s55
	v_lshl_add_u64 v[176:177], s[10:11], 0, v[204:205]
	s_add_i32 m0, s78, 0xc000
	ds_read_b128 v[144:147], v222
	ds_read_b128 v[148:151], v222 offset:1024
	ds_read_b128 v[152:155], v222 offset:2048
	ds_read_b128 v[156:159], v222 offset:3072
	ds_read_b128 v[160:163], v222 offset:4096
	ds_read_b128 v[164:167], v222 offset:5120
	ds_read_b128 v[168:171], v222 offset:6144
	ds_read_b128 v[172:175], v222 offset:7168
	global_load_lds_dwordx4 v[176:177], off
	s_add_i32 m0, s78, 0xe000
	v_lshl_add_u64 v[176:177], s[10:11], 0, v[206:207]
	global_load_lds_dwordx4 v[176:177], off
	s_waitcnt lgkmcnt(8)
	s_barrier
	s_waitcnt lgkmcnt(0)
	s_waitcnt lgkmcnt(0)
	v_mfma_f32_16x16x32_bf16 v[140:143], v[64:67], v[144:147], v[140:143]
	v_mfma_f32_16x16x32_bf16 v[136:139], v[84:87], v[144:147], v[136:139]
	v_mfma_f32_16x16x32_bf16 v[124:127], v[64:67], v[152:155], v[124:127]
	v_mfma_f32_16x16x32_bf16 v[120:123], v[84:87], v[152:155], v[120:123]
	v_mfma_f32_16x16x32_bf16 v[108:111], v[64:67], v[160:163], v[108:111]
	v_mfma_f32_16x16x32_bf16 v[104:107], v[84:87], v[160:163], v[104:107]
	v_mfma_f32_16x16x32_bf16 v[88:91], v[64:67], v[168:171], v[88:91]
	v_mfma_f32_16x16x32_bf16 v[80:83], v[84:87], v[168:171], v[80:83]
	v_mfma_f32_16x16x32_bf16 v[140:143], v[68:71], v[148:151], v[140:143]
	v_mfma_f32_16x16x32_bf16 v[136:139], v[92:95], v[148:151], v[136:139]
	v_mfma_f32_16x16x32_bf16 v[124:127], v[68:71], v[156:159], v[124:127]
	v_mfma_f32_16x16x32_bf16 v[120:123], v[92:95], v[156:159], v[120:123]
	v_mfma_f32_16x16x32_bf16 v[108:111], v[68:71], v[164:167], v[108:111]
	v_mfma_f32_16x16x32_bf16 v[104:107], v[92:95], v[164:167], v[104:107]
	v_mfma_f32_16x16x32_bf16 v[88:91], v[68:71], v[172:175], v[88:91]
	v_mfma_f32_16x16x32_bf16 v[80:83], v[92:95], v[172:175], v[80:83]
	s_barrier
	s_add_i32 s28, s89, s67
	v_lshl_add_u64 v[212:213], s[62:63], 0, v[198:199]
	s_mov_b32 m0, s28
	ds_read_b128 v[176:179], v223
	ds_read_b128 v[180:183], v223 offset:1024
	ds_read_b128 v[184:187], v223 offset:2048
	ds_read_b128 v[188:191], v223 offset:3072
	global_load_lds_dwordx4 v[212:213], off
	s_add_i32 m0, s28, 0x2000
	v_lshl_add_u64 v[214:215], s[62:63], 0, v[202:203]
	global_load_lds_dwordx4 v[214:215], off
	s_barrier
	s_waitcnt lgkmcnt(0)
	s_waitcnt lgkmcnt(0)
	v_mfma_f32_16x16x32_bf16 v[132:135], v[176:179], v[144:147], v[132:135]
	v_mfma_f32_16x16x32_bf16 v[128:131], v[184:187], v[144:147], v[128:131]
	v_mfma_f32_16x16x32_bf16 v[116:119], v[176:179], v[152:155], v[116:119]
	v_mfma_f32_16x16x32_bf16 v[112:115], v[184:187], v[152:155], v[112:115]
	v_mfma_f32_16x16x32_bf16 v[100:103], v[176:179], v[160:163], v[100:103]
	v_mfma_f32_16x16x32_bf16 v[96:99], v[184:187], v[160:163], v[96:99]
	v_mfma_f32_16x16x32_bf16 v[76:79], v[176:179], v[168:171], v[76:79]
	v_mfma_f32_16x16x32_bf16 v[72:75], v[184:187], v[168:171], v[72:75]
	v_mfma_f32_16x16x32_bf16 v[132:135], v[180:183], v[148:151], v[132:135]
	v_mfma_f32_16x16x32_bf16 v[128:131], v[188:191], v[148:151], v[128:131]
	v_mfma_f32_16x16x32_bf16 v[116:119], v[180:183], v[156:159], v[116:119]
	v_mfma_f32_16x16x32_bf16 v[112:115], v[188:191], v[156:159], v[112:115]
	v_mfma_f32_16x16x32_bf16 v[100:103], v[180:183], v[164:167], v[100:103]
	v_mfma_f32_16x16x32_bf16 v[96:99], v[188:191], v[164:167], v[96:99]
	v_mfma_f32_16x16x32_bf16 v[76:79], v[180:183], v[172:175], v[76:79]
	v_mfma_f32_16x16x32_bf16 v[72:75], v[188:191], v[172:175], v[72:75]
	s_mov_b32 m0, s78
	v_lshl_add_u64 v[216:217], s[64:65], 0, v[196:197]
	s_barrier
	ds_read_b128 v[144:147], v222 offset:16384
	ds_read_b128 v[148:151], v222 offset:17408
	ds_read_b128 v[152:155], v222 offset:18432
	ds_read_b128 v[156:159], v222 offset:19456
	ds_read_b128 v[160:163], v222 offset:20480
	ds_read_b128 v[164:167], v222 offset:21504
	ds_read_b128 v[168:171], v222 offset:22528
	ds_read_b128 v[172:175], v222 offset:23552
	global_load_lds_dwordx4 v[216:217], off
	s_mov_b32 m0, s79
	v_lshl_add_u64 v[226:227], s[64:65], 0, v[200:201]
	global_load_lds_dwordx4 v[226:227], off
	s_barrier
	s_waitcnt lgkmcnt(0)
	s_waitcnt lgkmcnt(0)
	v_mfma_f32_16x16x32_bf16 v[60:63], v[64:67], v[144:147], v[60:63]
	v_mfma_f32_16x16x32_bf16 v[56:59], v[84:87], v[144:147], v[56:59]
	v_mfma_f32_16x16x32_bf16 v[44:47], v[64:67], v[152:155], v[44:47]
	v_mfma_f32_16x16x32_bf16 v[40:43], v[84:87], v[152:155], v[40:43]
	v_mfma_f32_16x16x32_bf16 v[28:31], v[64:67], v[160:163], v[28:31]
	v_mfma_f32_16x16x32_bf16 v[24:27], v[84:87], v[160:163], v[24:27]
	v_mfma_f32_16x16x32_bf16 v[12:15], v[64:67], v[168:171], v[12:15]
	v_mfma_f32_16x16x32_bf16 v[8:11], v[84:87], v[168:171], v[8:11]
	v_mfma_f32_16x16x32_bf16 v[60:63], v[68:71], v[148:151], v[60:63]
	v_mfma_f32_16x16x32_bf16 v[56:59], v[92:95], v[148:151], v[56:59]
	v_mfma_f32_16x16x32_bf16 v[44:47], v[68:71], v[156:159], v[44:47]
	v_mfma_f32_16x16x32_bf16 v[40:43], v[92:95], v[156:159], v[40:43]
	v_mfma_f32_16x16x32_bf16 v[28:31], v[68:71], v[164:167], v[28:31]
	v_mfma_f32_16x16x32_bf16 v[24:27], v[92:95], v[164:167], v[24:27]
	v_mfma_f32_16x16x32_bf16 v[12:15], v[68:71], v[172:175], v[12:15]
	v_mfma_f32_16x16x32_bf16 v[8:11], v[92:95], v[172:175], v[8:11]
	s_barrier
	s_add_u32 s94, s62, 0x10000
	s_addc_u32 s95, s63, 0
	s_add_i32 s28, s90, s67
	s_mov_b32 m0, s28
	v_lshl_add_u64 v[64:65], s[94:95], 0, v[198:199]
	global_load_lds_dwordx4 v[64:65], off
	s_add_i32 m0, s28, 0x2000
	v_lshl_add_u64 v[64:65], s[94:95], 0, v[202:203]
	global_load_lds_dwordx4 v[64:65], off
	s_waitcnt vmcnt(6)
	s_barrier
	v_mfma_f32_16x16x32_bf16 v[52:55], v[176:179], v[144:147], v[52:55]
	v_mfma_f32_16x16x32_bf16 v[48:51], v[184:187], v[144:147], v[48:51]
	v_mfma_f32_16x16x32_bf16 v[36:39], v[176:179], v[152:155], v[36:39]
	v_mfma_f32_16x16x32_bf16 v[32:35], v[184:187], v[152:155], v[32:35]
	v_mfma_f32_16x16x32_bf16 v[20:23], v[176:179], v[160:163], v[20:23]
	v_mfma_f32_16x16x32_bf16 v[16:19], v[184:187], v[160:163], v[16:19]
	v_mfma_f32_16x16x32_bf16 v[4:7], v[176:179], v[168:171], v[4:7]
	v_mfma_f32_16x16x32_bf16 v[0:3], v[184:187], v[168:171], v[0:3]
	v_mfma_f32_16x16x32_bf16 v[52:55], v[180:183], v[148:151], v[52:55]
	v_mfma_f32_16x16x32_bf16 v[48:51], v[188:191], v[148:151], v[48:51]
	v_mfma_f32_16x16x32_bf16 v[36:39], v[180:183], v[156:159], v[36:39]
	v_mfma_f32_16x16x32_bf16 v[32:35], v[188:191], v[156:159], v[32:35]
	v_mfma_f32_16x16x32_bf16 v[20:23], v[180:183], v[164:167], v[20:23]
	v_mfma_f32_16x16x32_bf16 v[16:19], v[188:191], v[164:167], v[16:19]
	v_mfma_f32_16x16x32_bf16 v[4:7], v[180:183], v[172:175], v[4:7]
	v_mfma_f32_16x16x32_bf16 v[0:3], v[188:191], v[172:175], v[0:3]
	s_add_i32 s28, 0, 0x18000
	v_add_u32_e32 v92, s28, v218
	s_barrier
	ds_read_b128 v[64:67], v92
	ds_read_b128 v[68:71], v92 offset:1024
	ds_read_b128 v[84:87], v92 offset:2048
	ds_read_b128 v[92:95], v92 offset:3072
	s_add_u32 s64, s64, 0x40000
	s_addc_u32 s65, s65, 0
	s_mov_b32 m0, s80
	v_lshl_add_u64 v[176:177], s[64:65], 0, v[196:197]
	ds_read_b128 v[144:147], v222 offset:32768
	ds_read_b128 v[148:151], v222 offset:33792
	ds_read_b128 v[152:155], v222 offset:34816
	ds_read_b128 v[156:159], v222 offset:35840
	ds_read_b128 v[160:163], v222 offset:36864
	ds_read_b128 v[164:167], v222 offset:37888
	ds_read_b128 v[168:171], v222 offset:38912
	ds_read_b128 v[172:175], v222 offset:39936
	global_load_lds_dwordx4 v[176:177], off
	s_mov_b32 m0, s81
	v_lshl_add_u64 v[176:177], s[64:65], 0, v[200:201]
	global_load_lds_dwordx4 v[176:177], off
	s_waitcnt lgkmcnt(8)
	s_barrier
	s_waitcnt lgkmcnt(0)
	s_waitcnt lgkmcnt(0)
	v_mfma_f32_16x16x32_bf16 v[140:143], v[64:67], v[144:147], v[140:143]
	v_mfma_f32_16x16x32_bf16 v[136:139], v[84:87], v[144:147], v[136:139]
	v_mfma_f32_16x16x32_bf16 v[124:127], v[64:67], v[152:155], v[124:127]
	v_mfma_f32_16x16x32_bf16 v[120:123], v[84:87], v[152:155], v[120:123]
	v_mfma_f32_16x16x32_bf16 v[108:111], v[64:67], v[160:163], v[108:111]
	v_mfma_f32_16x16x32_bf16 v[104:107], v[84:87], v[160:163], v[104:107]
	v_mfma_f32_16x16x32_bf16 v[88:91], v[64:67], v[168:171], v[88:91]
	v_mfma_f32_16x16x32_bf16 v[80:83], v[84:87], v[168:171], v[80:83]
	v_mfma_f32_16x16x32_bf16 v[140:143], v[68:71], v[148:151], v[140:143]
	v_mfma_f32_16x16x32_bf16 v[136:139], v[92:95], v[148:151], v[136:139]
	v_mfma_f32_16x16x32_bf16 v[124:127], v[68:71], v[156:159], v[124:127]
	v_mfma_f32_16x16x32_bf16 v[120:123], v[92:95], v[156:159], v[120:123]
	v_mfma_f32_16x16x32_bf16 v[108:111], v[68:71], v[164:167], v[108:111]
	v_mfma_f32_16x16x32_bf16 v[104:107], v[92:95], v[164:167], v[104:107]
	v_mfma_f32_16x16x32_bf16 v[88:91], v[68:71], v[172:175], v[88:91]
	v_mfma_f32_16x16x32_bf16 v[80:83], v[92:95], v[172:175], v[80:83]
	s_barrier
	s_add_i32 s29, 0, 0x1c000
	s_add_i32 s28, s28, s67
	v_add_u32_e32 v188, s29, v218
	v_lshl_add_u64 v[212:213], v[212:213], 0, s[52:53]
	s_mov_b32 m0, s28
	ds_read_b128 v[176:179], v188
	ds_read_b128 v[180:183], v188 offset:1024
	ds_read_b128 v[184:187], v188 offset:2048
	ds_read_b128 v[188:191], v188 offset:3072
	global_load_lds_dwordx4 v[212:213], off
	s_add_i32 m0, s28, 0x2000
	v_lshl_add_u64 v[212:213], v[214:215], 0, s[52:53]
	global_load_lds_dwordx4 v[212:213], off
	s_barrier
	s_waitcnt lgkmcnt(0)
	s_waitcnt lgkmcnt(0)
	v_mfma_f32_16x16x32_bf16 v[132:135], v[176:179], v[144:147], v[132:135]
	v_mfma_f32_16x16x32_bf16 v[128:131], v[184:187], v[144:147], v[128:131]
	v_mfma_f32_16x16x32_bf16 v[116:119], v[176:179], v[152:155], v[116:119]
	v_mfma_f32_16x16x32_bf16 v[112:115], v[184:187], v[152:155], v[112:115]
	v_mfma_f32_16x16x32_bf16 v[100:103], v[176:179], v[160:163], v[100:103]
	v_mfma_f32_16x16x32_bf16 v[96:99], v[184:187], v[160:163], v[96:99]
	v_mfma_f32_16x16x32_bf16 v[76:79], v[176:179], v[168:171], v[76:79]
	v_mfma_f32_16x16x32_bf16 v[72:75], v[184:187], v[168:171], v[72:75]
	v_mfma_f32_16x16x32_bf16 v[132:135], v[180:183], v[148:151], v[132:135]
	v_mfma_f32_16x16x32_bf16 v[128:131], v[188:191], v[148:151], v[128:131]
	v_mfma_f32_16x16x32_bf16 v[116:119], v[180:183], v[156:159], v[116:119]
	v_mfma_f32_16x16x32_bf16 v[112:115], v[188:191], v[156:159], v[112:115]
	v_mfma_f32_16x16x32_bf16 v[100:103], v[180:183], v[164:167], v[100:103]
	v_mfma_f32_16x16x32_bf16 v[96:99], v[188:191], v[164:167], v[96:99]
	v_mfma_f32_16x16x32_bf16 v[76:79], v[180:183], v[172:175], v[76:79]
	v_mfma_f32_16x16x32_bf16 v[72:75], v[188:191], v[172:175], v[72:75]
	s_mov_b32 m0, s85
	v_lshl_add_u64 v[212:213], v[216:217], 0, s[52:53]
	s_barrier
	ds_read_b128 v[144:147], v222 offset:49152
	ds_read_b128 v[148:151], v222 offset:50176
	ds_read_b128 v[152:155], v222 offset:51200
	ds_read_b128 v[156:159], v222 offset:52224
	ds_read_b128 v[160:163], v222 offset:53248
	ds_read_b128 v[164:167], v222 offset:54272
	ds_read_b128 v[168:171], v222 offset:55296
	ds_read_b128 v[172:175], v222 offset:56320
	global_load_lds_dwordx4 v[212:213], off
	s_mov_b32 m0, s87
	v_lshl_add_u64 v[212:213], v[226:227], 0, s[52:53]
	global_load_lds_dwordx4 v[212:213], off
	s_barrier
	s_waitcnt lgkmcnt(0)
	s_waitcnt lgkmcnt(0)
	v_mfma_f32_16x16x32_bf16 v[60:63], v[64:67], v[144:147], v[60:63]
	v_mfma_f32_16x16x32_bf16 v[56:59], v[84:87], v[144:147], v[56:59]
	v_mfma_f32_16x16x32_bf16 v[44:47], v[64:67], v[152:155], v[44:47]
	v_mfma_f32_16x16x32_bf16 v[40:43], v[84:87], v[152:155], v[40:43]
	v_mfma_f32_16x16x32_bf16 v[28:31], v[64:67], v[160:163], v[28:31]
	v_mfma_f32_16x16x32_bf16 v[24:27], v[84:87], v[160:163], v[24:27]
	v_mfma_f32_16x16x32_bf16 v[12:15], v[64:67], v[168:171], v[12:15]
	v_mfma_f32_16x16x32_bf16 v[8:11], v[84:87], v[168:171], v[8:11]
	v_mfma_f32_16x16x32_bf16 v[60:63], v[68:71], v[148:151], v[60:63]
	v_mfma_f32_16x16x32_bf16 v[56:59], v[92:95], v[148:151], v[56:59]
	v_mfma_f32_16x16x32_bf16 v[44:47], v[68:71], v[156:159], v[44:47]
	v_mfma_f32_16x16x32_bf16 v[40:43], v[92:95], v[156:159], v[40:43]
	v_mfma_f32_16x16x32_bf16 v[28:31], v[68:71], v[164:167], v[28:31]
	v_mfma_f32_16x16x32_bf16 v[24:27], v[92:95], v[164:167], v[24:27]
	v_mfma_f32_16x16x32_bf16 v[12:15], v[68:71], v[172:175], v[12:15]
	v_mfma_f32_16x16x32_bf16 v[8:11], v[92:95], v[172:175], v[8:11]
	s_barrier
	s_add_u32 s62, s62, 0x10080
	s_addc_u32 s63, s63, 0
	s_add_i32 s28, s29, s67
	s_mov_b32 m0, s28
	v_lshl_add_u64 v[64:65], s[62:63], 0, v[198:199]
	global_load_lds_dwordx4 v[64:65], off
	s_add_i32 m0, s28, 0x2000
	v_lshl_add_u64 v[64:65], s[62:63], 0, v[202:203]
	global_load_lds_dwordx4 v[64:65], off
	s_waitcnt vmcnt(6)
	s_barrier
	v_mfma_f32_16x16x32_bf16 v[52:55], v[176:179], v[144:147], v[52:55]
	v_mfma_f32_16x16x32_bf16 v[48:51], v[184:187], v[144:147], v[48:51]
	v_mfma_f32_16x16x32_bf16 v[36:39], v[176:179], v[152:155], v[36:39]
	v_mfma_f32_16x16x32_bf16 v[32:35], v[184:187], v[152:155], v[32:35]
	v_mfma_f32_16x16x32_bf16 v[20:23], v[176:179], v[160:163], v[20:23]
	v_mfma_f32_16x16x32_bf16 v[16:19], v[184:187], v[160:163], v[16:19]
	v_mfma_f32_16x16x32_bf16 v[4:7], v[176:179], v[168:171], v[4:7]
	v_mfma_f32_16x16x32_bf16 v[0:3], v[184:187], v[168:171], v[0:3]
	v_mfma_f32_16x16x32_bf16 v[52:55], v[180:183], v[148:151], v[52:55]
	v_mfma_f32_16x16x32_bf16 v[48:51], v[188:191], v[148:151], v[48:51]
	v_mfma_f32_16x16x32_bf16 v[36:39], v[180:183], v[156:159], v[36:39]
	v_mfma_f32_16x16x32_bf16 v[32:35], v[188:191], v[156:159], v[32:35]
	v_mfma_f32_16x16x32_bf16 v[20:23], v[180:183], v[164:167], v[20:23]
	v_mfma_f32_16x16x32_bf16 v[16:19], v[188:191], v[164:167], v[16:19]
	v_mfma_f32_16x16x32_bf16 v[4:7], v[180:183], v[172:175], v[4:7]
	v_mfma_f32_16x16x32_bf16 v[0:3], v[188:191], v[172:175], v[0:3]
	s_add_i32 s92, s92, 2
	s_add_u32 s10, s10, 0x100
	s_addc_u32 s11, s11, 0
	s_add_u32 s55, s55, 0x100
	s_addc_u32 s57, s57, 0
	s_cmp_gt_u32 s92, 13
	s_barrier
	s_cbranch_scc0 .LBB0_740
	v_lshl_add_u32 v212, s8, 8, v195
	v_lshl_or_b32 v214, s12, 8, v219
	v_ashrrev_i32_e32 v213, 31, v212
	v_ashrrev_i32_e32 v215, 31, v214
	s_mov_b64 s[8:9], -1
	s_and_b64 vcc, exec, s[48:49]
	s_cbranch_vccz .LBB0_743
	v_lshlrev_b64 v[64:65], 12, v[212:213]
	v_lshl_add_u64 v[64:65], s[36:37], 0, v[64:65]
	v_lshl_add_u64 v[64:65], v[214:215], 2, v[64:65]
	global_load_dwordx4 v[160:163], v[64:65], off offset:16
	global_load_dwordx4 v[164:167], v[64:65], off
	global_load_dwordx4 v[168:171], v[64:65], off offset:144
	global_load_dwordx4 v[172:175], v[64:65], off offset:128
	s_mov_b64 s[8:9], 0

.LBB0_904:
	ds_read_b128 v[146:149], v169
	ds_read_b128 v[150:153], v169 offset:1024
	ds_read_b128 v[154:157], v169 offset:2048
	ds_read_b128 v[174:177], v169 offset:3072
	s_add_u32 s28, s0, 0xfffc0080
	s_addc_u32 s29, s1, -1
	s_cmp_eq_u32 s78, 12
	s_cselect_b32 s53, s7, s29
	s_cselect_b32 s52, s45, s28
	s_cselect_b32 s51, s37, s77
	s_cselect_b32 s50, s67, s76
	v_lshl_add_u64 v[158:159], s[0:1], 0, v[138:139]
	s_add_i32 m0, s54, 0xc000
	ds_read_b128 v[178:181], v171
	ds_read_b128 v[182:185], v171 offset:1024
	ds_read_b128 v[186:189], v171 offset:2048
	ds_read_b128 v[196:199], v171 offset:3072
	ds_read_b128 v[200:203], v171 offset:4096
	ds_read_b128 v[204:207], v171 offset:5120
	ds_read_b128 v[208:211], v171 offset:6144
	ds_read_b128 v[212:215], v171 offset:7168
	global_load_lds_dwordx4 v[158:159], off
	s_add_i32 m0, s54, 0xe000
	v_lshl_add_u64 v[158:159], s[0:1], 0, v[140:141]
	global_load_lds_dwordx4 v[158:159], off
	s_waitcnt lgkmcnt(8)
	s_barrier
	s_waitcnt lgkmcnt(0)
	s_waitcnt lgkmcnt(0)
	v_mfma_f32_16x16x32_bf16 v[124:127], v[146:149], v[178:181], v[124:127]
	v_mfma_f32_16x16x32_bf16 v[120:123], v[154:157], v[178:181], v[120:123]
	v_mfma_f32_16x16x32_bf16 v[108:111], v[146:149], v[186:189], v[108:111]
	v_mfma_f32_16x16x32_bf16 v[104:107], v[154:157], v[186:189], v[104:107]
	v_mfma_f32_16x16x32_bf16 v[92:95], v[146:149], v[200:203], v[92:95]
	v_mfma_f32_16x16x32_bf16 v[88:91], v[154:157], v[200:203], v[88:91]
	v_mfma_f32_16x16x32_bf16 v[76:79], v[146:149], v[208:211], v[76:79]
	v_mfma_f32_16x16x32_bf16 v[72:75], v[154:157], v[208:211], v[72:75]
	v_mfma_f32_16x16x32_bf16 v[124:127], v[150:153], v[182:185], v[124:127]
	v_mfma_f32_16x16x32_bf16 v[120:123], v[174:177], v[182:185], v[120:123]
	v_mfma_f32_16x16x32_bf16 v[108:111], v[150:153], v[196:199], v[108:111]
	v_mfma_f32_16x16x32_bf16 v[104:107], v[174:177], v[196:199], v[104:107]
	v_mfma_f32_16x16x32_bf16 v[92:95], v[150:153], v[204:207], v[92:95]
	v_mfma_f32_16x16x32_bf16 v[88:91], v[174:177], v[204:207], v[88:91]
	v_mfma_f32_16x16x32_bf16 v[76:79], v[150:153], v[212:215], v[76:79]
	v_mfma_f32_16x16x32_bf16 v[72:75], v[174:177], v[212:215], v[72:75]
	s_barrier
	s_add_i32 s28, s63, s13
	v_lshl_add_u64 v[158:159], s[50:51], 0, v[132:133]
	s_mov_b32 m0, s28
	ds_read_b128 v[216:219], v172
	ds_read_b128 v[220:223], v172 offset:1024
	ds_read_b128 v[224:227], v172 offset:2048
	ds_read_b128 v[228:231], v172 offset:3072
	global_load_lds_dwordx4 v[158:159], off
	s_add_i32 m0, s28, 0x2000
	v_lshl_add_u64 v[164:165], s[50:51], 0, v[128:129]
	global_load_lds_dwordx4 v[164:165], off
	s_barrier
	s_waitcnt lgkmcnt(0)
	s_waitcnt lgkmcnt(0)
	v_mfma_f32_16x16x32_bf16 v[116:119], v[216:219], v[178:181], v[116:119]
	v_mfma_f32_16x16x32_bf16 v[112:115], v[224:227], v[178:181], v[112:115]
	v_mfma_f32_16x16x32_bf16 v[100:103], v[216:219], v[186:189], v[100:103]
	v_mfma_f32_16x16x32_bf16 v[96:99], v[224:227], v[186:189], v[96:99]
	v_mfma_f32_16x16x32_bf16 v[84:87], v[216:219], v[200:203], v[84:87]
	v_mfma_f32_16x16x32_bf16 v[80:83], v[224:227], v[200:203], v[80:83]
	v_mfma_f32_16x16x32_bf16 v[68:71], v[216:219], v[208:211], v[68:71]
	v_mfma_f32_16x16x32_bf16 v[64:67], v[224:227], v[208:211], v[64:67]
	v_mfma_f32_16x16x32_bf16 v[116:119], v[220:223], v[182:185], v[116:119]
	v_mfma_f32_16x16x32_bf16 v[112:115], v[228:231], v[182:185], v[112:115]
	v_mfma_f32_16x16x32_bf16 v[100:103], v[220:223], v[196:199], v[100:103]
	v_mfma_f32_16x16x32_bf16 v[96:99], v[228:231], v[196:199], v[96:99]
	v_mfma_f32_16x16x32_bf16 v[84:87], v[220:223], v[204:207], v[84:87]
	v_mfma_f32_16x16x32_bf16 v[80:83], v[228:231], v[204:207], v[80:83]
	v_mfma_f32_16x16x32_bf16 v[68:71], v[220:223], v[212:215], v[68:71]
	v_mfma_f32_16x16x32_bf16 v[64:67], v[228:231], v[212:215], v[64:67]
	s_mov_b32 m0, s54
	v_lshl_add_u64 v[190:191], s[52:53], 0, v[134:135]
	s_barrier
	ds_read_b128 v[178:181], v171 offset:16384
	ds_read_b128 v[182:185], v171 offset:17408
	ds_read_b128 v[186:189], v171 offset:18432
	ds_read_b128 v[196:199], v171 offset:19456
	ds_read_b128 v[200:203], v171 offset:20480
	ds_read_b128 v[204:207], v171 offset:21504
	ds_read_b128 v[208:211], v171 offset:22528
	ds_read_b128 v[212:215], v171 offset:23552
	global_load_lds_dwordx4 v[190:191], off
	s_mov_b32 m0, s55
	v_lshl_add_u64 v[232:233], s[52:53], 0, v[130:131]
	global_load_lds_dwordx4 v[232:233], off
	s_barrier
	s_waitcnt lgkmcnt(0)
	s_waitcnt lgkmcnt(0)
	v_mfma_f32_16x16x32_bf16 v[60:63], v[146:149], v[178:181], v[60:63]
	v_mfma_f32_16x16x32_bf16 v[56:59], v[154:157], v[178:181], v[56:59]
	v_mfma_f32_16x16x32_bf16 v[44:47], v[146:149], v[186:189], v[44:47]
	v_mfma_f32_16x16x32_bf16 v[40:43], v[154:157], v[186:189], v[40:43]
	v_mfma_f32_16x16x32_bf16 v[28:31], v[146:149], v[200:203], v[28:31]
	v_mfma_f32_16x16x32_bf16 v[24:27], v[154:157], v[200:203], v[24:27]
	v_mfma_f32_16x16x32_bf16 v[12:15], v[146:149], v[208:211], v[12:15]
	v_mfma_f32_16x16x32_bf16 v[8:11], v[154:157], v[208:211], v[8:11]
	v_mfma_f32_16x16x32_bf16 v[60:63], v[150:153], v[182:185], v[60:63]
	v_mfma_f32_16x16x32_bf16 v[56:59], v[174:177], v[182:185], v[56:59]
	v_mfma_f32_16x16x32_bf16 v[44:47], v[150:153], v[196:199], v[44:47]
	v_mfma_f32_16x16x32_bf16 v[40:43], v[174:177], v[196:199], v[40:43]
	v_mfma_f32_16x16x32_bf16 v[28:31], v[150:153], v[204:207], v[28:31]
	v_mfma_f32_16x16x32_bf16 v[24:27], v[174:177], v[204:207], v[24:27]
	v_mfma_f32_16x16x32_bf16 v[12:15], v[150:153], v[212:215], v[12:15]
	v_mfma_f32_16x16x32_bf16 v[8:11], v[174:177], v[212:215], v[8:11]
	s_barrier
	s_add_u32 s80, s50, 0x10000
	s_addc_u32 s81, s51, 0
	s_add_i32 s28, s64, s13
	s_mov_b32 m0, s28
	v_lshl_add_u64 v[146:147], s[80:81], 0, v[132:133]
	global_load_lds_dwordx4 v[146:147], off
	s_add_i32 m0, s28, 0x2000
	v_lshl_add_u64 v[146:147], s[80:81], 0, v[128:129]
	global_load_lds_dwordx4 v[146:147], off
	s_waitcnt vmcnt(6)
	s_barrier
	v_mfma_f32_16x16x32_bf16 v[52:55], v[216:219], v[178:181], v[52:55]
	v_mfma_f32_16x16x32_bf16 v[48:51], v[224:227], v[178:181], v[48:51]
	v_mfma_f32_16x16x32_bf16 v[36:39], v[216:219], v[186:189], v[36:39]
	v_mfma_f32_16x16x32_bf16 v[32:35], v[224:227], v[186:189], v[32:35]
	v_mfma_f32_16x16x32_bf16 v[20:23], v[216:219], v[200:203], v[20:23]
	v_mfma_f32_16x16x32_bf16 v[16:19], v[224:227], v[200:203], v[16:19]
	v_mfma_f32_16x16x32_bf16 v[4:7], v[216:219], v[208:211], v[4:7]
	v_mfma_f32_16x16x32_bf16 v[0:3], v[224:227], v[208:211], v[0:3]
	v_mfma_f32_16x16x32_bf16 v[52:55], v[220:223], v[182:185], v[52:55]
	v_mfma_f32_16x16x32_bf16 v[48:51], v[228:231], v[182:185], v[48:51]
	v_mfma_f32_16x16x32_bf16 v[36:39], v[220:223], v[196:199], v[36:39]
	v_mfma_f32_16x16x32_bf16 v[32:35], v[228:231], v[196:199], v[32:35]
	v_mfma_f32_16x16x32_bf16 v[20:23], v[220:223], v[204:207], v[20:23]
	v_mfma_f32_16x16x32_bf16 v[16:19], v[228:231], v[204:207], v[16:19]
	v_mfma_f32_16x16x32_bf16 v[4:7], v[220:223], v[212:215], v[4:7]
	v_mfma_f32_16x16x32_bf16 v[0:3], v[228:231], v[212:215], v[0:3]
	s_add_i32 s28, 0, 0x18000
	v_add_u32_e32 v160, s28, v163
	s_barrier
	ds_read_b128 v[146:149], v160
	ds_read_b128 v[150:153], v160 offset:1024
	ds_read_b128 v[154:157], v160 offset:2048
	ds_read_b128 v[174:177], v160 offset:3072
	s_add_u32 s52, s52, 0x40000
	s_addc_u32 s53, s53, 0
	s_mov_b32 m0, s56
	v_lshl_add_u64 v[216:217], s[52:53], 0, v[134:135]
	ds_read_b128 v[178:181], v171 offset:32768
	ds_read_b128 v[182:185], v171 offset:33792
	ds_read_b128 v[186:189], v171 offset:34816
	ds_read_b128 v[196:199], v171 offset:35840
	ds_read_b128 v[200:203], v171 offset:36864
	ds_read_b128 v[204:207], v171 offset:37888
	ds_read_b128 v[208:211], v171 offset:38912
	ds_read_b128 v[212:215], v171 offset:39936
	global_load_lds_dwordx4 v[216:217], off
	s_mov_b32 m0, s57
	v_lshl_add_u64 v[216:217], s[52:53], 0, v[130:131]
	global_load_lds_dwordx4 v[216:217], off
	s_waitcnt lgkmcnt(8)
	s_barrier
	s_waitcnt lgkmcnt(0)
	s_waitcnt lgkmcnt(0)
	v_mfma_f32_16x16x32_bf16 v[124:127], v[146:149], v[178:181], v[124:127]
	v_mfma_f32_16x16x32_bf16 v[120:123], v[154:157], v[178:181], v[120:123]
	v_mfma_f32_16x16x32_bf16 v[108:111], v[146:149], v[186:189], v[108:111]
	v_mfma_f32_16x16x32_bf16 v[104:107], v[154:157], v[186:189], v[104:107]
	v_mfma_f32_16x16x32_bf16 v[92:95], v[146:149], v[200:203], v[92:95]
	v_mfma_f32_16x16x32_bf16 v[88:91], v[154:157], v[200:203], v[88:91]
	v_mfma_f32_16x16x32_bf16 v[76:79], v[146:149], v[208:211], v[76:79]
	v_mfma_f32_16x16x32_bf16 v[72:75], v[154:157], v[208:211], v[72:75]
	v_mfma_f32_16x16x32_bf16 v[124:127], v[150:153], v[182:185], v[124:127]
	v_mfma_f32_16x16x32_bf16 v[120:123], v[174:177], v[182:185], v[120:123]
	v_mfma_f32_16x16x32_bf16 v[108:111], v[150:153], v[196:199], v[108:111]
	v_mfma_f32_16x16x32_bf16 v[104:107], v[174:177], v[196:199], v[104:107]
	v_mfma_f32_16x16x32_bf16 v[92:95], v[150:153], v[204:207], v[92:95]
	v_mfma_f32_16x16x32_bf16 v[88:91], v[174:177], v[204:207], v[88:91]
	v_mfma_f32_16x16x32_bf16 v[76:79], v[150:153], v[212:215], v[76:79]
	v_mfma_f32_16x16x32_bf16 v[72:75], v[174:177], v[212:215], v[72:75]
	s_barrier
	s_add_i32 s29, 0, 0x1c000
	s_add_i32 s28, s28, s13
	v_add_u32_e32 v160, s29, v163
	v_lshl_add_u64 v[158:159], v[158:159], 0, s[8:9]
	s_mov_b32 m0, s28
	ds_read_b128 v[216:219], v160
	ds_read_b128 v[220:223], v160 offset:1024
	ds_read_b128 v[224:227], v160 offset:2048
	ds_read_b128 v[228:231], v160 offset:3072
	global_load_lds_dwordx4 v[158:159], off
	s_add_i32 m0, s28, 0x2000
	v_lshl_add_u64 v[158:159], v[164:165], 0, s[8:9]
	global_load_lds_dwordx4 v[158:159], off
	s_barrier
	s_waitcnt lgkmcnt(0)
	s_waitcnt lgkmcnt(0)
	v_mfma_f32_16x16x32_bf16 v[116:119], v[216:219], v[178:181], v[116:119]
	v_mfma_f32_16x16x32_bf16 v[112:115], v[224:227], v[178:181], v[112:115]
	v_mfma_f32_16x16x32_bf16 v[100:103], v[216:219], v[186:189], v[100:103]
	v_mfma_f32_16x16x32_bf16 v[96:99], v[224:227], v[186:189], v[96:99]
	v_mfma_f32_16x16x32_bf16 v[84:87], v[216:219], v[200:203], v[84:87]
	v_mfma_f32_16x16x32_bf16 v[80:83], v[224:227], v[200:203], v[80:83]
	v_mfma_f32_16x16x32_bf16 v[68:71], v[216:219], v[208:211], v[68:71]
	v_mfma_f32_16x16x32_bf16 v[64:67], v[224:227], v[208:211], v[64:67]
	v_mfma_f32_16x16x32_bf16 v[116:119], v[220:223], v[182:185], v[116:119]
	v_mfma_f32_16x16x32_bf16 v[112:115], v[228:231], v[182:185], v[112:115]
	v_mfma_f32_16x16x32_bf16 v[100:103], v[220:223], v[196:199], v[100:103]
	v_mfma_f32_16x16x32_bf16 v[96:99], v[228:231], v[196:199], v[96:99]
	v_mfma_f32_16x16x32_bf16 v[84:87], v[220:223], v[204:207], v[84:87]
	v_mfma_f32_16x16x32_bf16 v[80:83], v[228:231], v[204:207], v[80:83]
	v_mfma_f32_16x16x32_bf16 v[68:71], v[220:223], v[212:215], v[68:71]
	v_mfma_f32_16x16x32_bf16 v[64:67], v[228:231], v[212:215], v[64:67]
	s_mov_b32 m0, s60
	v_lshl_add_u64 v[158:159], v[190:191], 0, s[8:9]
	s_barrier
	ds_read_b128 v[178:181], v171 offset:49152
	ds_read_b128 v[182:185], v171 offset:50176
	ds_read_b128 v[186:189], v171 offset:51200
	ds_read_b128 v[196:199], v171 offset:52224
	ds_read_b128 v[200:203], v171 offset:53248
	ds_read_b128 v[204:207], v171 offset:54272
	ds_read_b128 v[208:211], v171 offset:55296
	ds_read_b128 v[212:215], v171 offset:56320
	global_load_lds_dwordx4 v[158:159], off
	s_mov_b32 m0, s61
	v_lshl_add_u64 v[158:159], v[232:233], 0, s[8:9]
	global_load_lds_dwordx4 v[158:159], off
	s_barrier
	s_waitcnt lgkmcnt(0)
	s_waitcnt lgkmcnt(0)
	v_mfma_f32_16x16x32_bf16 v[60:63], v[146:149], v[178:181], v[60:63]
	v_mfma_f32_16x16x32_bf16 v[56:59], v[154:157], v[178:181], v[56:59]
	v_mfma_f32_16x16x32_bf16 v[44:47], v[146:149], v[186:189], v[44:47]
	v_mfma_f32_16x16x32_bf16 v[40:43], v[154:157], v[186:189], v[40:43]
	v_mfma_f32_16x16x32_bf16 v[28:31], v[146:149], v[200:203], v[28:31]
	v_mfma_f32_16x16x32_bf16 v[24:27], v[154:157], v[200:203], v[24:27]
	v_mfma_f32_16x16x32_bf16 v[12:15], v[146:149], v[208:211], v[12:15]
	v_mfma_f32_16x16x32_bf16 v[8:11], v[154:157], v[208:211], v[8:11]
	v_mfma_f32_16x16x32_bf16 v[60:63], v[150:153], v[182:185], v[60:63]
	v_mfma_f32_16x16x32_bf16 v[56:59], v[174:177], v[182:185], v[56:59]
	v_mfma_f32_16x16x32_bf16 v[44:47], v[150:153], v[196:199], v[44:47]
	v_mfma_f32_16x16x32_bf16 v[40:43], v[174:177], v[196:199], v[40:43]
	v_mfma_f32_16x16x32_bf16 v[28:31], v[150:153], v[204:207], v[28:31]
	v_mfma_f32_16x16x32_bf16 v[24:27], v[174:177], v[204:207], v[24:27]
	v_mfma_f32_16x16x32_bf16 v[12:15], v[150:153], v[212:215], v[12:15]
	v_mfma_f32_16x16x32_bf16 v[8:11], v[174:177], v[212:215], v[8:11]
	s_barrier
	s_add_u32 s50, s50, 0x10080
	s_addc_u32 s51, s51, 0
	s_add_i32 s28, s29, s13
	s_mov_b32 m0, s28
	v_lshl_add_u64 v[146:147], s[50:51], 0, v[132:133]
	global_load_lds_dwordx4 v[146:147], off
	s_add_i32 m0, s28, 0x2000
	v_lshl_add_u64 v[146:147], s[50:51], 0, v[128:129]
	global_load_lds_dwordx4 v[146:147], off
	s_waitcnt vmcnt(6)
	s_barrier
	v_mfma_f32_16x16x32_bf16 v[52:55], v[216:219], v[178:181], v[52:55]
	v_mfma_f32_16x16x32_bf16 v[48:51], v[224:227], v[178:181], v[48:51]
	v_mfma_f32_16x16x32_bf16 v[36:39], v[216:219], v[186:189], v[36:39]
	v_mfma_f32_16x16x32_bf16 v[32:35], v[224:227], v[186:189], v[32:35]
	v_mfma_f32_16x16x32_bf16 v[20:23], v[216:219], v[200:203], v[20:23]
	v_mfma_f32_16x16x32_bf16 v[16:19], v[224:227], v[200:203], v[16:19]
	v_mfma_f32_16x16x32_bf16 v[4:7], v[216:219], v[208:211], v[4:7]
	v_mfma_f32_16x16x32_bf16 v[0:3], v[224:227], v[208:211], v[0:3]
	v_mfma_f32_16x16x32_bf16 v[52:55], v[220:223], v[182:185], v[52:55]
	v_mfma_f32_16x16x32_bf16 v[48:51], v[228:231], v[182:185], v[48:51]
	v_mfma_f32_16x16x32_bf16 v[36:39], v[220:223], v[196:199], v[36:39]
	v_mfma_f32_16x16x32_bf16 v[32:35], v[228:231], v[196:199], v[32:35]
	v_mfma_f32_16x16x32_bf16 v[20:23], v[220:223], v[204:207], v[20:23]
	v_mfma_f32_16x16x32_bf16 v[16:19], v[228:231], v[204:207], v[16:19]
	v_mfma_f32_16x16x32_bf16 v[4:7], v[220:223], v[212:215], v[4:7]
	v_mfma_f32_16x16x32_bf16 v[0:3], v[228:231], v[212:215], v[0:3]
	s_add_i32 s78, s78, 2
	s_add_u32 s0, s0, 0x100
	s_addc_u32 s1, s1, 0
	s_add_u32 s76, s76, 0x100
	s_addc_u32 s77, s77, 0
	s_cmp_gt_u32 s78, 13
	s_barrier
	s_cbranch_scc0 .LBB0_904
	v_lshl_add_u32 v146, s6, 8, v161
	v_or_b32_e32 v164, 16, v146
	v_ashrrev_i32_e32 v165, 31, v164
	v_lshlrev_b64 v[148:149], 6, v[164:165]
	v_or_b32_e32 v158, 32, v146
	v_lshl_add_u64 v[148:149], v[136:137], 0, v[148:149]
	v_ashrrev_i32_e32 v159, 31, v158
	v_or_b32_e32 v156, 48, v146
	global_load_dwordx4 v[174:177], v[148:149], off
	v_lshlrev_b64 v[148:149], 6, v[158:159]
	v_ashrrev_i32_e32 v157, 31, v156
	v_add_u32_e32 v154, 0x80, v146
	v_lshl_add_u64 v[148:149], v[136:137], 0, v[148:149]
	v_lshlrev_b64 v[150:151], 6, v[156:157]
	v_ashrrev_i32_e32 v155, 31, v154
	v_lshl_add_u64 v[150:151], v[136:137], 0, v[150:151]
	global_load_dwordx4 v[178:181], v[148:149], off
	global_load_dwordx4 v[182:185], v[150:151], off
	v_lshlrev_b64 v[148:149], 6, v[154:155]
	v_lshl_add_u64 v[148:149], v[136:137], 0, v[148:149]
	global_load_dwordx4 v[186:189], v[148:149], off
	v_ashrrev_i32_e32 v147, 31, v146
	v_lshlrev_b64 v[148:149], 6, v[146:147]
	v_add_u32_e32 v152, 0x90, v146
	v_lshl_add_u64 v[148:149], v[136:137], 0, v[148:149]
	v_ashrrev_i32_e32 v153, 31, v152
	global_load_dwordx4 v[196:199], v[148:149], off
	v_lshlrev_b64 v[148:149], 6, v[152:153]
	v_lshl_add_u64 v[148:149], v[136:137], 0, v[148:149]
	global_load_dwordx4 v[200:203], v[148:149], off
	v_add_u32_e32 v148, 0xa0, v146
	v_ashrrev_i32_e32 v149, 31, v148
	v_lshlrev_b64 v[150:151], 6, v[148:149]
	v_lshl_add_u64 v[150:151], v[136:137], 0, v[150:151]
	global_load_dwordx4 v[204:207], v[150:151], off
	v_add_u32_e32 v150, 0xb0, v146
	v_ashrrev_i32_e32 v151, 31, v150
	v_lshlrev_b64 v[208:209], 6, v[150:151]
	v_lshl_add_u64 v[208:209], v[136:137], 0, v[208:209]
	global_load_dwordx4 v[208:211], v[208:209], off
	v_and_b32_e32 v149, 64, v173
	v_xor_b32_e32 v147, 16, v173
	v_add_u32_e32 v149, 64, v149
	v_cmp_lt_i32_e32 vcc, v147, v149
	v_xor_b32_e32 v153, 32, v173
	v_mov_b64_e32 v[190:191], s[12:13]
	v_cndmask_b32_e32 v147, v173, v147, vcc
	v_lshlrev_b32_e32 v147, 2, v147
	v_cmp_lt_i32_e32 vcc, v153, v149
	s_waitcnt vmcnt(0)
	v_mov_b32_e32 v212, v175
	v_mov_b32_e32 v213, v176
	v_mov_b32_e32 v175, v177
	v_pk_add_f32 v[174:175], v[212:213], v[174:175]
	v_cndmask_b32_e32 v149, v173, v153, vcc
	v_lshlrev_b32_e32 v149, 2, v149
	v_mov_b32_e32 v176, v179
	v_mov_b32_e32 v177, v180
	v_mov_b32_e32 v179, v181
	v_mov_b32_e32 v180, v183
	v_mov_b32_e32 v181, v184
	v_mov_b32_e32 v183, v185
	v_mov_b32_e32 v184, v187
	v_mov_b32_e32 v185, v188
	v_mov_b32_e32 v187, v189
	v_pk_add_f32 v[176:177], v[176:177], v[178:179]
	v_pk_add_f32 v[178:179], v[180:181], v[182:183]
	v_pk_add_f32 v[180:181], v[184:185], v[186:187]
	v_mov_b32_e32 v182, v176
	v_mov_b32_e32 v183, v174
	v_mov_b32_e32 v174, v177
	v_mov_b32_e32 v176, v180
	v_mov_b32_e32 v177, v178
	v_mov_b32_e32 v178, v181
	v_pk_add_f32 v[174:175], v[182:183], v[174:175]
	v_pk_add_f32 v[176:177], v[176:177], v[178:179]
	ds_bpermute_b32 v179, v147, v175
	ds_bpermute_b32 v178, v147, v174
	ds_bpermute_b32 v181, v147, v177
	ds_bpermute_b32 v180, v147, v176
	v_mov_b32_e32 v184, v201
	v_mov_b32_e32 v185, v202
	s_waitcnt lgkmcnt(0)
	v_pk_add_f32 v[174:175], v[174:175], v[178:179]
	ds_bpermute_b32 v179, v149, v175
	v_pk_add_f32 v[176:177], v[176:177], v[180:181]
	ds_bpermute_b32 v178, v149, v174
	ds_bpermute_b32 v181, v149, v177
	ds_bpermute_b32 v180, v149, v176
	v_mov_b32_e32 v201, v203
	v_mov_b32_e32 v182, v197
	s_waitcnt lgkmcnt(2)
	v_pk_add_f32 v[174:175], v[174:175], v[178:179]
	v_pk_add_f32 v[178:179], v[184:185], v[200:201]
	s_waitcnt lgkmcnt(0)
	v_pk_add_f32 v[176:177], v[176:177], v[180:181]
	v_pk_fma_f32 v[174:175], v[174:175], s[10:11], v[190:191] op_sel_hi:[1,0,0]
	v_mov_b32_e32 v180, v205
	v_mov_b32_e32 v181, v206
	v_mov_b32_e32 v205, v207
	v_mul_f32_e32 v151, 0x4b800000, v175
	v_cmp_gt_f32_e32 vcc, s65, v175
	v_pk_add_f32 v[180:181], v[180:181], v[204:205]
	v_mov_b32_e32 v185, v178
	v_cndmask_b32_e32 v151, v175, v151, vcc
	v_mov_b32_e32 v184, v180
	v_mov_b32_e32 v178, v181
	v_rsq_f32_e32 v151, v151
	v_pk_add_f32 v[178:179], v[184:185], v[178:179]
	ds_bpermute_b32 v181, v147, v179
	ds_bpermute_b32 v180, v147, v178
	v_pk_fma_f32 v[176:177], v[176:177], s[10:11], v[190:191] op_sel_hi:[1,0,0]
	v_mul_f32_e32 v153, 0x4b800000, v174
	v_cmp_gt_f32_e64 s[0:1], s65, v174
	v_mul_f32_e32 v157, 0x45800000, v151
	v_mul_f32_e32 v155, 0x4b800000, v177
	v_cndmask_b32_e64 v153, v174, v153, s[0:1]
	v_cmp_gt_f32_e64 s[6:7], s65, v177
	v_cndmask_b32_e32 v174, v151, v157, vcc
	v_mul_f32_e32 v151, 0x4b800000, v176
	v_cmp_gt_f32_e32 vcc, s65, v176
	v_cndmask_b32_e64 v155, v177, v155, s[6:7]
	v_rsq_f32_e32 v153, v153
	v_cndmask_b32_e32 v151, v176, v151, vcc
	s_waitcnt lgkmcnt(0)
	v_pk_add_f32 v[176:177], v[178:179], v[180:181]
	ds_bpermute_b32 v179, v149, v177
	ds_bpermute_b32 v178, v149, v176
	v_rsq_f32_e32 v155, v155
	v_mul_f32_e32 v159, 0x45800000, v153
	v_cndmask_b32_e64 v180, v153, v159, s[0:1]
	v_rsq_f32_e32 v151, v151
	s_waitcnt lgkmcnt(0)
	v_pk_add_f32 v[176:177], v[176:177], v[178:179]
	v_mul_f32_e32 v153, 0x45800000, v155
	v_pk_fma_f32 v[176:177], v[176:177], s[10:11], v[190:191] op_sel_hi:[1,0,0]
	v_cndmask_b32_e64 v170, v155, v153, s[6:7]
	v_mul_f32_e32 v155, 0x4b800000, v177
	v_cmp_gt_f32_e64 s[0:1], s65, v177
	v_mul_f32_e32 v157, 0x4b800000, v176
	v_cmp_gt_f32_e64 s[6:7], s65, v176
	v_cndmask_b32_e64 v155, v177, v155, s[0:1]
	v_rsq_f32_e32 v155, v155
	v_cndmask_b32_e64 v157, v176, v157, s[6:7]
	v_rsq_f32_e32 v157, v157
	v_mul_f32_e32 v153, 0x45800000, v151
	v_cndmask_b32_e32 v168, v151, v153, vcc
	v_mul_f32_e32 v151, 0x45800000, v155
	v_mov_b32_e32 v183, v198
	v_mov_b32_e32 v197, v199
	v_cndmask_b32_e64 v166, v155, v151, s[0:1]
	v_mul_f32_e32 v151, 0x45800000, v157
	v_mov_b32_e32 v176, v209
	v_mov_b32_e32 v177, v210
	v_mov_b32_e32 v209, v211
	v_pk_add_f32 v[182:183], v[182:183], v[196:197]
	v_cndmask_b32_e64 v162, v157, v151, s[6:7]
	v_pk_add_f32 v[176:177], v[176:177], v[208:209]
	v_mov_b32_e32 v178, v182
	v_mov_b32_e32 v179, v176
	v_mov_b32_e32 v176, v183
	v_pk_add_f32 v[176:177], v[178:179], v[176:177]
	ds_bpermute_b32 v178, v147, v176
	ds_bpermute_b32 v179, v147, v177
	v_lshl_or_b32 v182, s66, 8, v167
	v_pk_mul_f32 v[100:101], v[100:101], v[174:175] op_sel_hi:[1,0]
	v_pk_mul_f32 v[108:109], v[108:109], v[174:175] op_sel_hi:[1,0]
	v_ashrrev_i32_e32 v183, 31, v182
	s_waitcnt lgkmcnt(0)
	v_pk_add_f32 v[176:177], v[176:177], v[178:179]
	ds_bpermute_b32 v178, v149, v176
	ds_bpermute_b32 v179, v149, v177
	v_pk_mul_f32 v[96:97], v[96:97], v[174:175] op_sel_hi:[1,0]
	v_pk_mul_f32 v[102:103], v[102:103], v[174:175] op_sel_hi:[1,0]
	v_pk_mul_f32 v[110:111], v[110:111], v[174:175] op_sel_hi:[1,0]
	v_cvt_pk_bf16_f32 v108, v108, v109
	s_waitcnt lgkmcnt(0)
	v_pk_add_f32 v[176:177], v[176:177], v[178:179]
	v_pk_mul_f32 v[106:107], v[106:107], v[174:175] op_sel_hi:[1,0]
	v_pk_fma_f32 v[176:177], v[176:177], s[10:11], v[190:191] op_sel_hi:[1,0,0]
	v_pk_mul_f32 v[104:105], v[104:105], v[174:175] op_sel_hi:[1,0]
	v_mul_f32_e32 v147, 0x4b800000, v177
	v_cmp_gt_f32_e32 vcc, s65, v177
	v_mul_f32_e32 v149, 0x4b800000, v176
	v_cmp_gt_f32_e64 s[0:1], s65, v176
	v_cndmask_b32_e32 v147, v177, v147, vcc
	v_rsq_f32_e32 v147, v147
	v_cndmask_b32_e64 v149, v176, v149, s[0:1]
	v_rsq_f32_e32 v149, v149
	v_cvt_pk_bf16_f32 v100, v100, v101
	v_mul_f32_e32 v151, 0x45800000, v147
	v_cndmask_b32_e32 v160, v147, v151, vcc
	v_mul_f32_e32 v147, 0x45800000, v149
	v_cndmask_b32_e64 v176, v149, v147, s[0:1]
	v_pk_mul_f32 v[112:113], v[112:113], v[176:177] op_sel_hi:[1,0]
	v_pk_mul_f32 v[116:117], v[116:117], v[176:177] op_sel_hi:[1,0]
	v_pk_mul_f32 v[124:125], v[124:125], v[176:177] op_sel_hi:[1,0]
	v_pk_mul_f32 v[122:123], v[122:123], v[176:177] op_sel_hi:[1,0]
	v_pk_mul_f32 v[120:121], v[120:121], v[176:177] op_sel_hi:[1,0]
	v_pk_mul_f32 v[114:115], v[114:115], v[176:177] op_sel_hi:[1,0]
	v_pk_mul_f32 v[118:119], v[118:119], v[176:177] op_sel_hi:[1,0]
	v_pk_mul_f32 v[126:127], v[126:127], v[176:177] op_sel_hi:[1,0]
	v_cvt_pk_bf16_f32 v124, v124, v125
	v_cvt_pk_bf16_f32 v120, v120, v121
	v_cvt_pk_bf16_f32 v121, v122, v123
	v_cvt_pk_bf16_f32 v122, v116, v117
	v_cvt_pk_bf16_f32 v112, v112, v113
	v_cvt_pk_bf16_f32 v125, v126, v127
	v_cvt_pk_bf16_f32 v118, v118, v119
	v_cvt_pk_bf16_f32 v113, v114, v115
	v_cndmask_b32_e64 v114, v124, v122, s[2:3]
	v_mov_b32_e32 v123, 0
	v_cndmask_b32_e64 v115, v120, v112, s[2:3]
	v_mov_b32_e32 v126, 0
	v_mov_b32_dpp v123, v114 row_ror:8 row_mask:0xf bank_mask:0xf
	v_cndmask_b32_e64 v114, v125, v118, s[2:3]
	v_mov_b32_e32 v119, 0
	v_mov_b32_dpp v126, v115 row_ror:8 row_mask:0xf bank_mask:0xf
	v_mov_b32_e32 v127, 0
	v_mov_b32_dpp v119, v114 row_ror:8 row_mask:0xf bank_mask:0xf
	v_cndmask_b32_e64 v114, v121, v113, s[2:3]
	v_cndmask_b32_e64 v116, v126, v120, s[2:3]
	v_cndmask_b32_e64 v120, v112, v126, s[2:3]
	v_add_u32_e32 v112, -8, v146
	v_mov_b32_dpp v127, v114 row_ror:8 row_mask:0xf bank_mask:0xf
	v_cndmask_b32_e64 v112, v112, v146, s[2:3]
	v_cndmask_b32_e64 v117, v127, v121, s[2:3]
	v_cndmask_b32_e64 v121, v113, v127, s[2:3]
	v_ashrrev_i32_e32 v113, 31, v112
	v_lshlrev_b64 v[112:113], 10, v[112:113]
	v_cndmask_b32_e64 v115, v119, v125, s[2:3]
	v_cndmask_b32_e64 v114, v123, v124, s[2:3]
	v_cndmask_b32_e64 v119, v118, v119, s[2:3]
	v_cndmask_b32_e64 v118, v122, v123, s[2:3]
	v_lshl_add_u64 v[122:123], s[38:39], 0, v[112:113]
	v_lshlrev_b64 v[112:113], 1, v[182:183]
	v_pk_mul_f32 v[98:99], v[98:99], v[174:175] op_sel_hi:[1,0]
	v_cvt_pk_bf16_f32 v109, v110, v111
	v_cvt_pk_bf16_f32 v104, v104, v105
	v_cvt_pk_bf16_f32 v105, v106, v107
	v_cvt_pk_bf16_f32 v101, v102, v103
	v_cvt_pk_bf16_f32 v102, v96, v97
	v_cndmask_b32_e64 v96, v108, v100, s[2:3]
	v_mov_b32_e32 v106, 0
	v_lshl_add_u64 v[122:123], v[122:123], 0, v[112:113]
	v_cvt_pk_bf16_f32 v103, v98, v99
	v_mov_b32_dpp v106, v96 row_ror:8 row_mask:0xf bank_mask:0xf
	v_cndmask_b32_e64 v96, v109, v101, s[2:3]
	v_mov_b32_e32 v107, 0
	v_cndmask_b32_e64 v97, v104, v102, s[2:3]
	v_mov_b32_e32 v110, 0
	global_store_dwordx4 v[122:123], v[114:117], off
	v_mov_b32_dpp v107, v96 row_ror:8 row_mask:0xf bank_mask:0xf
	v_cndmask_b32_e64 v96, v105, v103, s[2:3]
	v_add_u32_e32 v116, 8, v146
	v_mov_b32_dpp v110, v97 row_ror:8 row_mask:0xf bank_mask:0xf
	v_mov_b32_e32 v111, 0
	v_cndmask_b32_e64 v114, v146, v116, s[2:3]
	v_cndmask_b32_e64 v98, v110, v104, s[2:3]
	v_mov_b32_dpp v111, v96 row_ror:8 row_mask:0xf bank_mask:0xf
	v_cndmask_b32_e64 v104, v116, v164, s[2:3]
	v_ashrrev_i32_e32 v115, 31, v114
	v_cndmask_b32_e64 v99, v111, v105, s[2:3]
	v_ashrrev_i32_e32 v105, 31, v104
	v_pk_mul_f32 v[84:85], v[84:85], v[180:181] op_sel_hi:[1,0]
	v_pk_mul_f32 v[92:93], v[92:93], v[180:181] op_sel_hi:[1,0]
	v_lshlrev_b64 v[114:115], 10, v[114:115]
	v_lshlrev_b64 v[104:105], 10, v[104:105]
	v_pk_mul_f32 v[80:81], v[80:81], v[180:181] op_sel_hi:[1,0]
	v_pk_mul_f32 v[86:87], v[86:87], v[180:181] op_sel_hi:[1,0]
	v_pk_mul_f32 v[94:95], v[94:95], v[180:181] op_sel_hi:[1,0]
	v_cvt_pk_bf16_f32 v92, v92, v93
	v_pk_mul_f32 v[90:91], v[90:91], v[180:181] op_sel_hi:[1,0]
	v_pk_mul_f32 v[88:89], v[88:89], v[180:181] op_sel_hi:[1,0]
	v_cvt_pk_bf16_f32 v84, v84, v85
	v_lshl_add_u64 v[114:115], s[38:39], 0, v[114:115]
	v_lshl_add_u64 v[104:105], s[38:39], 0, v[104:105]
	v_pk_mul_f32 v[82:83], v[82:83], v[180:181] op_sel_hi:[1,0]
	v_cvt_pk_bf16_f32 v93, v94, v95
	v_cvt_pk_bf16_f32 v88, v88, v89
	v_cvt_pk_bf16_f32 v89, v90, v91
	v_cvt_pk_bf16_f32 v85, v86, v87
	v_cvt_pk_bf16_f32 v86, v80, v81
	v_cndmask_b32_e64 v80, v92, v84, s[2:3]
	v_mov_b32_e32 v90, 0
	v_lshl_add_u64 v[114:115], v[114:115], 0, v[112:113]
	v_cndmask_b32_e64 v97, v107, v109, s[2:3]
	v_cndmask_b32_e64 v96, v106, v108, s[2:3]
	v_lshl_add_u64 v[104:105], v[104:105], 0, v[112:113]
	v_cvt_pk_bf16_f32 v87, v82, v83
	v_mov_b32_dpp v90, v80 row_ror:8 row_mask:0xf bank_mask:0xf
	v_cndmask_b32_e64 v80, v93, v85, s[2:3]
	v_mov_b32_e32 v91, 0
	v_cndmask_b32_e64 v81, v88, v86, s[2:3]
	v_mov_b32_e32 v94, 0
	global_store_dwordx4 v[114:115], v[118:121], off
	global_store_dwordx4 v[104:105], v[96:99], off
	v_mov_b32_dpp v91, v80 row_ror:8 row_mask:0xf bank_mask:0xf
	v_cndmask_b32_e64 v80, v89, v87, s[2:3]
	v_add_u32_e32 v98, 24, v146
	v_mov_b32_dpp v94, v81 row_ror:8 row_mask:0xf bank_mask:0xf
	v_mov_b32_e32 v95, 0
	v_cndmask_b32_e64 v96, v164, v98, s[2:3]
	v_cndmask_b32_e64 v82, v94, v88, s[2:3]
	v_mov_b32_dpp v95, v80 row_ror:8 row_mask:0xf bank_mask:0xf
	v_cndmask_b32_e64 v88, v98, v158, s[2:3]
	v_ashrrev_i32_e32 v97, 31, v96
	v_cndmask_b32_e64 v83, v95, v89, s[2:3]
	v_ashrrev_i32_e32 v89, 31, v88
	v_pk_mul_f32 v[68:69], v[68:69], v[170:171] op_sel_hi:[1,0]
	v_pk_mul_f32 v[76:77], v[76:77], v[170:171] op_sel_hi:[1,0]
	v_lshlrev_b64 v[96:97], 10, v[96:97]
	v_lshlrev_b64 v[88:89], 10, v[88:89]
	v_pk_mul_f32 v[64:65], v[64:65], v[170:171] op_sel_hi:[1,0]
	v_pk_mul_f32 v[70:71], v[70:71], v[170:171] op_sel_hi:[1,0]
	v_pk_mul_f32 v[78:79], v[78:79], v[170:171] op_sel_hi:[1,0]
	v_cvt_pk_bf16_f32 v76, v76, v77
	v_pk_mul_f32 v[74:75], v[74:75], v[170:171] op_sel_hi:[1,0]
	v_pk_mul_f32 v[72:73], v[72:73], v[170:171] op_sel_hi:[1,0]
	v_cvt_pk_bf16_f32 v68, v68, v69
	v_lshl_add_u64 v[96:97], s[38:39], 0, v[96:97]
	v_lshl_add_u64 v[88:89], s[38:39], 0, v[88:89]
	v_pk_mul_f32 v[66:67], v[66:67], v[170:171] op_sel_hi:[1,0]
	v_cvt_pk_bf16_f32 v77, v78, v79
	v_cvt_pk_bf16_f32 v72, v72, v73
	v_cvt_pk_bf16_f32 v73, v74, v75
	v_cvt_pk_bf16_f32 v69, v70, v71
	v_cvt_pk_bf16_f32 v70, v64, v65
	v_cndmask_b32_e64 v64, v76, v68, s[2:3]
	v_mov_b32_e32 v74, 0
	v_cndmask_b32_e64 v103, v103, v111, s[2:3]
	v_cndmask_b32_e64 v102, v102, v110, s[2:3]
	v_cndmask_b32_e64 v101, v101, v107, s[2:3]
	v_cndmask_b32_e64 v100, v100, v106, s[2:3]
	v_lshl_add_u64 v[96:97], v[96:97], 0, v[112:113]
	v_cndmask_b32_e64 v81, v91, v93, s[2:3]
	v_cndmask_b32_e64 v80, v90, v92, s[2:3]
	v_lshl_add_u64 v[88:89], v[88:89], 0, v[112:113]
	v_cvt_pk_bf16_f32 v71, v66, v67
	v_mov_b32_dpp v74, v64 row_ror:8 row_mask:0xf bank_mask:0xf
	v_cndmask_b32_e64 v64, v77, v69, s[2:3]
	v_mov_b32_e32 v75, 0
	v_cndmask_b32_e64 v65, v72, v70, s[2:3]
	v_mov_b32_e32 v78, 0
	global_store_dwordx4 v[96:97], v[100:103], off
	global_store_dwordx4 v[88:89], v[80:83], off
	v_mov_b32_dpp v75, v64 row_ror:8 row_mask:0xf bank_mask:0xf
	v_cndmask_b32_e64 v64, v73, v71, s[2:3]
	v_add_u32_e32 v82, 40, v146
	v_mov_b32_dpp v78, v65 row_ror:8 row_mask:0xf bank_mask:0xf
	v_mov_b32_e32 v79, 0
	v_cndmask_b32_e64 v80, v158, v82, s[2:3]
	v_cndmask_b32_e64 v66, v78, v72, s[2:3]
	v_mov_b32_dpp v79, v64 row_ror:8 row_mask:0xf bank_mask:0xf
	v_cndmask_b32_e64 v72, v82, v156, s[2:3]
	v_ashrrev_i32_e32 v81, 31, v80
	v_cndmask_b32_e64 v67, v79, v73, s[2:3]
	v_ashrrev_i32_e32 v73, 31, v72
	v_pk_mul_f32 v[48:49], v[48:49], v[168:169] op_sel_hi:[1,0]
	v_pk_mul_f32 v[54:55], v[54:55], v[168:169] op_sel_hi:[1,0]
	v_pk_mul_f32 v[52:53], v[52:53], v[168:169] op_sel_hi:[1,0]
	v_pk_mul_f32 v[60:61], v[60:61], v[168:169] op_sel_hi:[1,0]
	v_pk_mul_f32 v[56:57], v[56:57], v[168:169] op_sel_hi:[1,0]
	v_lshlrev_b64 v[80:81], 10, v[80:81]
	v_lshlrev_b64 v[72:73], 10, v[72:73]
	v_pk_mul_f32 v[62:63], v[62:63], v[168:169] op_sel_hi:[1,0]
	v_cvt_pk_bf16_f32 v60, v60, v61
	v_pk_mul_f32 v[58:59], v[58:59], v[168:169] op_sel_hi:[1,0]
	v_cvt_pk_bf16_f32 v56, v56, v57
	v_cvt_pk_bf16_f32 v52, v52, v53
	v_cvt_pk_bf16_f32 v53, v54, v55
	v_cvt_pk_bf16_f32 v54, v48, v49
	v_lshl_add_u64 v[80:81], s[38:39], 0, v[80:81]
	v_lshl_add_u64 v[72:73], s[38:39], 0, v[72:73]
	v_pk_mul_f32 v[50:51], v[50:51], v[168:169] op_sel_hi:[1,0]
	v_cvt_pk_bf16_f32 v61, v62, v63
	v_cvt_pk_bf16_f32 v57, v58, v59
	v_cndmask_b32_e64 v48, v60, v52, s[2:3]
	v_mov_b32_e32 v58, 0
	v_cndmask_b32_e64 v49, v56, v54, s[2:3]
	v_mov_b32_e32 v62, 0
	v_cndmask_b32_e64 v87, v87, v95, s[2:3]
	v_cndmask_b32_e64 v86, v86, v94, s[2:3]
	v_cndmask_b32_e64 v85, v85, v91, s[2:3]
	v_cndmask_b32_e64 v84, v84, v90, s[2:3]
	v_lshl_add_u64 v[80:81], v[80:81], 0, v[112:113]
	v_cndmask_b32_e64 v65, v75, v77, s[2:3]
	v_cndmask_b32_e64 v64, v74, v76, s[2:3]
	v_lshl_add_u64 v[72:73], v[72:73], 0, v[112:113]
	v_cvt_pk_bf16_f32 v55, v50, v51
	v_mov_b32_dpp v58, v48 row_ror:8 row_mask:0xf bank_mask:0xf
	v_cndmask_b32_e64 v48, v61, v53, s[2:3]
	v_mov_b32_e32 v59, 0
	v_mov_b32_dpp v62, v49 row_ror:8 row_mask:0xf bank_mask:0xf
	global_store_dwordx4 v[80:81], v[84:87], off
	global_store_dwordx4 v[72:73], v[64:67], off
	v_mov_b32_dpp v59, v48 row_ror:8 row_mask:0xf bank_mask:0xf
	v_cndmask_b32_e64 v48, v57, v55, s[2:3]
	v_add_u32_e32 v64, 56, v146
	v_mov_b32_e32 v63, 0
	v_cndmask_b32_e64 v50, v62, v56, s[2:3]
	v_add_u32_e32 v56, 0x78, v146
	v_cndmask_b32_e64 v64, v156, v64, s[2:3]
	v_mov_b32_dpp v63, v48 row_ror:8 row_mask:0xf bank_mask:0xf
	v_cndmask_b32_e64 v56, v56, v154, s[2:3]
	v_ashrrev_i32_e32 v65, 31, v64
	v_cndmask_b32_e64 v51, v63, v57, s[2:3]
	v_ashrrev_i32_e32 v57, 31, v56
	v_pk_mul_f32 v[36:37], v[36:37], v[166:167] op_sel_hi:[1,0]
	v_pk_mul_f32 v[44:45], v[44:45], v[166:167] op_sel_hi:[1,0]
	v_lshlrev_b64 v[64:65], 10, v[64:65]
	v_lshlrev_b64 v[56:57], 10, v[56:57]
	v_pk_mul_f32 v[32:33], v[32:33], v[166:167] op_sel_hi:[1,0]
	v_pk_mul_f32 v[38:39], v[38:39], v[166:167] op_sel_hi:[1,0]
	v_pk_mul_f32 v[46:47], v[46:47], v[166:167] op_sel_hi:[1,0]
	v_cvt_pk_bf16_f32 v44, v44, v45
	v_pk_mul_f32 v[42:43], v[42:43], v[166:167] op_sel_hi:[1,0]
	v_pk_mul_f32 v[40:41], v[40:41], v[166:167] op_sel_hi:[1,0]
	v_cvt_pk_bf16_f32 v36, v36, v37
	v_lshl_add_u64 v[64:65], s[38:39], 0, v[64:65]
	v_lshl_add_u64 v[56:57], s[38:39], 0, v[56:57]
	v_pk_mul_f32 v[34:35], v[34:35], v[166:167] op_sel_hi:[1,0]
	v_cvt_pk_bf16_f32 v45, v46, v47
	v_cvt_pk_bf16_f32 v40, v40, v41
	v_cvt_pk_bf16_f32 v41, v42, v43
	v_cvt_pk_bf16_f32 v37, v38, v39
	v_cvt_pk_bf16_f32 v38, v32, v33
	v_cndmask_b32_e64 v32, v44, v36, s[2:3]
	v_mov_b32_e32 v42, 0
	v_cndmask_b32_e64 v71, v71, v79, s[2:3]
	v_cndmask_b32_e64 v70, v70, v78, s[2:3]
	v_cndmask_b32_e64 v69, v69, v75, s[2:3]
	v_cndmask_b32_e64 v68, v68, v74, s[2:3]
	v_lshl_add_u64 v[64:65], v[64:65], 0, v[112:113]
	v_cndmask_b32_e64 v49, v59, v61, s[2:3]
	v_cndmask_b32_e64 v48, v58, v60, s[2:3]
	v_lshl_add_u64 v[56:57], v[56:57], 0, v[112:113]
	v_cvt_pk_bf16_f32 v39, v34, v35
	v_mov_b32_dpp v42, v32 row_ror:8 row_mask:0xf bank_mask:0xf
	v_cndmask_b32_e64 v32, v45, v37, s[2:3]
	v_mov_b32_e32 v43, 0
	v_cndmask_b32_e64 v33, v40, v38, s[2:3]
	v_mov_b32_e32 v46, 0
	global_store_dwordx4 v[64:65], v[68:71], off
	global_store_dwordx4 v[56:57], v[48:51], off
	v_mov_b32_dpp v43, v32 row_ror:8 row_mask:0xf bank_mask:0xf
	v_cndmask_b32_e64 v32, v41, v39, s[2:3]
	v_add_u32_e32 v50, 0x88, v146
	v_mov_b32_dpp v46, v33 row_ror:8 row_mask:0xf bank_mask:0xf
	v_mov_b32_e32 v47, 0
	v_cndmask_b32_e64 v34, v46, v40, s[2:3]
	v_cndmask_b32_e64 v40, v50, v152, s[2:3]
	v_mov_b32_dpp v47, v32 row_ror:8 row_mask:0xf bank_mask:0xf
	v_cndmask_b32_e64 v35, v47, v41, s[2:3]
	v_ashrrev_i32_e32 v41, 31, v40
	v_pk_mul_f32 v[20:21], v[20:21], v[162:163] op_sel_hi:[1,0]
	v_pk_mul_f32 v[28:29], v[28:29], v[162:163] op_sel_hi:[1,0]
	v_lshlrev_b64 v[40:41], 10, v[40:41]
	v_pk_mul_f32 v[16:17], v[16:17], v[162:163] op_sel_hi:[1,0]
	v_pk_mul_f32 v[22:23], v[22:23], v[162:163] op_sel_hi:[1,0]
	v_pk_mul_f32 v[30:31], v[30:31], v[162:163] op_sel_hi:[1,0]
	v_cvt_pk_bf16_f32 v28, v28, v29
	v_pk_mul_f32 v[26:27], v[26:27], v[162:163] op_sel_hi:[1,0]
	v_pk_mul_f32 v[24:25], v[24:25], v[162:163] op_sel_hi:[1,0]
	v_cvt_pk_bf16_f32 v20, v20, v21
	v_lshl_add_u64 v[40:41], s[38:39], 0, v[40:41]
	v_pk_mul_f32 v[18:19], v[18:19], v[162:163] op_sel_hi:[1,0]
	v_cvt_pk_bf16_f32 v29, v30, v31
	v_cvt_pk_bf16_f32 v24, v24, v25
	v_cvt_pk_bf16_f32 v25, v26, v27
	v_cvt_pk_bf16_f32 v21, v22, v23
	v_cvt_pk_bf16_f32 v22, v16, v17
	v_cndmask_b32_e64 v16, v28, v20, s[2:3]
	v_mov_b32_e32 v26, 0
	v_cndmask_b32_e64 v33, v43, v45, s[2:3]
	v_cndmask_b32_e64 v32, v42, v44, s[2:3]
	v_lshl_add_u64 v[40:41], v[40:41], 0, v[112:113]
	v_cvt_pk_bf16_f32 v23, v18, v19
	v_mov_b32_dpp v26, v16 row_ror:8 row_mask:0xf bank_mask:0xf
	v_cndmask_b32_e64 v16, v29, v21, s[2:3]
	v_mov_b32_e32 v27, 0
	v_cndmask_b32_e64 v17, v24, v22, s[2:3]
	v_mov_b32_e32 v30, 0
	global_store_dwordx4 v[40:41], v[32:35], off
	v_mov_b32_dpp v27, v16 row_ror:8 row_mask:0xf bank_mask:0xf
	v_cndmask_b32_e64 v16, v25, v23, s[2:3]
	v_add_u32_e32 v34, 0x98, v146
	v_mov_b32_dpp v30, v17 row_ror:8 row_mask:0xf bank_mask:0xf
	v_mov_b32_e32 v31, 0
	v_cndmask_b32_e64 v18, v30, v24, s[2:3]
	v_cndmask_b32_e64 v24, v34, v148, s[2:3]
	v_mov_b32_dpp v31, v16 row_ror:8 row_mask:0xf bank_mask:0xf
	v_cndmask_b32_e64 v19, v31, v25, s[2:3]
	v_ashrrev_i32_e32 v25, 31, v24
	v_lshlrev_b64 v[24:25], 10, v[24:25]
	v_lshl_add_u64 v[24:25], s[38:39], 0, v[24:25]
	v_cndmask_b32_e64 v17, v27, v29, s[2:3]
	v_cndmask_b32_e64 v16, v26, v28, s[2:3]
	v_lshl_add_u64 v[24:25], v[24:25], 0, v[112:113]
	global_store_dwordx4 v[24:25], v[16:19], off
	v_pk_mul_f32 v[4:5], v[4:5], v[160:161] op_sel_hi:[1,0]
	v_pk_mul_f32 v[12:13], v[12:13], v[160:161] op_sel_hi:[1,0]
	v_add_u32_e32 v18, 0xa8, v146
	v_cndmask_b32_e64 v16, v148, v18, s[2:3]
	v_ashrrev_i32_e32 v17, 31, v16
	v_pk_mul_f32 v[10:11], v[10:11], v[160:161] op_sel_hi:[1,0]
	v_pk_mul_f32 v[8:9], v[8:9], v[160:161] op_sel_hi:[1,0]
	v_lshlrev_b64 v[16:17], 10, v[16:17]
	v_pk_mul_f32 v[0:1], v[0:1], v[160:161] op_sel_hi:[1,0]
	v_pk_mul_f32 v[6:7], v[6:7], v[160:161] op_sel_hi:[1,0]
	v_pk_mul_f32 v[14:15], v[14:15], v[160:161] op_sel_hi:[1,0]
	v_cvt_pk_bf16_f32 v12, v12, v13
	v_cvt_pk_bf16_f32 v8, v8, v9
	v_cvt_pk_bf16_f32 v9, v10, v11
	v_cvt_pk_bf16_f32 v10, v4, v5
	v_lshl_add_u64 v[16:17], s[38:39], 0, v[16:17]
	v_pk_mul_f32 v[2:3], v[2:3], v[160:161] op_sel_hi:[1,0]
	v_cvt_pk_bf16_f32 v13, v14, v15
	v_cvt_pk_bf16_f32 v6, v6, v7
	v_cvt_pk_bf16_f32 v7, v0, v1
	v_cndmask_b32_e64 v0, v12, v10, s[2:3]
	v_mov_b32_e32 v14, 0
	v_cndmask_b32_e64 v4, v18, v150, s[2:3]
	v_cndmask_b32_e64 v23, v23, v31, s[2:3]
	v_cndmask_b32_e64 v22, v22, v30, s[2:3]
	v_cndmask_b32_e64 v21, v21, v27, s[2:3]
	v_cndmask_b32_e64 v20, v20, v26, s[2:3]
	v_lshl_add_u64 v[16:17], v[16:17], 0, v[112:113]
	v_cvt_pk_bf16_f32 v11, v2, v3
	v_mov_b32_dpp v14, v0 row_ror:8 row_mask:0xf bank_mask:0xf
	v_cndmask_b32_e64 v0, v13, v6, s[2:3]
	v_mov_b32_e32 v15, 0
	v_ashrrev_i32_e32 v5, 31, v4
	global_store_dwordx4 v[16:17], v[20:23], off
	v_mov_b32_dpp v15, v0 row_ror:8 row_mask:0xf bank_mask:0xf
	v_cndmask_b32_e64 v0, v9, v11, s[2:3]
	v_cndmask_b32_e64 v1, v8, v7, s[2:3]
	v_mov_b32_e32 v16, 0
	v_mov_b32_e32 v17, 0
	v_lshlrev_b64 v[4:5], 10, v[4:5]
	v_mov_b32_dpp v16, v1 row_ror:8 row_mask:0xf bank_mask:0xf
	v_mov_b32_dpp v17, v0 row_ror:8 row_mask:0xf bank_mask:0xf
	v_lshl_add_u64 v[4:5], s[38:39], 0, v[4:5]
	v_cndmask_b32_e64 v3, v17, v9, s[2:3]
	v_cndmask_b32_e64 v2, v16, v8, s[2:3]
	v_cndmask_b32_e64 v1, v15, v13, s[2:3]
	v_cndmask_b32_e64 v0, v14, v12, s[2:3]
	v_lshl_add_u64 v[4:5], v[4:5], 0, v[112:113]
	global_store_dwordx4 v[4:5], v[0:3], off
	v_cndmask_b32_e64 v48, v154, v50, s[2:3]
	v_cndmask_b32_e64 v32, v152, v34, s[2:3]
	v_add_u32_e32 v0, 0xb8, v146
	v_cndmask_b32_e64 v0, v150, v0, s[2:3]
	v_ashrrev_i32_e32 v49, 31, v48
	v_ashrrev_i32_e32 v33, 31, v32
	v_ashrrev_i32_e32 v1, 31, v0
	v_lshlrev_b64 v[48:49], 10, v[48:49]
	v_lshlrev_b64 v[32:33], 10, v[32:33]
	v_lshlrev_b64 v[0:1], 10, v[0:1]
	v_lshl_add_u64 v[48:49], s[38:39], 0, v[48:49]
	v_lshl_add_u64 v[32:33], s[38:39], 0, v[32:33]
	v_lshl_add_u64 v[0:1], s[38:39], 0, v[0:1]
	v_cndmask_b32_e64 v55, v55, v63, s[2:3]
	v_cndmask_b32_e64 v54, v54, v62, s[2:3]
	v_cndmask_b32_e64 v53, v53, v59, s[2:3]
	v_cndmask_b32_e64 v52, v52, v58, s[2:3]
	v_lshl_add_u64 v[48:49], v[48:49], 0, v[112:113]
	v_cndmask_b32_e64 v39, v39, v47, s[2:3]
	v_cndmask_b32_e64 v38, v38, v46, s[2:3]
	v_cndmask_b32_e64 v37, v37, v43, s[2:3]
	v_cndmask_b32_e64 v36, v36, v42, s[2:3]
	v_lshl_add_u64 v[32:33], v[32:33], 0, v[112:113]
	v_lshl_add_u64 v[4:5], v[0:1], 0, v[112:113]
	v_cndmask_b32_e64 v3, v11, v17, s[2:3]
	v_cndmask_b32_e64 v2, v7, v16, s[2:3]
	v_cndmask_b32_e64 v1, v6, v15, s[2:3]
	v_cndmask_b32_e64 v0, v10, v14, s[2:3]
	s_and_b64 vcc, exec, s[4:5]
	s_mov_b32 s66, s36
	s_mov_b32 s6, s44
	s_mov_b64 s[50:51], s[48:49]
	s_mov_b64 s[52:53], s[46:47]
	global_store_dwordx4 v[48:49], v[52:55], off
	global_store_dwordx4 v[32:33], v[36:39], off
	global_store_dwordx4 v[4:5], v[0:3], off
	s_cbranch_vccz .LBB0_897
	s_waitcnt vmcnt(0)
	s_cmpk_gt_u32 s11, 0xff
	s_cbranch_scc1 .LBB0_908
	s_barrier

.LBB0_997:
	ds_read_b128 v[128:131], v164
	ds_read_b128 v[132:135], v164 offset:1024
	ds_read_b128 v[152:155], v164 offset:2048
	ds_read_b128 v[156:159], v164 offset:3072
	s_add_u32 s28, s48, 0xfffe0080
	s_addc_u32 s29, s49, -1
	s_cmp_eq_u32 s79, 4
	s_cselect_b32 s53, s9, s29
	s_cselect_b32 s52, s41, s28
	s_cselect_b32 s51, s39, s78
	s_cselect_b32 s50, s76, s77
	v_lshl_add_u64 v[204:205], s[48:49], 0, v[144:145]
	s_add_i32 m0, s55, 0xc000
	ds_read_b128 v[168:171], v165
	ds_read_b128 v[172:175], v165 offset:1024
	ds_read_b128 v[176:179], v165 offset:2048
	ds_read_b128 v[180:183], v165 offset:3072
	ds_read_b128 v[184:187], v165 offset:4096
	ds_read_b128 v[188:191], v165 offset:5120
	ds_read_b128 v[196:199], v165 offset:6144
	ds_read_b128 v[200:203], v165 offset:7168
	global_load_lds_dwordx4 v[204:205], off
	s_add_i32 m0, s55, 0xe000
	v_lshl_add_u64 v[204:205], s[48:49], 0, v[146:147]
	global_load_lds_dwordx4 v[204:205], off
	s_waitcnt lgkmcnt(8)
	s_barrier
	s_waitcnt lgkmcnt(0)
	s_waitcnt lgkmcnt(0)
	v_mfma_f32_16x16x32_bf16 v[124:127], v[128:131], v[168:171], v[124:127]
	v_mfma_f32_16x16x32_bf16 v[120:123], v[152:155], v[168:171], v[120:123]
	v_mfma_f32_16x16x32_bf16 v[108:111], v[128:131], v[176:179], v[108:111]
	v_mfma_f32_16x16x32_bf16 v[104:107], v[152:155], v[176:179], v[104:107]
	v_mfma_f32_16x16x32_bf16 v[92:95], v[128:131], v[184:187], v[92:95]
	v_mfma_f32_16x16x32_bf16 v[88:91], v[152:155], v[184:187], v[88:91]
	v_mfma_f32_16x16x32_bf16 v[76:79], v[128:131], v[196:199], v[76:79]
	v_mfma_f32_16x16x32_bf16 v[72:75], v[152:155], v[196:199], v[72:75]
	v_mfma_f32_16x16x32_bf16 v[124:127], v[132:135], v[172:175], v[124:127]
	v_mfma_f32_16x16x32_bf16 v[120:123], v[156:159], v[172:175], v[120:123]
	v_mfma_f32_16x16x32_bf16 v[108:111], v[132:135], v[180:183], v[108:111]
	v_mfma_f32_16x16x32_bf16 v[104:107], v[156:159], v[180:183], v[104:107]
	v_mfma_f32_16x16x32_bf16 v[92:95], v[132:135], v[188:191], v[92:95]
	v_mfma_f32_16x16x32_bf16 v[88:91], v[156:159], v[188:191], v[88:91]
	v_mfma_f32_16x16x32_bf16 v[76:79], v[132:135], v[200:203], v[76:79]
	v_mfma_f32_16x16x32_bf16 v[72:75], v[156:159], v[200:203], v[72:75]
	s_barrier
	s_add_i32 s28, s65, s54
	v_lshl_add_u64 v[220:221], s[50:51], 0, v[138:139]
	s_mov_b32 m0, s28
	ds_read_b128 v[204:207], v166
	ds_read_b128 v[208:211], v166 offset:1024
	ds_read_b128 v[212:215], v166 offset:2048
	ds_read_b128 v[216:219], v166 offset:3072
	global_load_lds_dwordx4 v[220:221], off
	s_add_i32 m0, s28, 0x2000
	v_lshl_add_u64 v[222:223], s[50:51], 0, v[142:143]
	global_load_lds_dwordx4 v[222:223], off
	s_barrier
	s_waitcnt lgkmcnt(0)
	s_waitcnt lgkmcnt(0)
	v_mfma_f32_16x16x32_bf16 v[116:119], v[204:207], v[168:171], v[116:119]
	v_mfma_f32_16x16x32_bf16 v[112:115], v[212:215], v[168:171], v[112:115]
	v_mfma_f32_16x16x32_bf16 v[100:103], v[204:207], v[176:179], v[100:103]
	v_mfma_f32_16x16x32_bf16 v[96:99], v[212:215], v[176:179], v[96:99]
	v_mfma_f32_16x16x32_bf16 v[84:87], v[204:207], v[184:187], v[84:87]
	v_mfma_f32_16x16x32_bf16 v[80:83], v[212:215], v[184:187], v[80:83]
	v_mfma_f32_16x16x32_bf16 v[68:71], v[204:207], v[196:199], v[68:71]
	v_mfma_f32_16x16x32_bf16 v[64:67], v[212:215], v[196:199], v[64:67]
	v_mfma_f32_16x16x32_bf16 v[116:119], v[208:211], v[172:175], v[116:119]
	v_mfma_f32_16x16x32_bf16 v[112:115], v[216:219], v[172:175], v[112:115]
	v_mfma_f32_16x16x32_bf16 v[100:103], v[208:211], v[180:183], v[100:103]
	v_mfma_f32_16x16x32_bf16 v[96:99], v[216:219], v[180:183], v[96:99]
	v_mfma_f32_16x16x32_bf16 v[84:87], v[208:211], v[188:191], v[84:87]
	v_mfma_f32_16x16x32_bf16 v[80:83], v[216:219], v[188:191], v[80:83]
	v_mfma_f32_16x16x32_bf16 v[68:71], v[208:211], v[200:203], v[68:71]
	v_mfma_f32_16x16x32_bf16 v[64:67], v[216:219], v[200:203], v[64:67]
	s_mov_b32 m0, s55
	v_lshl_add_u64 v[224:225], s[52:53], 0, v[136:137]
	s_barrier
	ds_read_b128 v[168:171], v165 offset:16384
	ds_read_b128 v[172:175], v165 offset:17408
	ds_read_b128 v[176:179], v165 offset:18432
	ds_read_b128 v[180:183], v165 offset:19456
	ds_read_b128 v[184:187], v165 offset:20480
	ds_read_b128 v[188:191], v165 offset:21504
	ds_read_b128 v[196:199], v165 offset:22528
	ds_read_b128 v[200:203], v165 offset:23552
	global_load_lds_dwordx4 v[224:225], off
	s_mov_b32 m0, s56
	v_lshl_add_u64 v[226:227], s[52:53], 0, v[140:141]
	global_load_lds_dwordx4 v[226:227], off
	s_barrier
	s_waitcnt lgkmcnt(0)
	s_waitcnt lgkmcnt(0)
	v_mfma_f32_16x16x32_bf16 v[60:63], v[128:131], v[168:171], v[60:63]
	v_mfma_f32_16x16x32_bf16 v[56:59], v[152:155], v[168:171], v[56:59]
	v_mfma_f32_16x16x32_bf16 v[44:47], v[128:131], v[176:179], v[44:47]
	v_mfma_f32_16x16x32_bf16 v[40:43], v[152:155], v[176:179], v[40:43]
	v_mfma_f32_16x16x32_bf16 v[28:31], v[128:131], v[184:187], v[28:31]
	v_mfma_f32_16x16x32_bf16 v[24:27], v[152:155], v[184:187], v[24:27]
	v_mfma_f32_16x16x32_bf16 v[12:15], v[128:131], v[196:199], v[12:15]
	v_mfma_f32_16x16x32_bf16 v[8:11], v[152:155], v[196:199], v[8:11]
	v_mfma_f32_16x16x32_bf16 v[60:63], v[132:135], v[172:175], v[60:63]
	v_mfma_f32_16x16x32_bf16 v[56:59], v[156:159], v[172:175], v[56:59]
	v_mfma_f32_16x16x32_bf16 v[44:47], v[132:135], v[180:183], v[44:47]
	v_mfma_f32_16x16x32_bf16 v[40:43], v[156:159], v[180:183], v[40:43]
	v_mfma_f32_16x16x32_bf16 v[28:31], v[132:135], v[188:191], v[28:31]
	v_mfma_f32_16x16x32_bf16 v[24:27], v[156:159], v[188:191], v[24:27]
	v_mfma_f32_16x16x32_bf16 v[12:15], v[132:135], v[200:203], v[12:15]
	v_mfma_f32_16x16x32_bf16 v[8:11], v[156:159], v[200:203], v[8:11]
	s_barrier
	s_add_u32 s80, s50, 0x8000
	s_addc_u32 s81, s51, 0
	s_add_i32 s28, s66, s54
	s_mov_b32 m0, s28
	v_lshl_add_u64 v[128:129], s[80:81], 0, v[138:139]
	global_load_lds_dwordx4 v[128:129], off
	s_add_i32 m0, s28, 0x2000
	v_lshl_add_u64 v[128:129], s[80:81], 0, v[142:143]
	global_load_lds_dwordx4 v[128:129], off
	s_waitcnt vmcnt(6)
	s_barrier
	v_mfma_f32_16x16x32_bf16 v[52:55], v[204:207], v[168:171], v[52:55]
	v_mfma_f32_16x16x32_bf16 v[48:51], v[212:215], v[168:171], v[48:51]
	v_mfma_f32_16x16x32_bf16 v[36:39], v[204:207], v[176:179], v[36:39]
	v_mfma_f32_16x16x32_bf16 v[32:35], v[212:215], v[176:179], v[32:35]
	v_mfma_f32_16x16x32_bf16 v[20:23], v[204:207], v[184:187], v[20:23]
	v_mfma_f32_16x16x32_bf16 v[16:19], v[212:215], v[184:187], v[16:19]
	v_mfma_f32_16x16x32_bf16 v[4:7], v[204:207], v[196:199], v[4:7]
	v_mfma_f32_16x16x32_bf16 v[0:3], v[212:215], v[196:199], v[0:3]
	v_mfma_f32_16x16x32_bf16 v[52:55], v[208:211], v[172:175], v[52:55]
	v_mfma_f32_16x16x32_bf16 v[48:51], v[216:219], v[172:175], v[48:51]
	v_mfma_f32_16x16x32_bf16 v[36:39], v[208:211], v[180:183], v[36:39]
	v_mfma_f32_16x16x32_bf16 v[32:35], v[216:219], v[180:183], v[32:35]
	v_mfma_f32_16x16x32_bf16 v[20:23], v[208:211], v[188:191], v[20:23]
	v_mfma_f32_16x16x32_bf16 v[16:19], v[216:219], v[188:191], v[16:19]
	v_mfma_f32_16x16x32_bf16 v[4:7], v[208:211], v[200:203], v[4:7]
	v_mfma_f32_16x16x32_bf16 v[0:3], v[216:219], v[200:203], v[0:3]
	s_add_i32 s28, 0, 0x18000
	v_add_u32_e32 v156, s28, v161
	s_barrier
	ds_read_b128 v[128:131], v156
	ds_read_b128 v[132:135], v156 offset:1024
	ds_read_b128 v[152:155], v156 offset:2048
	ds_read_b128 v[156:159], v156 offset:3072
	s_add_u32 s52, s52, 0x20000
	s_addc_u32 s53, s53, 0
	s_mov_b32 m0, s57
	v_lshl_add_u64 v[204:205], s[52:53], 0, v[136:137]
	ds_read_b128 v[168:171], v165 offset:32768
	ds_read_b128 v[172:175], v165 offset:33792
	ds_read_b128 v[176:179], v165 offset:34816
	ds_read_b128 v[180:183], v165 offset:35840
	ds_read_b128 v[184:187], v165 offset:36864
	ds_read_b128 v[188:191], v165 offset:37888
	ds_read_b128 v[196:199], v165 offset:38912
	ds_read_b128 v[200:203], v165 offset:39936
	global_load_lds_dwordx4 v[204:205], off
	s_mov_b32 m0, s58
	v_lshl_add_u64 v[204:205], s[52:53], 0, v[140:141]
	global_load_lds_dwordx4 v[204:205], off
	s_waitcnt lgkmcnt(8)
	s_barrier
	s_waitcnt lgkmcnt(0)
	s_waitcnt lgkmcnt(0)
	v_mfma_f32_16x16x32_bf16 v[124:127], v[128:131], v[168:171], v[124:127]
	v_mfma_f32_16x16x32_bf16 v[120:123], v[152:155], v[168:171], v[120:123]
	v_mfma_f32_16x16x32_bf16 v[108:111], v[128:131], v[176:179], v[108:111]
	v_mfma_f32_16x16x32_bf16 v[104:107], v[152:155], v[176:179], v[104:107]
	v_mfma_f32_16x16x32_bf16 v[92:95], v[128:131], v[184:187], v[92:95]
	v_mfma_f32_16x16x32_bf16 v[88:91], v[152:155], v[184:187], v[88:91]
	v_mfma_f32_16x16x32_bf16 v[76:79], v[128:131], v[196:199], v[76:79]
	v_mfma_f32_16x16x32_bf16 v[72:75], v[152:155], v[196:199], v[72:75]
	v_mfma_f32_16x16x32_bf16 v[124:127], v[132:135], v[172:175], v[124:127]
	v_mfma_f32_16x16x32_bf16 v[120:123], v[156:159], v[172:175], v[120:123]
	v_mfma_f32_16x16x32_bf16 v[108:111], v[132:135], v[180:183], v[108:111]
	v_mfma_f32_16x16x32_bf16 v[104:107], v[156:159], v[180:183], v[104:107]
	v_mfma_f32_16x16x32_bf16 v[92:95], v[132:135], v[188:191], v[92:95]
	v_mfma_f32_16x16x32_bf16 v[88:91], v[156:159], v[188:191], v[88:91]
	v_mfma_f32_16x16x32_bf16 v[76:79], v[132:135], v[200:203], v[76:79]
	v_mfma_f32_16x16x32_bf16 v[72:75], v[156:159], v[200:203], v[72:75]
	s_barrier
	s_add_i32 s29, 0, 0x1c000
	s_add_i32 s28, s28, s54
	v_add_u32_e32 v195, s29, v161
	v_lshl_add_u64 v[220:221], v[220:221], 0, s[36:37]
	s_mov_b32 m0, s28
	ds_read_b128 v[204:207], v195
	ds_read_b128 v[208:211], v195 offset:1024
	ds_read_b128 v[212:215], v195 offset:2048
	ds_read_b128 v[216:219], v195 offset:3072
	global_load_lds_dwordx4 v[220:221], off
	s_add_i32 m0, s28, 0x2000
	v_lshl_add_u64 v[220:221], v[222:223], 0, s[36:37]
	global_load_lds_dwordx4 v[220:221], off
	s_barrier
	s_waitcnt lgkmcnt(0)
	s_waitcnt lgkmcnt(0)
	v_mfma_f32_16x16x32_bf16 v[116:119], v[204:207], v[168:171], v[116:119]
	v_mfma_f32_16x16x32_bf16 v[112:115], v[212:215], v[168:171], v[112:115]
	v_mfma_f32_16x16x32_bf16 v[100:103], v[204:207], v[176:179], v[100:103]
	v_mfma_f32_16x16x32_bf16 v[96:99], v[212:215], v[176:179], v[96:99]
	v_mfma_f32_16x16x32_bf16 v[84:87], v[204:207], v[184:187], v[84:87]
	v_mfma_f32_16x16x32_bf16 v[80:83], v[212:215], v[184:187], v[80:83]
	v_mfma_f32_16x16x32_bf16 v[68:71], v[204:207], v[196:199], v[68:71]
	v_mfma_f32_16x16x32_bf16 v[64:67], v[212:215], v[196:199], v[64:67]
	v_mfma_f32_16x16x32_bf16 v[116:119], v[208:211], v[172:175], v[116:119]
	v_mfma_f32_16x16x32_bf16 v[112:115], v[216:219], v[172:175], v[112:115]
	v_mfma_f32_16x16x32_bf16 v[100:103], v[208:211], v[180:183], v[100:103]
	v_mfma_f32_16x16x32_bf16 v[96:99], v[216:219], v[180:183], v[96:99]
	v_mfma_f32_16x16x32_bf16 v[84:87], v[208:211], v[188:191], v[84:87]
	v_mfma_f32_16x16x32_bf16 v[80:83], v[216:219], v[188:191], v[80:83]
	v_mfma_f32_16x16x32_bf16 v[68:71], v[208:211], v[200:203], v[68:71]
	v_mfma_f32_16x16x32_bf16 v[64:67], v[216:219], v[200:203], v[64:67]
	s_mov_b32 m0, s62
	v_lshl_add_u64 v[220:221], v[224:225], 0, s[36:37]
	s_barrier
	ds_read_b128 v[168:171], v165 offset:49152
	ds_read_b128 v[172:175], v165 offset:50176
	ds_read_b128 v[176:179], v165 offset:51200
	ds_read_b128 v[180:183], v165 offset:52224
	ds_read_b128 v[184:187], v165 offset:53248
	ds_read_b128 v[188:191], v165 offset:54272
	ds_read_b128 v[196:199], v165 offset:55296
	ds_read_b128 v[200:203], v165 offset:56320
	global_load_lds_dwordx4 v[220:221], off
	s_mov_b32 m0, s63
	v_lshl_add_u64 v[220:221], v[226:227], 0, s[36:37]
	global_load_lds_dwordx4 v[220:221], off
	s_barrier
	s_waitcnt lgkmcnt(0)
	s_waitcnt lgkmcnt(0)
	v_mfma_f32_16x16x32_bf16 v[60:63], v[128:131], v[168:171], v[60:63]
	v_mfma_f32_16x16x32_bf16 v[56:59], v[152:155], v[168:171], v[56:59]
	v_mfma_f32_16x16x32_bf16 v[44:47], v[128:131], v[176:179], v[44:47]
	v_mfma_f32_16x16x32_bf16 v[40:43], v[152:155], v[176:179], v[40:43]
	v_mfma_f32_16x16x32_bf16 v[28:31], v[128:131], v[184:187], v[28:31]
	v_mfma_f32_16x16x32_bf16 v[24:27], v[152:155], v[184:187], v[24:27]
	v_mfma_f32_16x16x32_bf16 v[12:15], v[128:131], v[196:199], v[12:15]
	v_mfma_f32_16x16x32_bf16 v[8:11], v[152:155], v[196:199], v[8:11]
	v_mfma_f32_16x16x32_bf16 v[60:63], v[132:135], v[172:175], v[60:63]
	v_mfma_f32_16x16x32_bf16 v[56:59], v[156:159], v[172:175], v[56:59]
	v_mfma_f32_16x16x32_bf16 v[44:47], v[132:135], v[180:183], v[44:47]
	v_mfma_f32_16x16x32_bf16 v[40:43], v[156:159], v[180:183], v[40:43]
	v_mfma_f32_16x16x32_bf16 v[28:31], v[132:135], v[188:191], v[28:31]
	v_mfma_f32_16x16x32_bf16 v[24:27], v[156:159], v[188:191], v[24:27]
	v_mfma_f32_16x16x32_bf16 v[12:15], v[132:135], v[200:203], v[12:15]
	v_mfma_f32_16x16x32_bf16 v[8:11], v[156:159], v[200:203], v[8:11]
	s_barrier
	s_add_u32 s50, s50, 0x8080
	s_addc_u32 s51, s51, 0
	s_add_i32 s28, s29, s54
	s_mov_b32 m0, s28
	v_lshl_add_u64 v[128:129], s[50:51], 0, v[138:139]
	global_load_lds_dwordx4 v[128:129], off
	s_add_i32 m0, s28, 0x2000
	v_lshl_add_u64 v[128:129], s[50:51], 0, v[142:143]
	global_load_lds_dwordx4 v[128:129], off
	s_waitcnt vmcnt(6)
	s_barrier
	v_mfma_f32_16x16x32_bf16 v[52:55], v[204:207], v[168:171], v[52:55]
	v_mfma_f32_16x16x32_bf16 v[48:51], v[212:215], v[168:171], v[48:51]
	v_mfma_f32_16x16x32_bf16 v[36:39], v[204:207], v[176:179], v[36:39]
	v_mfma_f32_16x16x32_bf16 v[32:35], v[212:215], v[176:179], v[32:35]
	v_mfma_f32_16x16x32_bf16 v[20:23], v[204:207], v[184:187], v[20:23]
	v_mfma_f32_16x16x32_bf16 v[16:19], v[212:215], v[184:187], v[16:19]
	v_mfma_f32_16x16x32_bf16 v[4:7], v[204:207], v[196:199], v[4:7]
	v_mfma_f32_16x16x32_bf16 v[0:3], v[212:215], v[196:199], v[0:3]
	v_mfma_f32_16x16x32_bf16 v[52:55], v[208:211], v[172:175], v[52:55]
	v_mfma_f32_16x16x32_bf16 v[48:51], v[216:219], v[172:175], v[48:51]
	v_mfma_f32_16x16x32_bf16 v[36:39], v[208:211], v[180:183], v[36:39]
	v_mfma_f32_16x16x32_bf16 v[32:35], v[216:219], v[180:183], v[32:35]
	v_mfma_f32_16x16x32_bf16 v[20:23], v[208:211], v[188:191], v[20:23]
	v_mfma_f32_16x16x32_bf16 v[16:19], v[216:219], v[188:191], v[16:19]
	v_mfma_f32_16x16x32_bf16 v[4:7], v[208:211], v[200:203], v[4:7]
	v_mfma_f32_16x16x32_bf16 v[0:3], v[216:219], v[200:203], v[0:3]
	s_add_i32 s79, s79, 2
	s_add_u32 s48, s48, 0x100
	s_addc_u32 s49, s49, 0
	s_add_u32 s77, s77, 0x100
	s_addc_u32 s78, s78, 0
	s_cmp_gt_u32 s79, 5
	s_barrier
	s_cbranch_scc0 .LBB0_997
	v_lshl_add_u32 v152, s8, 8, v160
	v_lshl_or_b32 v156, s10, 8, v162
	v_ashrrev_i32_e32 v153, 31, v152
	v_lshlrev_b64 v[128:129], 11, v[152:153]
	v_ashrrev_i32_e32 v157, 31, v156
	v_lshl_add_u64 v[128:129], s[42:43], 0, v[128:129]
	v_lshlrev_b64 v[130:131], 1, v[156:157]
	v_or_b32_e32 v158, 16, v152
	v_lshl_add_u64 v[128:129], v[128:129], 0, v[130:131]
	v_ashrrev_i32_e32 v159, 31, v158
	global_load_dwordx4 v[168:171], v[128:129], off
	global_load_dwordx4 v[172:175], v[128:129], off offset:64
	v_lshlrev_b64 v[128:129], 11, v[158:159]
	v_lshl_add_u64 v[128:129], s[42:43], 0, v[128:129]
	v_lshl_add_u64 v[128:129], v[128:129], 0, v[130:131]
	global_load_dwordx4 v[132:135], v[128:129], off
	s_nop 0
	global_load_dwordx4 v[128:131], v[128:129], off offset:64
	v_cndmask_b32_e64 v155, 0, 1, s[12:13]
	v_or_b32_e32 v154, v156, v163
	v_cmp_ne_u32_e64 s[8:9], 1, v155
	v_ashrrev_i32_e32 v155, 31, v154
	s_andn2_b64 vcc, exec, s[12:13]
	v_lshlrev_b64 v[154:155], 1, v[154:155]
	s_waitcnt vmcnt(0)
	v_lshlrev_b32_e32 v176, 16, v168
	v_and_b32_e32 v177, 0xffff0000, v168
	v_lshlrev_b32_e32 v168, 16, v169
	v_and_b32_e32 v169, 0xffff0000, v169
	v_lshlrev_b32_e32 v178, 16, v170
	v_and_b32_e32 v179, 0xffff0000, v170
	v_lshlrev_b32_e32 v170, 16, v171
	v_and_b32_e32 v171, 0xffff0000, v171
	v_lshlrev_b32_e32 v180, 16, v172
	v_and_b32_e32 v181, 0xffff0000, v172
	v_lshlrev_b32_e32 v172, 16, v173
	v_and_b32_e32 v173, 0xffff0000, v173
	v_lshlrev_b32_e32 v182, 16, v174
	v_and_b32_e32 v183, 0xffff0000, v174
	v_lshlrev_b32_e32 v174, 16, v175
	v_and_b32_e32 v175, 0xffff0000, v175
	v_pk_add_f32 v[126:127], v[126:127], v[168:169]
	v_pk_add_f32 v[124:125], v[124:125], v[176:177]
	v_pk_add_f32 v[122:123], v[122:123], v[170:171]
	v_pk_add_f32 v[120:121], v[120:121], v[178:179]
	v_pk_add_f32 v[118:119], v[118:119], v[172:173]
	v_pk_add_f32 v[116:117], v[116:117], v[180:181]
	v_pk_add_f32 v[114:115], v[114:115], v[174:175]
	v_pk_add_f32 v[112:113], v[112:113], v[182:183]
	v_add_u32_e32 v169, 8, v152
	s_cbranch_vccnz .LBB0_1000
	v_cvt_pk_bf16_f32 v168, v124, v125
	v_cvt_pk_bf16_f32 v174, v116, v117
	v_cvt_pk_bf16_f32 v170, v126, v127
	v_cvt_pk_bf16_f32 v171, v120, v121
	v_cvt_pk_bf16_f32 v175, v118, v119
	v_cvt_pk_bf16_f32 v176, v112, v113
	v_cndmask_b32_e64 v173, v168, v174, s[4:5]
	v_mov_b32_e32 v178, 0
	v_cvt_pk_bf16_f32 v172, v122, v123
	v_cvt_pk_bf16_f32 v177, v114, v115
	v_mov_b32_dpp v178, v173 row_ror:8 row_mask:0xf bank_mask:0xf
	v_cndmask_b32_e64 v173, v170, v175, s[4:5]
	v_mov_b32_e32 v179, 0
	v_cndmask_b32_e64 v180, v171, v176, s[4:5]
	v_mov_b32_e32 v181, 0
	v_mov_b32_dpp v179, v173 row_ror:8 row_mask:0xf bank_mask:0xf
	v_cndmask_b32_e64 v173, v172, v177, s[4:5]
	v_mov_b32_dpp v181, v180 row_ror:8 row_mask:0xf bank_mask:0xf
	v_mov_b32_e32 v180, 0
	v_cndmask_b32_e64 v174, v174, v178, s[4:5]
	v_cndmask_b32_e64 v175, v175, v179, s[4:5]
	v_mov_b32_dpp v180, v173 row_ror:8 row_mask:0xf bank_mask:0xf
	v_cndmask_b32_e64 v173, v180, v172, s[4:5]
	v_cndmask_b32_e64 v172, v181, v171, s[4:5]
	v_cndmask_b32_e64 v171, v179, v170, s[4:5]
	v_cndmask_b32_e64 v170, v178, v168, s[4:5]
	v_add_u32_e32 v168, -8, v152
	v_cndmask_b32_e64 v178, v168, v152, s[4:5]
	v_ashrrev_i32_e32 v179, 31, v178
	v_lshlrev_b64 v[178:179], 11, v[178:179]
	v_lshl_add_u64 v[178:179], s[68:69], 0, v[178:179]
	v_lshl_add_u64 v[178:179], v[178:179], 0, v[154:155]
	global_store_dwordx4 v[178:179], v[170:173], off
	v_cndmask_b32_e64 v177, v177, v180, s[4:5]
	v_cndmask_b32_e64 v176, v176, v181, s[4:5]
	v_cndmask_b32_e64 v170, v152, v169, s[4:5]
	v_ashrrev_i32_e32 v171, 31, v170
	v_lshlrev_b64 v[170:171], 11, v[170:171]
	v_lshl_add_u64 v[170:171], s[68:69], 0, v[170:171]
	v_lshl_add_u64 v[170:171], v[170:171], 0, v[154:155]
	global_store_dwordx4 v[170:171], v[174:177], off

.LBB0_1093:
	ds_read_b128 v[146:149], v167
	ds_read_b128 v[150:153], v167 offset:1024
	ds_read_b128 v[178:181], v167 offset:2048
	ds_read_b128 v[182:185], v167 offset:3072
	s_add_u32 s28, s0, 0xfffc0080
	s_addc_u32 s29, s1, -1
	s_cmp_eq_u32 s64, 12
	s_cselect_b32 s45, s37, s29
	s_cselect_b32 s44, s60, s28
	s_cselect_b32 s43, s13, s63
	s_cselect_b32 s42, s61, s62
	v_lshl_add_u64 v[156:157], s[0:1], 0, v[138:139]
	s_add_i32 m0, s47, 0xc000
	ds_read_b128 v[186:189], v171
	ds_read_b128 v[196:199], v171 offset:1024
	ds_read_b128 v[200:203], v171 offset:2048
	ds_read_b128 v[204:207], v171 offset:3072
	ds_read_b128 v[208:211], v171 offset:4096
	ds_read_b128 v[212:215], v171 offset:5120
	ds_read_b128 v[216:219], v171 offset:6144
	ds_read_b128 v[220:223], v171 offset:7168
	global_load_lds_dwordx4 v[156:157], off
	s_add_i32 m0, s47, 0xe000
	v_lshl_add_u64 v[156:157], s[0:1], 0, v[140:141]
	global_load_lds_dwordx4 v[156:157], off
	s_waitcnt lgkmcnt(8)
	s_barrier
	s_waitcnt lgkmcnt(0)
	s_waitcnt lgkmcnt(0)
	s_cmp_eq_u32 s64, -2
	s_cbranch_scc1 .Lz10_0_first
	v_mfma_f32_16x16x32_bf16 v[124:127], v[146:149], v[186:189], v[124:127]
	v_mfma_f32_16x16x32_bf16 v[120:123], v[178:181], v[186:189], v[120:123]
	v_mfma_f32_16x16x32_bf16 v[108:111], v[146:149], v[200:203], v[108:111]
	v_mfma_f32_16x16x32_bf16 v[104:107], v[178:181], v[200:203], v[104:107]
	v_mfma_f32_16x16x32_bf16 v[92:95], v[146:149], v[208:211], v[92:95]
	v_mfma_f32_16x16x32_bf16 v[88:91], v[178:181], v[208:211], v[88:91]
	v_mfma_f32_16x16x32_bf16 v[76:79], v[146:149], v[216:219], v[76:79]
	v_mfma_f32_16x16x32_bf16 v[72:75], v[178:181], v[216:219], v[72:75]
	v_mfma_f32_16x16x32_bf16 v[124:127], v[150:153], v[196:199], v[124:127]
	v_mfma_f32_16x16x32_bf16 v[120:123], v[182:185], v[196:199], v[120:123]
	v_mfma_f32_16x16x32_bf16 v[108:111], v[150:153], v[204:207], v[108:111]
	v_mfma_f32_16x16x32_bf16 v[104:107], v[182:185], v[204:207], v[104:107]
	v_mfma_f32_16x16x32_bf16 v[92:95], v[150:153], v[212:215], v[92:95]
	v_mfma_f32_16x16x32_bf16 v[88:91], v[182:185], v[212:215], v[88:91]
	v_mfma_f32_16x16x32_bf16 v[76:79], v[150:153], v[220:223], v[76:79]
	v_mfma_f32_16x16x32_bf16 v[72:75], v[182:185], v[220:223], v[72:75]
.Lz10_0_join:
	s_barrier
	s_add_i32 s28, s56, s11
	v_lshl_add_u64 v[156:157], s[42:43], 0, v[132:133]
	s_mov_b32 m0, s28
	ds_read_b128 v[224:227], v175
	ds_read_b128 v[228:231], v175 offset:1024
	ds_read_b128 v[232:235], v175 offset:2048
	ds_read_b128 v[236:239], v175 offset:3072
	global_load_lds_dwordx4 v[156:157], off
	s_add_i32 m0, s28, 0x2000
	v_lshl_add_u64 v[160:161], s[42:43], 0, v[128:129]
	global_load_lds_dwordx4 v[160:161], off
	s_barrier
	s_waitcnt lgkmcnt(0)
	s_waitcnt lgkmcnt(0)
	s_cmp_eq_u32 s64, -2
	s_cbranch_scc1 .Lz10_1_first
	v_mfma_f32_16x16x32_bf16 v[116:119], v[224:227], v[186:189], v[116:119]
	v_mfma_f32_16x16x32_bf16 v[112:115], v[232:235], v[186:189], v[112:115]
	v_mfma_f32_16x16x32_bf16 v[100:103], v[224:227], v[200:203], v[100:103]
	v_mfma_f32_16x16x32_bf16 v[96:99], v[232:235], v[200:203], v[96:99]
	v_mfma_f32_16x16x32_bf16 v[84:87], v[224:227], v[208:211], v[84:87]
	v_mfma_f32_16x16x32_bf16 v[80:83], v[232:235], v[208:211], v[80:83]
	v_mfma_f32_16x16x32_bf16 v[68:71], v[224:227], v[216:219], v[68:71]
	v_mfma_f32_16x16x32_bf16 v[64:67], v[232:235], v[216:219], v[64:67]
	v_mfma_f32_16x16x32_bf16 v[116:119], v[228:231], v[196:199], v[116:119]
	v_mfma_f32_16x16x32_bf16 v[112:115], v[236:239], v[196:199], v[112:115]
	v_mfma_f32_16x16x32_bf16 v[100:103], v[228:231], v[204:207], v[100:103]
	v_mfma_f32_16x16x32_bf16 v[96:99], v[236:239], v[204:207], v[96:99]
	v_mfma_f32_16x16x32_bf16 v[84:87], v[228:231], v[212:215], v[84:87]
	v_mfma_f32_16x16x32_bf16 v[80:83], v[236:239], v[212:215], v[80:83]
	v_mfma_f32_16x16x32_bf16 v[68:71], v[228:231], v[220:223], v[68:71]
	v_mfma_f32_16x16x32_bf16 v[64:67], v[236:239], v[220:223], v[64:67]
.Lz10_1_join:
	s_mov_b32 m0, s47
	v_lshl_add_u64 v[164:165], s[44:45], 0, v[134:135]
	s_barrier
	ds_read_b128 v[186:189], v171 offset:16384
	ds_read_b128 v[196:199], v171 offset:17408
	ds_read_b128 v[200:203], v171 offset:18432
	ds_read_b128 v[204:207], v171 offset:19456
	ds_read_b128 v[208:211], v171 offset:20480
	ds_read_b128 v[212:215], v171 offset:21504
	ds_read_b128 v[216:219], v171 offset:22528
	ds_read_b128 v[220:223], v171 offset:23552
	global_load_lds_dwordx4 v[164:165], off
	s_mov_b32 m0, s48
	v_lshl_add_u64 v[168:169], s[44:45], 0, v[130:131]
	global_load_lds_dwordx4 v[168:169], off
	s_barrier
	s_waitcnt lgkmcnt(0)
	s_waitcnt lgkmcnt(0)
	s_cmp_eq_u32 s64, -2
	s_cbranch_scc1 .Lz10_2_first
	v_mfma_f32_16x16x32_bf16 v[60:63], v[146:149], v[186:189], v[60:63]
	v_mfma_f32_16x16x32_bf16 v[56:59], v[178:181], v[186:189], v[56:59]
	v_mfma_f32_16x16x32_bf16 v[44:47], v[146:149], v[200:203], v[44:47]
	v_mfma_f32_16x16x32_bf16 v[40:43], v[178:181], v[200:203], v[40:43]
	v_mfma_f32_16x16x32_bf16 v[28:31], v[146:149], v[208:211], v[28:31]
	v_mfma_f32_16x16x32_bf16 v[24:27], v[178:181], v[208:211], v[24:27]
	v_mfma_f32_16x16x32_bf16 v[12:15], v[146:149], v[216:219], v[12:15]
	v_mfma_f32_16x16x32_bf16 v[8:11], v[178:181], v[216:219], v[8:11]
	v_mfma_f32_16x16x32_bf16 v[60:63], v[150:153], v[196:199], v[60:63]
	v_mfma_f32_16x16x32_bf16 v[56:59], v[182:185], v[196:199], v[56:59]
	v_mfma_f32_16x16x32_bf16 v[44:47], v[150:153], v[204:207], v[44:47]
	v_mfma_f32_16x16x32_bf16 v[40:43], v[182:185], v[204:207], v[40:43]
	v_mfma_f32_16x16x32_bf16 v[28:31], v[150:153], v[212:215], v[28:31]
	v_mfma_f32_16x16x32_bf16 v[24:27], v[182:185], v[212:215], v[24:27]
	v_mfma_f32_16x16x32_bf16 v[12:15], v[150:153], v[220:223], v[12:15]
	v_mfma_f32_16x16x32_bf16 v[8:11], v[182:185], v[220:223], v[8:11]
.Lz10_2_join:
	s_barrier
	s_add_u32 s66, s42, 0x40000
	s_addc_u32 s67, s43, 0
	s_add_i32 s28, s57, s11
	s_mov_b32 m0, s28
	v_lshl_add_u64 v[146:147], s[66:67], 0, v[132:133]
	global_load_lds_dwordx4 v[146:147], off
	s_add_i32 m0, s28, 0x2000
	v_lshl_add_u64 v[146:147], s[66:67], 0, v[128:129]
	global_load_lds_dwordx4 v[146:147], off
	s_waitcnt vmcnt(6)
	s_barrier
	s_cmp_eq_u32 s64, -2
	s_cbranch_scc1 .Lz10_3_first
	v_mfma_f32_16x16x32_bf16 v[52:55], v[224:227], v[186:189], v[52:55]
	v_mfma_f32_16x16x32_bf16 v[48:51], v[232:235], v[186:189], v[48:51]
	v_mfma_f32_16x16x32_bf16 v[36:39], v[224:227], v[200:203], v[36:39]
	v_mfma_f32_16x16x32_bf16 v[32:35], v[232:235], v[200:203], v[32:35]
	v_mfma_f32_16x16x32_bf16 v[20:23], v[224:227], v[208:211], v[20:23]
	v_mfma_f32_16x16x32_bf16 v[16:19], v[232:235], v[208:211], v[16:19]
	v_mfma_f32_16x16x32_bf16 v[4:7], v[224:227], v[216:219], v[4:7]
	v_mfma_f32_16x16x32_bf16 v[0:3], v[232:235], v[216:219], v[0:3]
	v_mfma_f32_16x16x32_bf16 v[52:55], v[228:231], v[196:199], v[52:55]
	v_mfma_f32_16x16x32_bf16 v[48:51], v[236:239], v[196:199], v[48:51]
	v_mfma_f32_16x16x32_bf16 v[36:39], v[228:231], v[204:207], v[36:39]
	v_mfma_f32_16x16x32_bf16 v[32:35], v[236:239], v[204:207], v[32:35]
	v_mfma_f32_16x16x32_bf16 v[20:23], v[228:231], v[212:215], v[20:23]
	v_mfma_f32_16x16x32_bf16 v[16:19], v[236:239], v[212:215], v[16:19]
	v_mfma_f32_16x16x32_bf16 v[4:7], v[228:231], v[220:223], v[4:7]
	v_mfma_f32_16x16x32_bf16 v[0:3], v[236:239], v[220:223], v[0:3]
.Lz10_3_join:
	s_add_i32 s28, 0, 0x18000
	v_add_u32_e32 v154, s28, v159
	s_barrier
	ds_read_b128 v[146:149], v154
	ds_read_b128 v[150:153], v154 offset:1024
	ds_read_b128 v[178:181], v154 offset:2048
	ds_read_b128 v[182:185], v154 offset:3072
	s_add_u32 s44, s44, 0x40000
	s_addc_u32 s45, s45, 0
	s_mov_b32 m0, s49
	v_lshl_add_u64 v[172:173], s[44:45], 0, v[134:135]
	ds_read_b128 v[186:189], v171 offset:32768
	ds_read_b128 v[196:199], v171 offset:33792
	ds_read_b128 v[200:203], v171 offset:34816
	ds_read_b128 v[204:207], v171 offset:35840
	ds_read_b128 v[208:211], v171 offset:36864
	ds_read_b128 v[212:215], v171 offset:37888
	ds_read_b128 v[216:219], v171 offset:38912
	ds_read_b128 v[220:223], v171 offset:39936
	global_load_lds_dwordx4 v[172:173], off
	s_mov_b32 m0, s50
	v_lshl_add_u64 v[172:173], s[44:45], 0, v[130:131]
	global_load_lds_dwordx4 v[172:173], off
	s_waitcnt lgkmcnt(8)
	s_barrier
	s_waitcnt lgkmcnt(0)
	s_waitcnt lgkmcnt(0)
	v_mfma_f32_16x16x32_bf16 v[124:127], v[146:149], v[186:189], v[124:127]
	v_mfma_f32_16x16x32_bf16 v[120:123], v[178:181], v[186:189], v[120:123]
	v_mfma_f32_16x16x32_bf16 v[108:111], v[146:149], v[200:203], v[108:111]
	v_mfma_f32_16x16x32_bf16 v[104:107], v[178:181], v[200:203], v[104:107]
	v_mfma_f32_16x16x32_bf16 v[92:95], v[146:149], v[208:211], v[92:95]
	v_mfma_f32_16x16x32_bf16 v[88:91], v[178:181], v[208:211], v[88:91]
	v_mfma_f32_16x16x32_bf16 v[76:79], v[146:149], v[216:219], v[76:79]
	v_mfma_f32_16x16x32_bf16 v[72:75], v[178:181], v[216:219], v[72:75]
	v_mfma_f32_16x16x32_bf16 v[124:127], v[150:153], v[196:199], v[124:127]
	v_mfma_f32_16x16x32_bf16 v[120:123], v[182:185], v[196:199], v[120:123]
	v_mfma_f32_16x16x32_bf16 v[108:111], v[150:153], v[204:207], v[108:111]
	v_mfma_f32_16x16x32_bf16 v[104:107], v[182:185], v[204:207], v[104:107]
	v_mfma_f32_16x16x32_bf16 v[92:95], v[150:153], v[212:215], v[92:95]
	v_mfma_f32_16x16x32_bf16 v[88:91], v[182:185], v[212:215], v[88:91]
	v_mfma_f32_16x16x32_bf16 v[76:79], v[150:153], v[220:223], v[76:79]
	v_mfma_f32_16x16x32_bf16 v[72:75], v[182:185], v[220:223], v[72:75]
	s_barrier
	s_add_i32 s29, 0, 0x1c000
	s_add_i32 s28, s28, s11
	v_add_u32_e32 v154, s29, v159
	v_lshl_add_u64 v[156:157], v[156:157], 0, s[6:7]
	s_mov_b32 m0, s28
	ds_read_b128 v[224:227], v154
	ds_read_b128 v[228:231], v154 offset:1024
	ds_read_b128 v[232:235], v154 offset:2048
	ds_read_b128 v[236:239], v154 offset:3072
	global_load_lds_dwordx4 v[156:157], off
	s_add_i32 m0, s28, 0x2000
	v_lshl_add_u64 v[156:157], v[160:161], 0, s[6:7]
	global_load_lds_dwordx4 v[156:157], off
	s_barrier
	s_waitcnt lgkmcnt(0)
	s_waitcnt lgkmcnt(0)
	v_mfma_f32_16x16x32_bf16 v[116:119], v[224:227], v[186:189], v[116:119]
	v_mfma_f32_16x16x32_bf16 v[112:115], v[232:235], v[186:189], v[112:115]
	v_mfma_f32_16x16x32_bf16 v[100:103], v[224:227], v[200:203], v[100:103]
	v_mfma_f32_16x16x32_bf16 v[96:99], v[232:235], v[200:203], v[96:99]
	v_mfma_f32_16x16x32_bf16 v[84:87], v[224:227], v[208:211], v[84:87]
	v_mfma_f32_16x16x32_bf16 v[80:83], v[232:235], v[208:211], v[80:83]
	v_mfma_f32_16x16x32_bf16 v[68:71], v[224:227], v[216:219], v[68:71]
	v_mfma_f32_16x16x32_bf16 v[64:67], v[232:235], v[216:219], v[64:67]
	v_mfma_f32_16x16x32_bf16 v[116:119], v[228:231], v[196:199], v[116:119]
	v_mfma_f32_16x16x32_bf16 v[112:115], v[236:239], v[196:199], v[112:115]
	v_mfma_f32_16x16x32_bf16 v[100:103], v[228:231], v[204:207], v[100:103]
	v_mfma_f32_16x16x32_bf16 v[96:99], v[236:239], v[204:207], v[96:99]
	v_mfma_f32_16x16x32_bf16 v[84:87], v[228:231], v[212:215], v[84:87]
	v_mfma_f32_16x16x32_bf16 v[80:83], v[236:239], v[212:215], v[80:83]
	v_mfma_f32_16x16x32_bf16 v[68:71], v[228:231], v[220:223], v[68:71]
	v_mfma_f32_16x16x32_bf16 v[64:67], v[236:239], v[220:223], v[64:67]
	s_mov_b32 m0, s53
	v_lshl_add_u64 v[156:157], v[164:165], 0, s[6:7]
	s_barrier
	ds_read_b128 v[186:189], v171 offset:49152
	ds_read_b128 v[196:199], v171 offset:50176
	ds_read_b128 v[200:203], v171 offset:51200
	ds_read_b128 v[204:207], v171 offset:52224
	ds_read_b128 v[208:211], v171 offset:53248
	ds_read_b128 v[212:215], v171 offset:54272
	ds_read_b128 v[216:219], v171 offset:55296
	ds_read_b128 v[220:223], v171 offset:56320
	global_load_lds_dwordx4 v[156:157], off
	s_mov_b32 m0, s54
	v_lshl_add_u64 v[156:157], v[168:169], 0, s[6:7]
	global_load_lds_dwordx4 v[156:157], off
	s_barrier
	s_waitcnt lgkmcnt(0)
	s_waitcnt lgkmcnt(0)
	v_mfma_f32_16x16x32_bf16 v[60:63], v[146:149], v[186:189], v[60:63]
	v_mfma_f32_16x16x32_bf16 v[56:59], v[178:181], v[186:189], v[56:59]
	v_mfma_f32_16x16x32_bf16 v[44:47], v[146:149], v[200:203], v[44:47]
	v_mfma_f32_16x16x32_bf16 v[40:43], v[178:181], v[200:203], v[40:43]
	v_mfma_f32_16x16x32_bf16 v[28:31], v[146:149], v[208:211], v[28:31]
	v_mfma_f32_16x16x32_bf16 v[24:27], v[178:181], v[208:211], v[24:27]
	v_mfma_f32_16x16x32_bf16 v[12:15], v[146:149], v[216:219], v[12:15]
	v_mfma_f32_16x16x32_bf16 v[8:11], v[178:181], v[216:219], v[8:11]
	v_mfma_f32_16x16x32_bf16 v[60:63], v[150:153], v[196:199], v[60:63]
	v_mfma_f32_16x16x32_bf16 v[56:59], v[182:185], v[196:199], v[56:59]
	v_mfma_f32_16x16x32_bf16 v[44:47], v[150:153], v[204:207], v[44:47]
	v_mfma_f32_16x16x32_bf16 v[40:43], v[182:185], v[204:207], v[40:43]
	v_mfma_f32_16x16x32_bf16 v[28:31], v[150:153], v[212:215], v[28:31]
	v_mfma_f32_16x16x32_bf16 v[24:27], v[182:185], v[212:215], v[24:27]
	v_mfma_f32_16x16x32_bf16 v[12:15], v[150:153], v[220:223], v[12:15]
	v_mfma_f32_16x16x32_bf16 v[8:11], v[182:185], v[220:223], v[8:11]
	s_barrier
	s_add_u32 s42, s42, 0x40080
	s_addc_u32 s43, s43, 0
	s_add_i32 s28, s29, s11
	s_mov_b32 m0, s28
	v_lshl_add_u64 v[146:147], s[42:43], 0, v[132:133]
	global_load_lds_dwordx4 v[146:147], off
	s_add_i32 m0, s28, 0x2000
	v_lshl_add_u64 v[146:147], s[42:43], 0, v[128:129]
	global_load_lds_dwordx4 v[146:147], off
	s_waitcnt vmcnt(6)
	s_barrier
	v_mfma_f32_16x16x32_bf16 v[52:55], v[224:227], v[186:189], v[52:55]
	v_mfma_f32_16x16x32_bf16 v[48:51], v[232:235], v[186:189], v[48:51]
	v_mfma_f32_16x16x32_bf16 v[36:39], v[224:227], v[200:203], v[36:39]
	v_mfma_f32_16x16x32_bf16 v[32:35], v[232:235], v[200:203], v[32:35]
	v_mfma_f32_16x16x32_bf16 v[20:23], v[224:227], v[208:211], v[20:23]
	v_mfma_f32_16x16x32_bf16 v[16:19], v[232:235], v[208:211], v[16:19]
	v_mfma_f32_16x16x32_bf16 v[4:7], v[224:227], v[216:219], v[4:7]
	v_mfma_f32_16x16x32_bf16 v[0:3], v[232:235], v[216:219], v[0:3]
	v_mfma_f32_16x16x32_bf16 v[52:55], v[228:231], v[196:199], v[52:55]
	v_mfma_f32_16x16x32_bf16 v[48:51], v[236:239], v[196:199], v[48:51]
	v_mfma_f32_16x16x32_bf16 v[36:39], v[228:231], v[204:207], v[36:39]
	v_mfma_f32_16x16x32_bf16 v[32:35], v[236:239], v[204:207], v[32:35]
	v_mfma_f32_16x16x32_bf16 v[20:23], v[228:231], v[212:215], v[20:23]
	v_mfma_f32_16x16x32_bf16 v[16:19], v[236:239], v[212:215], v[16:19]
	v_mfma_f32_16x16x32_bf16 v[4:7], v[228:231], v[220:223], v[4:7]
	v_mfma_f32_16x16x32_bf16 v[0:3], v[236:239], v[220:223], v[0:3]
	s_add_i32 s64, s64, 2
	s_add_u32 s0, s0, 0x100
	s_addc_u32 s1, s1, 0
	s_add_u32 s62, s62, 0x100
	s_addc_u32 s63, s63, 0
	s_cmp_gt_u32 s64, 13
	s_barrier
	s_cbranch_scc0 .LBB0_1093
	s_branch .Lz10_skip

.LBB0_1169:
	ds_read_b128 v[128:131], v167
	ds_read_b128 v[132:135], v167 offset:1024
	ds_read_b128 v[136:139], v167 offset:2048
	ds_read_b128 v[156:159], v167 offset:3072
	s_add_u32 s6, s40, 0x100
	s_addc_u32 s7, s41, 0
	s_cmp_eq_u32 s65, 40
	s_cselect_b32 s45, s1, s7
	s_cselect_b32 s44, s0, s6
	s_cselect_b32 s43, s39, s64
	s_cselect_b32 s42, s38, s63
	v_lshl_add_u64 v[202:203], s[40:41], 0, v[148:149]
	s_add_i32 m0, s47, 0xc000
	ds_read_b128 v[160:163], v168
	ds_read_b128 v[172:175], v168 offset:1024
	ds_read_b128 v[176:179], v168 offset:2048
	ds_read_b128 v[180:183], v168 offset:3072
	ds_read_b128 v[184:187], v168 offset:4096
	ds_read_b128 v[188:191], v168 offset:5120
	ds_read_b128 v[194:197], v168 offset:6144
	ds_read_b128 v[198:201], v168 offset:7168
	global_load_lds_dwordx4 v[202:203], off
	s_add_i32 m0, s47, 0xe000
	v_lshl_add_u64 v[202:203], s[40:41], 0, v[150:151]
	global_load_lds_dwordx4 v[202:203], off
	s_waitcnt lgkmcnt(8)
	s_barrier
	s_waitcnt lgkmcnt(0)
	s_waitcnt lgkmcnt(0)
	v_mfma_f32_16x16x32_bf16 v[124:127], v[128:131], v[160:163], v[124:127]
	v_mfma_f32_16x16x32_bf16 v[120:123], v[136:139], v[160:163], v[120:123]
	v_mfma_f32_16x16x32_bf16 v[108:111], v[128:131], v[176:179], v[108:111]
	v_mfma_f32_16x16x32_bf16 v[104:107], v[136:139], v[176:179], v[104:107]
	v_mfma_f32_16x16x32_bf16 v[92:95], v[128:131], v[184:187], v[92:95]
	v_mfma_f32_16x16x32_bf16 v[88:91], v[136:139], v[184:187], v[88:91]
	v_mfma_f32_16x16x32_bf16 v[76:79], v[128:131], v[194:197], v[76:79]
	v_mfma_f32_16x16x32_bf16 v[72:75], v[136:139], v[194:197], v[72:75]
	v_mfma_f32_16x16x32_bf16 v[124:127], v[132:135], v[172:175], v[124:127]
	v_mfma_f32_16x16x32_bf16 v[120:123], v[156:159], v[172:175], v[120:123]
	v_mfma_f32_16x16x32_bf16 v[108:111], v[132:135], v[180:183], v[108:111]
	v_mfma_f32_16x16x32_bf16 v[104:107], v[156:159], v[180:183], v[104:107]
	v_mfma_f32_16x16x32_bf16 v[92:95], v[132:135], v[188:191], v[92:95]
	v_mfma_f32_16x16x32_bf16 v[88:91], v[156:159], v[188:191], v[88:91]
	v_mfma_f32_16x16x32_bf16 v[76:79], v[132:135], v[198:201], v[76:79]
	v_mfma_f32_16x16x32_bf16 v[72:75], v[156:159], v[198:201], v[72:75]
	s_barrier
	s_add_i32 s28, s57, s46
	v_lshl_add_u64 v[218:219], s[42:43], 0, v[142:143]
	s_mov_b32 m0, s28
	ds_read_b128 v[202:205], v169
	ds_read_b128 v[206:209], v169 offset:1024
	ds_read_b128 v[210:213], v169 offset:2048
	ds_read_b128 v[214:217], v169 offset:3072
	global_load_lds_dwordx4 v[218:219], off
	s_add_i32 m0, s28, 0x2000
	v_lshl_add_u64 v[220:221], s[42:43], 0, v[146:147]
	global_load_lds_dwordx4 v[220:221], off
	s_barrier
	s_waitcnt lgkmcnt(0)
	s_waitcnt lgkmcnt(0)
	v_mfma_f32_16x16x32_bf16 v[116:119], v[202:205], v[160:163], v[116:119]
	v_mfma_f32_16x16x32_bf16 v[112:115], v[210:213], v[160:163], v[112:115]
	v_mfma_f32_16x16x32_bf16 v[100:103], v[202:205], v[176:179], v[100:103]
	v_mfma_f32_16x16x32_bf16 v[96:99], v[210:213], v[176:179], v[96:99]
	v_mfma_f32_16x16x32_bf16 v[84:87], v[202:205], v[184:187], v[84:87]
	v_mfma_f32_16x16x32_bf16 v[80:83], v[210:213], v[184:187], v[80:83]
	v_mfma_f32_16x16x32_bf16 v[68:71], v[202:205], v[194:197], v[68:71]
	v_mfma_f32_16x16x32_bf16 v[64:67], v[210:213], v[194:197], v[64:67]
	v_mfma_f32_16x16x32_bf16 v[116:119], v[206:209], v[172:175], v[116:119]
	v_mfma_f32_16x16x32_bf16 v[112:115], v[214:217], v[172:175], v[112:115]
	v_mfma_f32_16x16x32_bf16 v[100:103], v[206:209], v[180:183], v[100:103]
	v_mfma_f32_16x16x32_bf16 v[96:99], v[214:217], v[180:183], v[96:99]
	v_mfma_f32_16x16x32_bf16 v[84:87], v[206:209], v[188:191], v[84:87]
	v_mfma_f32_16x16x32_bf16 v[80:83], v[214:217], v[188:191], v[80:83]
	v_mfma_f32_16x16x32_bf16 v[68:71], v[206:209], v[198:201], v[68:71]
	v_mfma_f32_16x16x32_bf16 v[64:67], v[214:217], v[198:201], v[64:67]
	s_mov_b32 m0, s47
	v_lshl_add_u64 v[222:223], s[44:45], 0, v[140:141]
	s_barrier
	ds_read_b128 v[160:163], v168 offset:16384
	ds_read_b128 v[172:175], v168 offset:17408
	ds_read_b128 v[176:179], v168 offset:18432
	ds_read_b128 v[180:183], v168 offset:19456
	ds_read_b128 v[184:187], v168 offset:20480
	ds_read_b128 v[188:191], v168 offset:21504
	ds_read_b128 v[194:197], v168 offset:22528
	ds_read_b128 v[198:201], v168 offset:23552
	global_load_lds_dwordx4 v[222:223], off
	s_mov_b32 m0, s48
	v_lshl_add_u64 v[224:225], s[44:45], 0, v[144:145]
	global_load_lds_dwordx4 v[224:225], off
	s_barrier
	s_waitcnt lgkmcnt(0)
	s_waitcnt lgkmcnt(0)
	v_mfma_f32_16x16x32_bf16 v[60:63], v[128:131], v[160:163], v[60:63]
	v_mfma_f32_16x16x32_bf16 v[56:59], v[136:139], v[160:163], v[56:59]
	v_mfma_f32_16x16x32_bf16 v[44:47], v[128:131], v[176:179], v[44:47]
	v_mfma_f32_16x16x32_bf16 v[40:43], v[136:139], v[176:179], v[40:43]
	v_mfma_f32_16x16x32_bf16 v[28:31], v[128:131], v[184:187], v[28:31]
	v_mfma_f32_16x16x32_bf16 v[24:27], v[136:139], v[184:187], v[24:27]
	v_mfma_f32_16x16x32_bf16 v[12:15], v[128:131], v[194:197], v[12:15]
	v_mfma_f32_16x16x32_bf16 v[8:11], v[136:139], v[194:197], v[8:11]
	v_mfma_f32_16x16x32_bf16 v[60:63], v[132:135], v[172:175], v[60:63]
	v_mfma_f32_16x16x32_bf16 v[56:59], v[156:159], v[172:175], v[56:59]
	v_mfma_f32_16x16x32_bf16 v[44:47], v[132:135], v[180:183], v[44:47]
	v_mfma_f32_16x16x32_bf16 v[40:43], v[156:159], v[180:183], v[40:43]
	v_mfma_f32_16x16x32_bf16 v[28:31], v[132:135], v[188:191], v[28:31]
	v_mfma_f32_16x16x32_bf16 v[24:27], v[156:159], v[188:191], v[24:27]
	v_mfma_f32_16x16x32_bf16 v[12:15], v[132:135], v[198:201], v[12:15]
	v_mfma_f32_16x16x32_bf16 v[8:11], v[156:159], v[198:201], v[8:11]
	s_barrier
	s_add_u32 s40, s42, 0x2c000
	s_addc_u32 s41, s43, 0
	s_add_i32 s28, s58, s46
	s_mov_b32 m0, s28
	v_lshl_add_u64 v[128:129], s[40:41], 0, v[142:143]
	global_load_lds_dwordx4 v[128:129], off
	s_add_i32 m0, s28, 0x2000
	v_lshl_add_u64 v[128:129], s[40:41], 0, v[146:147]
	global_load_lds_dwordx4 v[128:129], off
	s_waitcnt vmcnt(6)
	s_barrier
	v_mfma_f32_16x16x32_bf16 v[52:55], v[202:205], v[160:163], v[52:55]
	v_mfma_f32_16x16x32_bf16 v[48:51], v[210:213], v[160:163], v[48:51]
	v_mfma_f32_16x16x32_bf16 v[36:39], v[202:205], v[176:179], v[36:39]
	v_mfma_f32_16x16x32_bf16 v[32:35], v[210:213], v[176:179], v[32:35]
	v_mfma_f32_16x16x32_bf16 v[20:23], v[202:205], v[184:187], v[20:23]
	v_mfma_f32_16x16x32_bf16 v[16:19], v[210:213], v[184:187], v[16:19]
	v_mfma_f32_16x16x32_bf16 v[4:7], v[202:205], v[194:197], v[4:7]
	v_mfma_f32_16x16x32_bf16 v[0:3], v[210:213], v[194:197], v[0:3]
	v_mfma_f32_16x16x32_bf16 v[52:55], v[206:209], v[172:175], v[52:55]
	v_mfma_f32_16x16x32_bf16 v[48:51], v[214:217], v[172:175], v[48:51]
	v_mfma_f32_16x16x32_bf16 v[36:39], v[206:209], v[180:183], v[36:39]
	v_mfma_f32_16x16x32_bf16 v[32:35], v[214:217], v[180:183], v[32:35]
	v_mfma_f32_16x16x32_bf16 v[20:23], v[206:209], v[188:191], v[20:23]
	v_mfma_f32_16x16x32_bf16 v[16:19], v[214:217], v[188:191], v[16:19]
	v_mfma_f32_16x16x32_bf16 v[4:7], v[206:209], v[198:201], v[4:7]
	v_mfma_f32_16x16x32_bf16 v[0:3], v[214:217], v[198:201], v[0:3]
	s_add_i32 s28, 0, 0x18000
	v_add_u32_e32 v156, s28, v165
	s_barrier
	ds_read_b128 v[128:131], v156
	ds_read_b128 v[132:135], v156 offset:1024
	ds_read_b128 v[136:139], v156 offset:2048
	ds_read_b128 v[156:159], v156 offset:3072
	s_add_u32 s40, s44, 0xb0000
	s_addc_u32 s41, s45, 0
	s_mov_b32 m0, s49
	v_lshl_add_u64 v[202:203], s[40:41], 0, v[140:141]
	ds_read_b128 v[160:163], v168 offset:32768
	ds_read_b128 v[172:175], v168 offset:33792
	ds_read_b128 v[176:179], v168 offset:34816
	ds_read_b128 v[180:183], v168 offset:35840
	ds_read_b128 v[184:187], v168 offset:36864
	ds_read_b128 v[188:191], v168 offset:37888
	ds_read_b128 v[194:197], v168 offset:38912
	ds_read_b128 v[198:201], v168 offset:39936
	global_load_lds_dwordx4 v[202:203], off
	s_mov_b32 m0, s50
	v_lshl_add_u64 v[202:203], s[40:41], 0, v[144:145]
	global_load_lds_dwordx4 v[202:203], off
	s_waitcnt lgkmcnt(8)
	s_barrier
	s_waitcnt lgkmcnt(0)
	s_waitcnt lgkmcnt(0)
	v_mfma_f32_16x16x32_bf16 v[124:127], v[128:131], v[160:163], v[124:127]
	v_mfma_f32_16x16x32_bf16 v[120:123], v[136:139], v[160:163], v[120:123]
	v_mfma_f32_16x16x32_bf16 v[108:111], v[128:131], v[176:179], v[108:111]
	v_mfma_f32_16x16x32_bf16 v[104:107], v[136:139], v[176:179], v[104:107]
	v_mfma_f32_16x16x32_bf16 v[92:95], v[128:131], v[184:187], v[92:95]
	v_mfma_f32_16x16x32_bf16 v[88:91], v[136:139], v[184:187], v[88:91]
	v_mfma_f32_16x16x32_bf16 v[76:79], v[128:131], v[194:197], v[76:79]
	v_mfma_f32_16x16x32_bf16 v[72:75], v[136:139], v[194:197], v[72:75]
	v_mfma_f32_16x16x32_bf16 v[124:127], v[132:135], v[172:175], v[124:127]
	v_mfma_f32_16x16x32_bf16 v[120:123], v[156:159], v[172:175], v[120:123]
	v_mfma_f32_16x16x32_bf16 v[108:111], v[132:135], v[180:183], v[108:111]
	v_mfma_f32_16x16x32_bf16 v[104:107], v[156:159], v[180:183], v[104:107]
	v_mfma_f32_16x16x32_bf16 v[92:95], v[132:135], v[188:191], v[92:95]
	v_mfma_f32_16x16x32_bf16 v[88:91], v[156:159], v[188:191], v[88:91]
	v_mfma_f32_16x16x32_bf16 v[76:79], v[132:135], v[198:201], v[76:79]
	v_mfma_f32_16x16x32_bf16 v[72:75], v[156:159], v[198:201], v[72:75]
	s_barrier
	s_add_i32 s29, 0, 0x1c000
	s_add_i32 s28, s28, s46
	v_add_u32_e32 v171, s29, v165
	v_lshl_add_u64 v[218:219], v[218:219], 0, s[36:37]
	s_mov_b32 m0, s28
	ds_read_b128 v[202:205], v171
	ds_read_b128 v[206:209], v171 offset:1024
	ds_read_b128 v[210:213], v171 offset:2048
	ds_read_b128 v[214:217], v171 offset:3072
	global_load_lds_dwordx4 v[218:219], off
	s_add_i32 m0, s28, 0x2000
	v_lshl_add_u64 v[218:219], v[220:221], 0, s[36:37]
	global_load_lds_dwordx4 v[218:219], off
	s_barrier
	s_waitcnt lgkmcnt(0)
	s_waitcnt lgkmcnt(0)
	v_mfma_f32_16x16x32_bf16 v[116:119], v[202:205], v[160:163], v[116:119]
	v_mfma_f32_16x16x32_bf16 v[112:115], v[210:213], v[160:163], v[112:115]
	v_mfma_f32_16x16x32_bf16 v[100:103], v[202:205], v[176:179], v[100:103]
	v_mfma_f32_16x16x32_bf16 v[96:99], v[210:213], v[176:179], v[96:99]
	v_mfma_f32_16x16x32_bf16 v[84:87], v[202:205], v[184:187], v[84:87]
	v_mfma_f32_16x16x32_bf16 v[80:83], v[210:213], v[184:187], v[80:83]
	v_mfma_f32_16x16x32_bf16 v[68:71], v[202:205], v[194:197], v[68:71]
	v_mfma_f32_16x16x32_bf16 v[64:67], v[210:213], v[194:197], v[64:67]
	v_mfma_f32_16x16x32_bf16 v[116:119], v[206:209], v[172:175], v[116:119]
	v_mfma_f32_16x16x32_bf16 v[112:115], v[214:217], v[172:175], v[112:115]
	v_mfma_f32_16x16x32_bf16 v[100:103], v[206:209], v[180:183], v[100:103]
	v_mfma_f32_16x16x32_bf16 v[96:99], v[214:217], v[180:183], v[96:99]
	v_mfma_f32_16x16x32_bf16 v[84:87], v[206:209], v[188:191], v[84:87]
	v_mfma_f32_16x16x32_bf16 v[80:83], v[214:217], v[188:191], v[80:83]
	v_mfma_f32_16x16x32_bf16 v[68:71], v[206:209], v[198:201], v[68:71]
	v_mfma_f32_16x16x32_bf16 v[64:67], v[214:217], v[198:201], v[64:67]
	s_mov_b32 m0, s54
	v_lshl_add_u64 v[218:219], v[222:223], 0, s[36:37]
	s_barrier
	ds_read_b128 v[160:163], v168 offset:49152
	ds_read_b128 v[172:175], v168 offset:50176
	ds_read_b128 v[176:179], v168 offset:51200
	ds_read_b128 v[180:183], v168 offset:52224
	ds_read_b128 v[184:187], v168 offset:53248
	ds_read_b128 v[188:191], v168 offset:54272
	ds_read_b128 v[194:197], v168 offset:55296
	ds_read_b128 v[198:201], v168 offset:56320
	global_load_lds_dwordx4 v[218:219], off
	s_mov_b32 m0, s55
	v_lshl_add_u64 v[218:219], v[224:225], 0, s[36:37]
	global_load_lds_dwordx4 v[218:219], off
	s_barrier
	s_waitcnt lgkmcnt(0)
	s_waitcnt lgkmcnt(0)
	v_mfma_f32_16x16x32_bf16 v[60:63], v[128:131], v[160:163], v[60:63]
	v_mfma_f32_16x16x32_bf16 v[56:59], v[136:139], v[160:163], v[56:59]
	v_mfma_f32_16x16x32_bf16 v[44:47], v[128:131], v[176:179], v[44:47]
	v_mfma_f32_16x16x32_bf16 v[40:43], v[136:139], v[176:179], v[40:43]
	v_mfma_f32_16x16x32_bf16 v[28:31], v[128:131], v[184:187], v[28:31]
	v_mfma_f32_16x16x32_bf16 v[24:27], v[136:139], v[184:187], v[24:27]
	v_mfma_f32_16x16x32_bf16 v[12:15], v[128:131], v[194:197], v[12:15]
	v_mfma_f32_16x16x32_bf16 v[8:11], v[136:139], v[194:197], v[8:11]
	v_mfma_f32_16x16x32_bf16 v[60:63], v[132:135], v[172:175], v[60:63]
	v_mfma_f32_16x16x32_bf16 v[56:59], v[156:159], v[172:175], v[56:59]
	v_mfma_f32_16x16x32_bf16 v[44:47], v[132:135], v[180:183], v[44:47]
	v_mfma_f32_16x16x32_bf16 v[40:43], v[156:159], v[180:183], v[40:43]
	v_mfma_f32_16x16x32_bf16 v[28:31], v[132:135], v[188:191], v[28:31]
	v_mfma_f32_16x16x32_bf16 v[24:27], v[156:159], v[188:191], v[24:27]
	v_mfma_f32_16x16x32_bf16 v[12:15], v[132:135], v[198:201], v[12:15]
	v_mfma_f32_16x16x32_bf16 v[8:11], v[156:159], v[198:201], v[8:11]
	s_barrier
	s_add_u32 s40, s42, 0x2c080
	s_addc_u32 s41, s43, 0
	s_add_i32 s28, s29, s46
	s_mov_b32 m0, s28
	v_lshl_add_u64 v[128:129], s[40:41], 0, v[142:143]
	global_load_lds_dwordx4 v[128:129], off
	s_add_i32 m0, s28, 0x2000
	v_lshl_add_u64 v[128:129], s[40:41], 0, v[146:147]
	global_load_lds_dwordx4 v[128:129], off
	s_waitcnt vmcnt(6)
	s_barrier
	v_mfma_f32_16x16x32_bf16 v[52:55], v[202:205], v[160:163], v[52:55]
	v_mfma_f32_16x16x32_bf16 v[48:51], v[210:213], v[160:163], v[48:51]
	v_mfma_f32_16x16x32_bf16 v[36:39], v[202:205], v[176:179], v[36:39]
	v_mfma_f32_16x16x32_bf16 v[32:35], v[210:213], v[176:179], v[32:35]
	v_mfma_f32_16x16x32_bf16 v[20:23], v[202:205], v[184:187], v[20:23]
	v_mfma_f32_16x16x32_bf16 v[16:19], v[210:213], v[184:187], v[16:19]
	v_mfma_f32_16x16x32_bf16 v[4:7], v[202:205], v[194:197], v[4:7]
	v_mfma_f32_16x16x32_bf16 v[0:3], v[210:213], v[194:197], v[0:3]
	v_mfma_f32_16x16x32_bf16 v[52:55], v[206:209], v[172:175], v[52:55]
	v_mfma_f32_16x16x32_bf16 v[48:51], v[214:217], v[172:175], v[48:51]
	v_mfma_f32_16x16x32_bf16 v[36:39], v[206:209], v[180:183], v[36:39]
	v_mfma_f32_16x16x32_bf16 v[32:35], v[214:217], v[180:183], v[32:35]
	v_mfma_f32_16x16x32_bf16 v[20:23], v[206:209], v[188:191], v[20:23]
	v_mfma_f32_16x16x32_bf16 v[16:19], v[214:217], v[188:191], v[16:19]
	v_mfma_f32_16x16x32_bf16 v[4:7], v[206:209], v[198:201], v[4:7]
	v_mfma_f32_16x16x32_bf16 v[0:3], v[214:217], v[198:201], v[0:3]
	s_add_i32 s65, s65, 2
	s_add_u32 s63, s63, 0x100
	s_addc_u32 s64, s64, 0
	s_cmp_gt_u32 s65, 41
	s_mov_b64 s[40:41], s[6:7]
	s_barrier
	s_cbranch_scc0 .LBB0_1169
	v_lshl_add_u32 v171, s62, 8, v164
	v_lshl_or_b32 v188, s10, 8, v166
	s_mov_b32 s63, 0xffff0000
	v_lshlrev_b32_e32 v128, 11, v171
	v_lshl_add_u32 v128, v188, 1, v128
	v_lshlrev_b32_e32 v129, 12, v171
	v_lshl_add_u32 v129, v188, 2, v129
	v_lshlrev_b32_e32 v132, 2, v188
	s_mov_b64 s[70:71], s[68:69]
	global_load_dwordx4 v[194:197], v128, s[70:71]
	global_load_dwordx4 v[198:201], v128, s[70:71] offset:64
	s_add_u32 s70, s70, 0x8000
	s_addc_u32 s71, s71, 0
	global_load_dwordx4 v[202:205], v128, s[70:71]
	global_load_dwordx4 v[206:209], v128, s[70:71] offset:64
	s_add_u32 s70, s70, 0x8000
	s_addc_u32 s71, s71, 0
	global_load_dwordx4 v[210:213], v128, s[70:71]
	global_load_dwordx4 v[214:217], v128, s[70:71] offset:64
	s_add_u32 s70, s70, 0x8000
	s_addc_u32 s71, s71, 0
	global_load_dwordx4 v[218:221], v128, s[70:71]
	global_load_dwordx4 v[222:225], v128, s[70:71] offset:64
	s_add_u32 s70, s70, 0x28000
	s_addc_u32 s71, s71, 0
	global_load_dwordx4 v[226:229], v128, s[70:71]
	global_load_dwordx4 v[230:233], v128, s[70:71] offset:64
	s_add_u32 s70, s70, 0x8000
	s_addc_u32 s71, s71, 0
	global_load_dwordx4 v[234:237], v128, s[70:71]
	global_load_dwordx4 v[238:241], v128, s[70:71] offset:64
	s_add_u32 s70, s70, 0x8000
	s_addc_u32 s71, s71, 0
	global_load_dwordx4 v[172:175], v128, s[70:71]
	global_load_dwordx4 v[176:179], v128, s[70:71] offset:64
	s_add_u32 s70, s70, 0x8000
	s_addc_u32 s71, s71, 0
	global_load_dwordx4 v[180:183], v128, s[70:71]
	global_load_dwordx4 v[184:187], v128, s[70:71] offset:64
	s_bfe_u32 s42, s17, 0x20006
	s_lshl_b32 s43, s10, 4
	s_lshl_b32 s42, s42, 2
	s_add_i32 s43, s43, s42
	v_lshl_add_u32 v130, v171, 6, s43
	v_and_b32_e32 v131, 48, v170
	v_lshl_add_u32 v131, v171, 6, v131
	v_xor_b32_e32 v134, 16, v170
	v_xor_b32_e32 v135, 32, v170
	v_lshlrev_b32_e32 v134, 2, v134
	v_lshlrev_b32_e32 v135, 2, v135
	v_cmp_gt_u32_e64 s[64:65], 16, v170
	s_add_u32 s74, s8, 0x2000
	s_addc_u32 s75, s9, 0
	s_lshl_b32 s42, s62, 7
	s_add_u32 s78, s26, 0x3c08000
	s_addc_u32 s79, s27, 0
	s_add_u32 s78, s78, s42
	s_addc_u32 s79, s79, 0
	s_waitcnt vmcnt(14)
	v_lshlrev_b32_e32 v136, 16, v194
	v_and_b32_e32 v137, s63, v194
	v_pk_add_f32 v[124:125], v[124:125], v[136:137]
	v_lshlrev_b32_e32 v138, 16, v195
	v_and_b32_e32 v139, s63, v195
	v_pk_add_f32 v[126:127], v[126:127], v[138:139]
	v_lshlrev_b32_e32 v190, 16, v196
	v_and_b32_e32 v191, s63, v196
	v_pk_add_f32 v[120:121], v[120:121], v[190:191]
	v_lshlrev_b32_e32 v136, 16, v197
	v_and_b32_e32 v137, s63, v197
	v_pk_add_f32 v[122:123], v[122:123], v[136:137]
	v_lshlrev_b32_e32 v138, 16, v198
	v_and_b32_e32 v139, s63, v198
	v_pk_add_f32 v[116:117], v[116:117], v[138:139]
	v_lshlrev_b32_e32 v190, 16, v199
	v_and_b32_e32 v191, s63, v199
	v_pk_add_f32 v[118:119], v[118:119], v[190:191]
	v_lshlrev_b32_e32 v136, 16, v200
	v_and_b32_e32 v137, s63, v200
	v_pk_add_f32 v[112:113], v[112:113], v[136:137]
	v_lshlrev_b32_e32 v138, 16, v201
	v_and_b32_e32 v139, s63, v201
	v_pk_add_f32 v[114:115], v[114:115], v[138:139]
	v_mul_f32_e32 v156, v120, v120
	v_mul_f32_e32 v189, v112, v112
	v_fmac_f32_e32 v156, v121, v121
	v_fmac_f32_e32 v189, v113, v113
	v_fmac_f32_e32 v156, v122, v122
	v_fmac_f32_e32 v189, v114, v114
	v_fmac_f32_e32 v156, v123, v123
	v_fmac_f32_e32 v189, v115, v115
	v_fmac_f32_e32 v156, v124, v124
	v_fmac_f32_e32 v189, v116, v116
	v_fmac_f32_e32 v156, v125, v125
	v_fmac_f32_e32 v189, v117, v117
	v_fmac_f32_e32 v156, v126, v126
	v_fmac_f32_e32 v189, v118, v118
	v_fmac_f32_e32 v156, v127, v127
	v_fmac_f32_e32 v189, v119, v119
	v_add_f32_e32 v156, v156, v189
	s_waitcnt vmcnt(12)
	v_lshlrev_b32_e32 v190, 16, v202
	v_and_b32_e32 v191, s63, v202
	v_pk_add_f32 v[108:109], v[108:109], v[190:191]
	v_lshlrev_b32_e32 v136, 16, v203
	v_and_b32_e32 v137, s63, v203
	v_pk_add_f32 v[110:111], v[110:111], v[136:137]
	v_lshlrev_b32_e32 v138, 16, v204
	v_and_b32_e32 v139, s63, v204
	v_pk_add_f32 v[104:105], v[104:105], v[138:139]
	v_lshlrev_b32_e32 v190, 16, v205
	v_and_b32_e32 v191, s63, v205
	v_pk_add_f32 v[106:107], v[106:107], v[190:191]
	v_lshlrev_b32_e32 v136, 16, v206
	v_and_b32_e32 v137, s63, v206
	v_pk_add_f32 v[100:101], v[100:101], v[136:137]
	v_lshlrev_b32_e32 v138, 16, v207
	v_and_b32_e32 v139, s63, v207
	v_pk_add_f32 v[102:103], v[102:103], v[138:139]
	v_lshlrev_b32_e32 v190, 16, v208
	v_and_b32_e32 v191, s63, v208
	v_pk_add_f32 v[96:97], v[96:97], v[190:191]
	v_lshlrev_b32_e32 v136, 16, v209
	v_and_b32_e32 v137, s63, v209
	v_pk_add_f32 v[98:99], v[98:99], v[136:137]
	v_mul_f32_e32 v157, v104, v104
	v_mul_f32_e32 v189, v96, v96
	v_fmac_f32_e32 v157, v105, v105
	v_fmac_f32_e32 v189, v97, v97
	v_fmac_f32_e32 v157, v106, v106
	v_fmac_f32_e32 v189, v98, v98
	v_fmac_f32_e32 v157, v107, v107
	v_fmac_f32_e32 v189, v99, v99
	v_fmac_f32_e32 v157, v108, v108
	v_fmac_f32_e32 v189, v100, v100
	v_fmac_f32_e32 v157, v109, v109
	v_fmac_f32_e32 v189, v101, v101
	v_fmac_f32_e32 v157, v110, v110
	v_fmac_f32_e32 v189, v102, v102
	v_fmac_f32_e32 v157, v111, v111
	v_fmac_f32_e32 v189, v103, v103
	v_add_f32_e32 v157, v157, v189
	s_waitcnt vmcnt(10)
	v_lshlrev_b32_e32 v138, 16, v210
	v_and_b32_e32 v139, s63, v210
	v_pk_add_f32 v[92:93], v[92:93], v[138:139]
	v_lshlrev_b32_e32 v190, 16, v211
	v_and_b32_e32 v191, s63, v211
	v_pk_add_f32 v[94:95], v[94:95], v[190:191]
	v_lshlrev_b32_e32 v136, 16, v212
	v_and_b32_e32 v137, s63, v212
	v_pk_add_f32 v[88:89], v[88:89], v[136:137]
	v_lshlrev_b32_e32 v138, 16, v213
	v_and_b32_e32 v139, s63, v213
	v_pk_add_f32 v[90:91], v[90:91], v[138:139]
	v_lshlrev_b32_e32 v190, 16, v214
	v_and_b32_e32 v191, s63, v214
	v_pk_add_f32 v[84:85], v[84:85], v[190:191]
	v_lshlrev_b32_e32 v136, 16, v215
	v_and_b32_e32 v137, s63, v215
	v_pk_add_f32 v[86:87], v[86:87], v[136:137]
	v_lshlrev_b32_e32 v138, 16, v216
	v_and_b32_e32 v139, s63, v216
	v_pk_add_f32 v[80:81], v[80:81], v[138:139]
	v_lshlrev_b32_e32 v190, 16, v217
	v_and_b32_e32 v191, s63, v217
	v_pk_add_f32 v[82:83], v[82:83], v[190:191]
	v_mul_f32_e32 v158, v88, v88
	v_mul_f32_e32 v189, v80, v80
	v_fmac_f32_e32 v158, v89, v89
	v_fmac_f32_e32 v189, v81, v81
	v_fmac_f32_e32 v158, v90, v90
	v_fmac_f32_e32 v189, v82, v82
	v_fmac_f32_e32 v158, v91, v91
	v_fmac_f32_e32 v189, v83, v83
	v_fmac_f32_e32 v158, v92, v92
	v_fmac_f32_e32 v189, v84, v84
	v_fmac_f32_e32 v158, v93, v93
	v_fmac_f32_e32 v189, v85, v85
	v_fmac_f32_e32 v158, v94, v94
	v_fmac_f32_e32 v189, v86, v86
	v_fmac_f32_e32 v158, v95, v95
	v_fmac_f32_e32 v189, v87, v87
	v_add_f32_e32 v158, v158, v189
	s_waitcnt vmcnt(8)
	v_lshlrev_b32_e32 v136, 16, v218
	v_and_b32_e32 v137, s63, v218
	v_pk_add_f32 v[76:77], v[76:77], v[136:137]
	v_lshlrev_b32_e32 v138, 16, v219
	v_and_b32_e32 v139, s63, v219
	v_pk_add_f32 v[78:79], v[78:79], v[138:139]
	v_lshlrev_b32_e32 v190, 16, v220
	v_and_b32_e32 v191, s63, v220
	v_pk_add_f32 v[72:73], v[72:73], v[190:191]
	v_lshlrev_b32_e32 v136, 16, v221
	v_and_b32_e32 v137, s63, v221
	v_pk_add_f32 v[74:75], v[74:75], v[136:137]
	v_lshlrev_b32_e32 v138, 16, v222
	v_and_b32_e32 v139, s63, v222
	v_pk_add_f32 v[68:69], v[68:69], v[138:139]
	v_lshlrev_b32_e32 v190, 16, v223
	v_and_b32_e32 v191, s63, v223
	v_pk_add_f32 v[70:71], v[70:71], v[190:191]
	v_lshlrev_b32_e32 v136, 16, v224
	v_and_b32_e32 v137, s63, v224
	v_pk_add_f32 v[64:65], v[64:65], v[136:137]
	v_lshlrev_b32_e32 v138, 16, v225
	v_and_b32_e32 v139, s63, v225
	v_pk_add_f32 v[66:67], v[66:67], v[138:139]
	v_mul_f32_e32 v159, v72, v72
	v_mul_f32_e32 v189, v64, v64
	v_fmac_f32_e32 v159, v73, v73
	v_fmac_f32_e32 v189, v65, v65
	v_fmac_f32_e32 v159, v74, v74
	v_fmac_f32_e32 v189, v66, v66
	v_fmac_f32_e32 v159, v75, v75
	v_fmac_f32_e32 v189, v67, v67
	v_fmac_f32_e32 v159, v76, v76
	v_fmac_f32_e32 v189, v68, v68
	v_fmac_f32_e32 v159, v77, v77
	v_fmac_f32_e32 v189, v69, v69
	v_fmac_f32_e32 v159, v78, v78
	v_fmac_f32_e32 v189, v70, v70
	v_fmac_f32_e32 v159, v79, v79
	v_fmac_f32_e32 v189, v71, v71
	v_add_f32_e32 v159, v159, v189
	s_waitcnt vmcnt(6)
	v_lshlrev_b32_e32 v190, 16, v226
	v_and_b32_e32 v191, s63, v226
	v_pk_add_f32 v[60:61], v[60:61], v[190:191]
	v_lshlrev_b32_e32 v136, 16, v227
	v_and_b32_e32 v137, s63, v227
	v_pk_add_f32 v[62:63], v[62:63], v[136:137]
	v_lshlrev_b32_e32 v138, 16, v228
	v_and_b32_e32 v139, s63, v228
	v_pk_add_f32 v[56:57], v[56:57], v[138:139]
	v_lshlrev_b32_e32 v190, 16, v229
	v_and_b32_e32 v191, s63, v229
	v_pk_add_f32 v[58:59], v[58:59], v[190:191]
	v_lshlrev_b32_e32 v136, 16, v230
	v_and_b32_e32 v137, s63, v230
	v_pk_add_f32 v[52:53], v[52:53], v[136:137]
	v_lshlrev_b32_e32 v138, 16, v231
	v_and_b32_e32 v139, s63, v231
	v_pk_add_f32 v[54:55], v[54:55], v[138:139]
	v_lshlrev_b32_e32 v190, 16, v232
	v_and_b32_e32 v191, s63, v232
	v_pk_add_f32 v[48:49], v[48:49], v[190:191]
	v_lshlrev_b32_e32 v136, 16, v233
	v_and_b32_e32 v137, s63, v233
	v_pk_add_f32 v[50:51], v[50:51], v[136:137]
	v_mul_f32_e32 v160, v56, v56
	v_mul_f32_e32 v189, v48, v48
	v_fmac_f32_e32 v160, v57, v57
	v_fmac_f32_e32 v189, v49, v49
	v_fmac_f32_e32 v160, v58, v58
	v_fmac_f32_e32 v189, v50, v50
	v_fmac_f32_e32 v160, v59, v59
	v_fmac_f32_e32 v189, v51, v51
	v_fmac_f32_e32 v160, v60, v60
	v_fmac_f32_e32 v189, v52, v52
	v_fmac_f32_e32 v160, v61, v61
	v_fmac_f32_e32 v189, v53, v53
	v_fmac_f32_e32 v160, v62, v62
	v_fmac_f32_e32 v189, v54, v54
	v_fmac_f32_e32 v160, v63, v63
	v_fmac_f32_e32 v189, v55, v55
	v_add_f32_e32 v160, v160, v189
	s_waitcnt vmcnt(4)
	v_lshlrev_b32_e32 v138, 16, v234
	v_and_b32_e32 v139, s63, v234
	v_pk_add_f32 v[44:45], v[44:45], v[138:139]
	v_lshlrev_b32_e32 v190, 16, v235
	v_and_b32_e32 v191, s63, v235
	v_pk_add_f32 v[46:47], v[46:47], v[190:191]
	v_lshlrev_b32_e32 v136, 16, v236
	v_and_b32_e32 v137, s63, v236
	v_pk_add_f32 v[40:41], v[40:41], v[136:137]
	v_lshlrev_b32_e32 v138, 16, v237
	v_and_b32_e32 v139, s63, v237
	v_pk_add_f32 v[42:43], v[42:43], v[138:139]
	v_lshlrev_b32_e32 v190, 16, v238
	v_and_b32_e32 v191, s63, v238
	v_pk_add_f32 v[36:37], v[36:37], v[190:191]
	v_lshlrev_b32_e32 v136, 16, v239
	v_and_b32_e32 v137, s63, v239
	v_pk_add_f32 v[38:39], v[38:39], v[136:137]
	v_lshlrev_b32_e32 v138, 16, v240
	v_and_b32_e32 v139, s63, v240
	v_pk_add_f32 v[32:33], v[32:33], v[138:139]
	v_lshlrev_b32_e32 v190, 16, v241
	v_and_b32_e32 v191, s63, v241
	v_pk_add_f32 v[34:35], v[34:35], v[190:191]
	v_mul_f32_e32 v161, v40, v40
	v_mul_f32_e32 v189, v32, v32
	v_fmac_f32_e32 v161, v41, v41
	v_fmac_f32_e32 v189, v33, v33
	v_fmac_f32_e32 v161, v42, v42
	v_fmac_f32_e32 v189, v34, v34
	v_fmac_f32_e32 v161, v43, v43
	v_fmac_f32_e32 v189, v35, v35
	v_fmac_f32_e32 v161, v44, v44
	v_fmac_f32_e32 v189, v36, v36
	v_fmac_f32_e32 v161, v45, v45
	v_fmac_f32_e32 v189, v37, v37
	v_fmac_f32_e32 v161, v46, v46
	v_fmac_f32_e32 v189, v38, v38
	v_fmac_f32_e32 v161, v47, v47
	v_fmac_f32_e32 v189, v39, v39
	v_add_f32_e32 v161, v161, v189
	s_waitcnt vmcnt(2)
	v_lshlrev_b32_e32 v136, 16, v172
	v_and_b32_e32 v137, s63, v172
	v_pk_add_f32 v[28:29], v[28:29], v[136:137]
	v_lshlrev_b32_e32 v138, 16, v173
	v_and_b32_e32 v139, s63, v173
	v_pk_add_f32 v[30:31], v[30:31], v[138:139]
	v_lshlrev_b32_e32 v190, 16, v174
	v_and_b32_e32 v191, s63, v174
	v_pk_add_f32 v[24:25], v[24:25], v[190:191]
	v_lshlrev_b32_e32 v136, 16, v175
	v_and_b32_e32 v137, s63, v175
	v_pk_add_f32 v[26:27], v[26:27], v[136:137]
	v_lshlrev_b32_e32 v138, 16, v176
	v_and_b32_e32 v139, s63, v176
	v_pk_add_f32 v[20:21], v[20:21], v[138:139]
	v_lshlrev_b32_e32 v190, 16, v177
	v_and_b32_e32 v191, s63, v177
	v_pk_add_f32 v[22:23], v[22:23], v[190:191]
	v_lshlrev_b32_e32 v136, 16, v178
	v_and_b32_e32 v137, s63, v178
	v_pk_add_f32 v[16:17], v[16:17], v[136:137]
	v_lshlrev_b32_e32 v138, 16, v179
	v_and_b32_e32 v139, s63, v179
	v_pk_add_f32 v[18:19], v[18:19], v[138:139]
	v_mul_f32_e32 v162, v24, v24
	v_mul_f32_e32 v189, v16, v16
	v_fmac_f32_e32 v162, v25, v25
	v_fmac_f32_e32 v189, v17, v17
	v_fmac_f32_e32 v162, v26, v26
	v_fmac_f32_e32 v189, v18, v18
	v_fmac_f32_e32 v162, v27, v27
	v_fmac_f32_e32 v189, v19, v19
	v_fmac_f32_e32 v162, v28, v28
	v_fmac_f32_e32 v189, v20, v20
	v_fmac_f32_e32 v162, v29, v29
	v_fmac_f32_e32 v189, v21, v21
	v_fmac_f32_e32 v162, v30, v30
	v_fmac_f32_e32 v189, v22, v22
	v_fmac_f32_e32 v162, v31, v31
	v_fmac_f32_e32 v189, v23, v23
	v_add_f32_e32 v162, v162, v189
	s_waitcnt vmcnt(0)
	v_lshlrev_b32_e32 v190, 16, v180
	v_and_b32_e32 v191, s63, v180
	v_pk_add_f32 v[12:13], v[12:13], v[190:191]
	v_lshlrev_b32_e32 v136, 16, v181
	v_and_b32_e32 v137, s63, v181
	v_pk_add_f32 v[14:15], v[14:15], v[136:137]
	v_lshlrev_b32_e32 v138, 16, v182
	v_and_b32_e32 v139, s63, v182
	v_pk_add_f32 v[8:9], v[8:9], v[138:139]
	v_lshlrev_b32_e32 v190, 16, v183
	v_and_b32_e32 v191, s63, v183
	v_pk_add_f32 v[10:11], v[10:11], v[190:191]
	v_lshlrev_b32_e32 v136, 16, v184
	v_and_b32_e32 v137, s63, v184
	v_pk_add_f32 v[4:5], v[4:5], v[136:137]
	v_lshlrev_b32_e32 v138, 16, v185
	v_and_b32_e32 v139, s63, v185
	v_pk_add_f32 v[6:7], v[6:7], v[138:139]
	v_lshlrev_b32_e32 v190, 16, v186
	v_and_b32_e32 v191, s63, v186
	v_pk_add_f32 v[0:1], v[0:1], v[190:191]
	v_lshlrev_b32_e32 v136, 16, v187
	v_and_b32_e32 v137, s63, v187
	v_pk_add_f32 v[2:3], v[2:3], v[136:137]
	v_mul_f32_e32 v163, v8, v8
	v_mul_f32_e32 v189, v0, v0
	v_fmac_f32_e32 v163, v9, v9
	v_fmac_f32_e32 v189, v1, v1
	v_fmac_f32_e32 v163, v10, v10
	v_fmac_f32_e32 v189, v2, v2
	v_fmac_f32_e32 v163, v11, v11
	v_fmac_f32_e32 v189, v3, v3
	v_fmac_f32_e32 v163, v12, v12
	v_fmac_f32_e32 v189, v4, v4
	v_fmac_f32_e32 v163, v13, v13
	v_fmac_f32_e32 v189, v5, v5
	v_fmac_f32_e32 v163, v14, v14
	v_fmac_f32_e32 v189, v6, v6
	v_fmac_f32_e32 v163, v15, v15
	v_fmac_f32_e32 v189, v7, v7
	v_add_f32_e32 v163, v163, v189
	ds_bpermute_b32 v136, v134, v156
	ds_bpermute_b32 v137, v134, v157
	ds_bpermute_b32 v138, v134, v158
	ds_bpermute_b32 v139, v134, v159
	ds_bpermute_b32 v188, v134, v160
	ds_bpermute_b32 v189, v134, v161
	ds_bpermute_b32 v190, v134, v162
	ds_bpermute_b32 v191, v134, v163
	s_waitcnt lgkmcnt(0)
	v_add_f32_e32 v156, v156, v136
	v_add_f32_e32 v157, v157, v137
	v_add_f32_e32 v158, v158, v138
	v_add_f32_e32 v159, v159, v139
	v_add_f32_e32 v160, v160, v188
	v_add_f32_e32 v161, v161, v189
	v_add_f32_e32 v162, v162, v190
	v_add_f32_e32 v163, v163, v191
	ds_bpermute_b32 v136, v135, v156
	ds_bpermute_b32 v137, v135, v157
	ds_bpermute_b32 v138, v135, v158
	ds_bpermute_b32 v139, v135, v159
	ds_bpermute_b32 v188, v135, v160
	ds_bpermute_b32 v189, v135, v161
	ds_bpermute_b32 v190, v135, v162
	ds_bpermute_b32 v191, v135, v163
	s_waitcnt lgkmcnt(0)
	v_add_f32_e32 v156, v156, v136
	v_add_f32_e32 v157, v157, v137
	v_add_f32_e32 v158, v158, v138
	v_add_f32_e32 v159, v159, v139
	v_add_f32_e32 v160, v160, v188
	v_add_f32_e32 v161, v161, v189
	v_add_f32_e32 v162, v162, v190
	v_add_f32_e32 v163, v163, v191
	s_and_saveexec_b64 s[66:67], s[64:65]
	global_store_dword v130, v156, s[8:9] sc1
	global_store_dword v130, v157, s[8:9] offset:1024 sc1
	global_store_dword v130, v158, s[8:9] offset:2048 sc1
	global_store_dword v130, v159, s[8:9] offset:3072 sc1
	global_store_dword v130, v160, s[74:75] sc1
	global_store_dword v130, v161, s[74:75] offset:1024 sc1
	global_store_dword v130, v162, s[74:75] offset:2048 sc1
	global_store_dword v130, v163, s[74:75] offset:3072 sc1
	s_or_b64 exec, exec, s[66:67]
	global_load_dwordx4 v[210:213], v132, s[22:23]
	global_load_dwordx4 v[214:217], v132, s[22:23] offset:16
	global_load_dwordx4 v[218:221], v132, s[22:23] offset:128
	global_load_dwordx4 v[222:225], v132, s[22:23] offset:144
	s_waitcnt vmcnt(0)
	s_barrier
	s_barrier
	s_cmpk_gt_u32 s17, 0xff
	s_cbranch_scc1 .Lf11_w1_a
	s_and_saveexec_b64 s[40:41], s[14:15]
	s_cbranch_execz .Lf11_t0_done
	v_mov_b32_e32 v133, 0
	v_mov_b32_e32 v189, 1
	global_atomic_add v133, v189, s[78:79]
	s_mov_b32 s80, 0
